# gMLP item LayerNorm staging: gamma/beta rows of chunks 1..3 of each commit loaded together with chunk 0's (were 4 serial load-wait-use groups per commit)
# speedup vs baseline: 1.0093x; 1.0009x over previous
.LBB0_897:
	s_or_b64 exec, exec, s[12:13]
	v_bfe_u32 v32, v4, 2, 7
	v_lshl_add_u64 v[0:1], s[4:5], 0, v[32:33]
	v_mad_u64_u32 v[2:3], s[12:13], v0, s9, v[34:35]
	v_mov_b32_e32 v0, v3
	v_mad_u64_u32 v[0:1], s[12:13], v1, s9, v[0:1]
	v_mov_b32_e32 v3, v0
	v_lshlrev_b32_e32 v0, 3, v4
	v_and_b32_e32 v5, 24, v0
	v_lshlrev_b32_e32 v0, 1, v5
	v_mov_b32_e32 v1, v33
	v_lshl_add_u64 v[46:47], v[2:3], 0, v[0:1]
	global_load_dwordx4 v[8:11], v[46:47], off offset:2048
	v_lshlrev_b32_e32 v157, 2, v5
	global_load_dwordx4 v[12:15], v[46:47], off offset:2112
	global_load_dwordx4 v[16:19], v[46:47], off offset:2176
	global_load_dwordx4 v[0:3], v[46:47], off offset:2240
	s_waitcnt lgkmcnt(0)
	s_barrier
	global_load_dwordx4 v[20:23], v157, s[48:49]
	global_load_dwordx4 v[24:27], v157, s[50:51]
	global_load_dwordx4 v[28:31], v157, s[48:49] offset:16
	global_load_dwordx4 v[36:39], v157, s[50:51] offset:16
	global_load_dwordx4 v[178:181], v157, s[48:49] offset:128
	global_load_dwordx4 v[182:185], v157, s[50:51] offset:128
	global_load_dwordx4 v[186:189], v157, s[48:49] offset:144
	global_load_dwordx4 v[190:193], v157, s[50:51] offset:144
	global_load_dwordx4 v[194:197], v157, s[48:49] offset:256
	global_load_dwordx4 v[198:201], v157, s[50:51] offset:256
	global_load_dwordx4 v[202:205], v157, s[48:49] offset:272
	global_load_dwordx4 v[206:209], v157, s[50:51] offset:272
	global_load_dwordx4 v[210:213], v157, s[48:49] offset:384
	global_load_dwordx4 v[214:217], v157, s[50:51] offset:384
	global_load_dwordx4 v[218:221], v157, s[48:49] offset:400
	global_load_dwordx4 v[238:241], v157, s[50:51] offset:400
	v_lshl_add_u32 v6, v32, 3, 0
	v_lshlrev_b32_e32 v7, 1, v32
	v_add_u32_e32 v160, 0x11000, v6
	v_mul_u32_u24_e32 v5, 0x110, v5
	v_add3_u32 v155, 0, v7, v5
	ds_read_b64 v[6:7], v160
	v_ashrrev_i32_e32 v44, 2, v4
	v_and_b32_e32 v50, 15, v4
	v_mov_b32_e32 v49, v33
	v_readlane_b32 s56, v254, 12
	v_readlane_b32 s58, v254, 14
	v_readlane_b32 s59, v254, 15
	v_readlane_b32 s57, v254, 13
	v_readlane_b32 s60, v254, 16
	v_readlane_b32 s61, v254, 17
	v_readlane_b32 s62, v254, 18
	v_readlane_b32 s63, v254, 19
	v_readlane_b32 s64, v254, 20
	v_readlane_b32 s65, v254, 21
	v_readlane_b32 s66, v254, 22
	v_readlane_b32 s67, v254, 23
	v_readlane_b32 s68, v254, 24
	v_readlane_b32 s69, v254, 25
	v_readlane_b32 s70, v254, 26
	v_readlane_b32 s71, v254, 27
	s_waitcnt vmcnt(7)
	v_lshlrev_b32_e32 v5, 16, v8
	s_waitcnt lgkmcnt(0)
	v_sub_f32_e32 v5, v5, v6
	v_and_b32_e32 v8, 0xffff0000, v8
	v_mul_f32_e32 v5, v7, v5
	v_lshlrev_b32_e32 v32, 16, v9
	v_sub_f32_e32 v8, v8, v6
	s_waitcnt vmcnt(2)
	v_fma_f32 v5, v20, v5, v24
	v_and_b32_e32 v9, 0xffff0000, v9
	v_sub_f32_e32 v32, v32, v6
	v_mul_f32_e32 v8, v7, v8
	v_cvt_pk_bf16_f32 v5, v5, v33
	v_lshlrev_b32_e32 v40, 16, v10
	v_sub_f32_e32 v9, v9, v6
	v_mul_f32_e32 v32, v7, v32
	v_fma_f32 v8, v21, v8, v25
	ds_write_b16 v155, v5
	v_cvt_pk_bf16_f32 v5, v8, v33
	v_and_b32_e32 v10, 0xffff0000, v10
	v_sub_f32_e32 v40, v40, v6
	v_mul_f32_e32 v9, v7, v9
	v_fma_f32 v20, v22, v32, v26
	ds_write_b16 v155, v5 offset:272
	v_cvt_pk_bf16_f32 v5, v20, v33
	v_lshlrev_b32_e32 v41, 16, v11
	v_sub_f32_e32 v10, v10, v6
	v_mul_f32_e32 v40, v7, v40
	v_fmac_f32_e32 v27, v23, v9
	ds_write_b16 v155, v5 offset:544
	v_cvt_pk_bf16_f32 v5, v27, v33
	v_and_b32_e32 v11, 0xffff0000, v11
	v_sub_f32_e32 v41, v41, v6
	v_mul_f32_e32 v10, v7, v10
	s_waitcnt vmcnt(0)
	v_fma_f32 v9, v40, v28, v36
	ds_write_b16 v155, v5 offset:816
	v_cvt_pk_bf16_f32 v5, v9, v33
	v_sub_f32_e32 v11, v11, v6
	v_mul_f32_e32 v41, v7, v41
	v_fma_f32 v10, v10, v29, v37
	ds_write_b16 v155, v5 offset:1088
	v_cvt_pk_bf16_f32 v5, v10, v33
	v_mul_f32_e32 v11, v7, v11
	v_fma_f32 v21, v41, v30, v38
	ds_write_b16 v155, v5 offset:1360
	v_cvt_pk_bf16_f32 v5, v21, v33
	v_fmac_f32_e32 v39, v11, v31
	ds_write_b16 v155, v5 offset:1632
	v_cvt_pk_bf16_f32 v5, v39, v33
	v_mov_b64_e32 v[8:9], v[178:179]
	v_mov_b64_e32 v[10:11], v[180:181]
	v_mov_b64_e32 v[20:21], v[182:183]
	v_mov_b64_e32 v[22:23], v[184:185]
	v_mov_b64_e32 v[24:25], v[186:187]
	v_mov_b64_e32 v[26:27], v[188:189]
	v_mov_b64_e32 v[28:29], v[190:191]
	v_mov_b64_e32 v[30:31], v[192:193]
	v_lshlrev_b32_e32 v32, 16, v12
	v_sub_f32_e32 v32, v32, v6
	v_and_b32_e32 v12, 0xffff0000, v12
	v_mul_f32_e32 v32, v7, v32
	v_lshlrev_b32_e32 v36, 16, v13
	v_sub_f32_e32 v12, v12, v6
	ds_write_b16 v155, v5 offset:1904
	v_and_b32_e32 v13, 0xffff0000, v13
	v_sub_f32_e32 v36, v36, v6
	v_mul_f32_e32 v12, v7, v12
	v_lshlrev_b32_e32 v37, 16, v14
	v_sub_f32_e32 v13, v13, v6
	v_mul_f32_e32 v36, v7, v36
	v_and_b32_e32 v14, 0xffff0000, v14
	v_sub_f32_e32 v37, v37, v6
	v_mul_f32_e32 v13, v7, v13
	v_lshlrev_b32_e32 v38, 16, v15
	v_sub_f32_e32 v14, v14, v6
	v_mul_f32_e32 v37, v7, v37
	v_and_b32_e32 v15, 0xffff0000, v15
	v_sub_f32_e32 v38, v38, v6
	v_mul_f32_e32 v14, v7, v14
	v_sub_f32_e32 v15, v15, v6
	v_mul_f32_e32 v38, v7, v38
	v_mul_f32_e32 v15, v7, v15
	s_waitcnt vmcnt(2)
	v_fma_f32 v5, v32, v8, v20
	v_cvt_pk_bf16_f32 v5, v5, v33
	v_fma_f32 v8, v12, v9, v21
	ds_write_b16 v155, v5 offset:8704
	v_cvt_pk_bf16_f32 v5, v8, v33
	v_fma_f32 v9, v36, v10, v22
	ds_write_b16 v155, v5 offset:8976
	v_cvt_pk_bf16_f32 v5, v9, v33
	v_fmac_f32_e32 v23, v13, v11
	ds_write_b16 v155, v5 offset:9248
	v_cvt_pk_bf16_f32 v5, v23, v33
	s_waitcnt vmcnt(0)
	v_fma_f32 v10, v37, v24, v28
	ds_write_b16 v155, v5 offset:9520
	v_cvt_pk_bf16_f32 v5, v10, v33
	v_fma_f32 v11, v14, v25, v29
	ds_write_b16 v155, v5 offset:9792
	v_cvt_pk_bf16_f32 v5, v11, v33
	v_fma_f32 v12, v38, v26, v30
	ds_write_b16 v155, v5 offset:10064
	v_cvt_pk_bf16_f32 v5, v12, v33
	v_fmac_f32_e32 v31, v15, v27
	ds_write_b16 v155, v5 offset:10336
	v_cvt_pk_bf16_f32 v5, v31, v33
	v_mov_b64_e32 v[8:9], v[194:195]
	v_mov_b64_e32 v[10:11], v[196:197]
	v_mov_b64_e32 v[12:13], v[198:199]
	v_mov_b64_e32 v[14:15], v[200:201]
	v_mov_b64_e32 v[20:21], v[202:203]
	v_mov_b64_e32 v[22:23], v[204:205]
	v_mov_b64_e32 v[24:25], v[206:207]
	v_mov_b64_e32 v[26:27], v[208:209]
	v_lshlrev_b32_e32 v28, 16, v16
	v_sub_f32_e32 v28, v28, v6
	v_and_b32_e32 v16, 0xffff0000, v16
	v_mul_f32_e32 v28, v7, v28
	v_lshlrev_b32_e32 v29, 16, v17
	v_sub_f32_e32 v16, v16, v6
	ds_write_b16 v155, v5 offset:10608
	v_and_b32_e32 v17, 0xffff0000, v17
	v_sub_f32_e32 v29, v29, v6
	v_mul_f32_e32 v16, v7, v16
	v_lshlrev_b32_e32 v30, 16, v18
	v_sub_f32_e32 v17, v17, v6
	v_mul_f32_e32 v29, v7, v29
	v_and_b32_e32 v18, 0xffff0000, v18
	v_sub_f32_e32 v30, v30, v6
	v_mul_f32_e32 v17, v7, v17
	v_lshlrev_b32_e32 v31, 16, v19
	v_sub_f32_e32 v18, v18, v6
	v_mul_f32_e32 v30, v7, v30
	v_and_b32_e32 v19, 0xffff0000, v19
	v_sub_f32_e32 v31, v31, v6
	v_mul_f32_e32 v18, v7, v18
	v_sub_f32_e32 v19, v19, v6
	v_mul_f32_e32 v31, v7, v31
	v_mul_f32_e32 v19, v7, v19
	s_waitcnt vmcnt(2)
	v_fma_f32 v5, v28, v8, v12
	v_cvt_pk_bf16_f32 v5, v5, v33
	v_fma_f32 v8, v16, v9, v13
	ds_write_b16 v155, v5 offset:17408
	v_cvt_pk_bf16_f32 v5, v8, v33
	v_fma_f32 v9, v29, v10, v14
	ds_write_b16 v155, v5 offset:17680
	v_cvt_pk_bf16_f32 v5, v9, v33
	v_fmac_f32_e32 v15, v17, v11
	ds_write_b16 v155, v5 offset:17952
	v_cvt_pk_bf16_f32 v5, v15, v33
	s_waitcnt vmcnt(0)
	v_fma_f32 v10, v30, v20, v24
	ds_write_b16 v155, v5 offset:18224
	v_cvt_pk_bf16_f32 v5, v10, v33
	v_fma_f32 v11, v18, v21, v25
	ds_write_b16 v155, v5 offset:18496
	v_cvt_pk_bf16_f32 v5, v11, v33
	v_fma_f32 v12, v31, v22, v26
	ds_write_b16 v155, v5 offset:18768
	v_cvt_pk_bf16_f32 v5, v12, v33
	v_fmac_f32_e32 v27, v19, v23
	ds_write_b16 v155, v5 offset:19040
	v_cvt_pk_bf16_f32 v5, v27, v33
	v_mov_b64_e32 v[8:9], v[210:211]
	v_mov_b64_e32 v[10:11], v[212:213]
	v_mov_b64_e32 v[12:13], v[214:215]
	v_mov_b64_e32 v[14:15], v[216:217]
	v_mov_b64_e32 v[16:17], v[218:219]
	v_mov_b64_e32 v[18:19], v[220:221]
	v_mov_b64_e32 v[20:21], v[238:239]
	v_mov_b64_e32 v[22:23], v[240:241]
	v_bfe_u32 v24, v4, 4, 2
	v_and_b32_e32 v26, -16, v44
	v_lshlrev_b32_e32 v32, 3, v24
	v_lshlrev_b32_e32 v48, 4, v24
	v_ashrrev_i32_e32 v25, 31, v26
	v_or_b32_e32 v24, v26, v50
	v_lshl_add_u64 v[26:27], s[0:1], 0, v[48:49]
	v_lshl_add_u64 v[36:37], s[4:5], 0, v[24:25]
	v_lshlrev_b64 v[24:25], 8, v[24:25]
	v_lshl_add_u64 v[42:43], v[26:27], 0, v[24:25]
	v_lshlrev_b32_e32 v24, 16, v0
	v_and_b32_e32 v0, 0xffff0000, v0
	v_lshlrev_b32_e32 v27, 16, v3
	v_and_b32_e32 v3, 0xffff0000, v3
	v_sub_f32_e32 v0, v0, v6
	v_lshlrev_b32_e32 v25, 16, v1
	v_and_b32_e32 v1, 0xffff0000, v1
	v_lshlrev_b32_e32 v26, 16, v2
	v_and_b32_e32 v2, 0xffff0000, v2
	v_sub_f32_e32 v24, v24, v6
	v_sub_f32_e32 v3, v3, v6
	v_mul_f32_e32 v0, v7, v0
	v_sub_f32_e32 v25, v25, v6
	v_sub_f32_e32 v1, v1, v6
	v_sub_f32_e32 v26, v26, v6
	v_sub_f32_e32 v2, v2, v6
	v_sub_f32_e32 v27, v27, v6
	v_mul_f32_e32 v6, v7, v24
	v_mul_f32_e32 v3, v7, v3
	v_mul_f32_e32 v24, v7, v25
	ds_write_b16 v155, v5 offset:19312
	v_mul_f32_e32 v1, v7, v1
	v_mul_f32_e32 v25, v7, v26
	v_mul_f32_e32 v2, v7, v2
	v_mul_f32_e32 v26, v7, v27
	v_mad_u64_u32 v[38:39], s[12:13], v36, s9, v[34:35]
	s_waitcnt vmcnt(2)
	v_fma_f32 v0, v0, v9, v13
	v_fma_f32 v5, v6, v8, v12
	s_waitcnt vmcnt(0)
	v_fmac_f32_e32 v23, v3, v19
	v_cvt_pk_bf16_f32 v3, v5, v33
	ds_write_b16 v155, v3 offset:26112
	v_cvt_pk_bf16_f32 v0, v0, v33
	v_fma_f32 v6, v24, v10, v14
	ds_write_b16 v155, v0 offset:26384
	v_cvt_pk_bf16_f32 v0, v6, v33
	v_fmac_f32_e32 v15, v1, v11
	ds_write_b16 v155, v0 offset:26656
	v_cvt_pk_bf16_f32 v0, v15, v33
	v_fma_f32 v1, v25, v16, v20
	ds_write_b16 v155, v0 offset:26928
	v_cvt_pk_bf16_f32 v0, v1, v33
	v_fma_f32 v2, v2, v17, v21
	ds_write_b16 v155, v0 offset:27200
	v_cvt_pk_bf16_f32 v0, v2, v33
	v_fma_f32 v7, v26, v18, v22
	ds_write_b16 v155, v0 offset:27472
	v_cvt_pk_bf16_f32 v0, v7, v33
	ds_write_b16 v155, v0 offset:27744
	v_cvt_pk_bf16_f32 v0, v23, v33
	ds_write_b16 v155, v0 offset:28016
	s_waitcnt lgkmcnt(0)
	s_barrier
	global_load_dwordx4 v[20:23], v[42:43], off
	global_load_dwordx4 v[24:27], v[42:43], off offset:64
	v_mov_b32_e32 v0, v39
	v_mad_u64_u32 v[0:1], s[12:13], v37, s9, v[0:1]
	v_mov_b32_e32 v39, v0
	v_lshl_add_u64 v[40:41], v[38:39], 0, v[32:33]
	global_load_dwordx2 v[224:225], v[40:41], off offset:1056
	global_load_dwordx2 v[226:227], v[40:41], off offset:1088
	global_load_dwordx2 v[228:229], v[40:41], off offset:1120
	global_load_dwordx2 v[230:231], v[40:41], off offset:1152
	global_load_dwordx2 v[232:233], v[40:41], off offset:1184
	global_load_dwordx2 v[234:235], v[40:41], off offset:1216
	global_load_dwordx2 v[236:237], v[40:41], off offset:1248
	global_load_dwordx2 v[52:53], v[40:41], off offset:1024
	global_load_dwordx4 v[28:31], v[42:43], off offset:128
	global_load_dwordx4 v[16:19], v[42:43], off offset:192
	v_bfi_b32 v0, -16, v44, v4
	v_ashrrev_i32_e32 v1, 31, v0
	v_lshl_add_u64 v[44:45], v[0:1], 2, s[58:59]
	global_load_dword v54, v[44:45], off
	v_mul_u32_u24_e32 v0, 0x110, v50
	v_add3_u32 v152, 0, v48, v0
	ds_read_b128 v[0:3], v152
	ds_read_b128 v[4:7], v152 offset:64
	ds_read_b128 v[48:51], v152 offset:128
	s_waitcnt vmcnt(5) lgkmcnt(2)
	v_mfma_f32_16x16x32_bf16 v[0:3], v[0:3], v[20:23], 0
	global_load_dwordx4 v[12:15], v[46:47], off offset:2304
	global_load_dwordx4 v[8:11], v[46:47], off offset:2368
	ds_read_b128 v[56:59], v152 offset:192
	s_waitcnt vmcnt(5)
	v_lshlrev_b32_e32 v64, 16, v52
	s_waitcnt lgkmcnt(2)
	v_mfma_f32_16x16x32_bf16 v[60:63], v[4:7], v[24:27], v[0:3]
	v_and_b32_e32 v65, 0xffff0000, v52
	v_lshlrev_b32_e32 v52, 16, v53
	v_and_b32_e32 v53, 0xffff0000, v53
	s_waitcnt vmcnt(4) lgkmcnt(1)
	v_mfma_f32_16x16x32_bf16 v[48:51], v[48:51], v[28:31], v[60:63]
	global_load_dwordx4 v[4:7], v[46:47], off offset:2432
	global_load_dwordx4 v[0:3], v[46:47], off offset:2496
	s_waitcnt vmcnt(0)
	v_lshlrev_b32_e32 v101, 16, v2
	s_waitcnt lgkmcnt(0)
	v_mfma_f32_16x16x32_bf16 v[48:51], v[56:59], v[16:19], v[48:51]
	v_and_b32_e32 v102, 0xffff0000, v2
	v_and_b32_e32 v100, 0xffff0000, v1
	v_lshlrev_b32_e32 v103, 16, v3
	v_and_b32_e32 v104, 0xffff0000, v3
	s_nop 3
	v_pk_add_f32 v[48:49], v[54:55], v[48:49] op_sel_hi:[0,1]
	v_pk_add_f32 v[50:51], v[54:55], v[50:51] op_sel_hi:[0,1]
	v_pk_mul_f32 v[48:49], v[48:49], v[64:65]
	v_pk_mul_f32 v[50:51], v[50:51], v[52:53]
	v_cvt_pk_bf16_f32 v150, v48, v49
	v_mul_f32_e32 v2, v49, v49
	v_cvt_pk_bf16_f32 v148, v50, v51
	ds_read_b128 v[56:59], v152 offset:4352
	ds_read_b128 v[60:63], v152 offset:4416
	s_waitcnt lgkmcnt(1)
	v_mfma_f32_16x16x32_bf16 v[56:59], v[56:59], v[20:23], 0
	v_pk_fma_f32 v[2:3], v[48:49], v[48:49], v[2:3] op_sel_hi:[1,1,0]
	s_nop 0
	v_mov_b32_e32 v84, v2
	s_waitcnt lgkmcnt(0)
	v_mfma_f32_16x16x32_bf16 v[56:59], v[60:63], v[24:27], v[56:59]
	ds_read_b128 v[60:63], v152 offset:4480
	ds_read_b128 v[64:67], v152 offset:4544
	v_mov_b64_e32 v[52:53], v[224:225]
	s_waitcnt lgkmcnt(1)
	v_mfma_f32_16x16x32_bf16 v[56:59], v[60:63], v[28:31], v[56:59]
	s_waitcnt vmcnt(0)
	v_lshlrev_b32_e32 v60, 16, v52
	s_waitcnt lgkmcnt(0)
	v_mfma_f32_16x16x32_bf16 v[56:59], v[64:67], v[16:19], v[56:59]
	v_and_b32_e32 v61, 0xffff0000, v52
	v_lshlrev_b32_e32 v62, 16, v53
	v_and_b32_e32 v63, 0xffff0000, v53
	s_nop 4
	v_pk_add_f32 v[56:57], v[54:55], v[56:57] op_sel_hi:[0,1]
	v_pk_add_f32 v[58:59], v[54:55], v[58:59] op_sel_hi:[0,1]
	v_pk_mul_f32 v[52:53], v[56:57], v[60:61]
	v_pk_mul_f32 v[60:61], v[58:59], v[62:63]
	v_cvt_pk_bf16_f32 v145, v52, v53
	s_nop 0
	v_cvt_pk_bf16_f32 v142, v60, v61
	ds_read_b128 v[56:59], v152 offset:8704
	ds_read_b128 v[62:65], v152 offset:8768
	s_waitcnt lgkmcnt(1)
	v_mfma_f32_16x16x32_bf16 v[56:59], v[56:59], v[20:23], 0
	s_waitcnt lgkmcnt(0)
	v_mfma_f32_16x16x32_bf16 v[56:59], v[62:65], v[24:27], v[56:59]
	ds_read_b128 v[62:65], v152 offset:8832
	ds_read_b128 v[66:69], v152 offset:8896
	s_waitcnt lgkmcnt(1)
	v_mfma_f32_16x16x32_bf16 v[56:59], v[62:65], v[28:31], v[56:59]
	v_mov_b64_e32 v[62:63], v[226:227]
	s_waitcnt vmcnt(0)
	v_lshlrev_b32_e32 v65, 16, v63
	s_waitcnt lgkmcnt(0)
	v_mfma_f32_16x16x32_bf16 v[56:59], v[66:69], v[16:19], v[56:59]
	v_and_b32_e32 v63, 0xffff0000, v63
	s_nop 6
	v_add_f32_e32 v55, v54, v56
	v_add_f32_e32 v56, v54, v57
	v_add_f32_e32 v57, v54, v58
	v_add_f32_e32 v58, v54, v59
	v_lshlrev_b32_e32 v59, 16, v62
	v_and_b32_e32 v62, 0xffff0000, v62
	v_mul_f32_e32 v64, v55, v59
	v_mul_f32_e32 v68, v56, v62
	v_mul_f32_e32 v66, v57, v65
	v_mul_f32_e32 v62, v58, v63
	v_cvt_pk_bf16_f32 v139, v64, v68
	v_cvt_pk_bf16_f32 v137, v66, v62
	ds_read_b128 v[56:59], v152 offset:13056
	ds_read_b128 v[70:73], v152 offset:13120
	s_waitcnt lgkmcnt(1)
	v_mfma_f32_16x16x32_bf16 v[56:59], v[56:59], v[20:23], 0
	s_waitcnt lgkmcnt(0)
	v_mfma_f32_16x16x32_bf16 v[56:59], v[70:73], v[24:27], v[56:59]
	ds_read_b128 v[70:73], v152 offset:13184
	ds_read_b128 v[74:77], v152 offset:13248
	v_mov_b64_e32 v[78:79], v[228:229]
	s_waitcnt lgkmcnt(1)
	v_mfma_f32_16x16x32_bf16 v[56:59], v[70:73], v[28:31], v[56:59]
	v_mov_b32_e32 v70, v64
	v_mov_b32_e32 v72, v66
	s_waitcnt vmcnt(0)
	v_lshlrev_b32_e32 v71, 16, v79
	s_waitcnt lgkmcnt(0)
	v_mfma_f32_16x16x32_bf16 v[56:59], v[74:77], v[16:19], v[56:59]
	v_and_b32_e32 v73, 0xffff0000, v79
	s_nop 6
	v_add_f32_e32 v55, v54, v56
	v_add_f32_e32 v56, v54, v57
	v_add_f32_e32 v65, v54, v58
	v_add_f32_e32 v67, v54, v59
	v_lshlrev_b32_e32 v57, 16, v78
	v_and_b32_e32 v58, 0xffff0000, v78
	v_mul_f32_e32 v85, v55, v57
	v_mul_f32_e32 v75, v56, v58
	v_pk_mul_f32 v[86:87], v[64:65], v[70:71]
	v_pk_mul_f32 v[88:89], v[66:67], v[72:73]
	v_cvt_pk_bf16_f32 v136, v85, v75
	v_lshlrev_b32_e32 v72, 16, v15
	v_cvt_pk_bf16_f32 v133, v87, v89
	ds_read_b128 v[56:59], v152 offset:17408
	ds_read_b128 v[76:79], v152 offset:17472
	s_waitcnt lgkmcnt(1)
	v_mfma_f32_16x16x32_bf16 v[56:59], v[56:59], v[20:23], 0
	v_and_b32_e32 v15, 0xffff0000, v15
	v_pk_mul_f32 v[48:49], v[88:89], v[88:89]
	s_waitcnt lgkmcnt(0)
	v_mfma_f32_16x16x32_bf16 v[56:59], v[76:79], v[24:27], v[56:59]
	ds_read_b128 v[76:79], v152 offset:17536
	ds_read_b128 v[80:83], v152 offset:17600
	s_waitcnt lgkmcnt(1)
	v_mfma_f32_16x16x32_bf16 v[56:59], v[76:79], v[28:31], v[56:59]
	v_mov_b64_e32 v[76:77], v[230:231]
	s_waitcnt lgkmcnt(0)
	v_mfma_f32_16x16x32_bf16 v[56:59], v[80:83], v[16:19], v[56:59]
	s_nop 7
	v_mov_b32_e32 v78, v56
	v_mov_b32_e32 v79, v58
	v_mov_b32_e32 v58, v57
	v_pk_add_f32 v[56:57], v[54:55], v[78:79] op_sel_hi:[0,1]
	v_pk_add_f32 v[58:59], v[54:55], v[58:59] op_sel_hi:[0,1]
	s_waitcnt vmcnt(0)
	v_lshlrev_b32_e32 v79, 16, v77
	v_lshlrev_b32_e32 v78, 16, v76
	v_and_b32_e32 v77, 0xffff0000, v77
	v_and_b32_e32 v76, 0xffff0000, v76
	v_pk_mul_f32 v[90:91], v[56:57], v[78:79]
	v_pk_mul_f32 v[92:93], v[58:59], v[76:77]
	s_nop 0
	v_cvt_pk_bf16_f32 v134, v90, v92
	v_cvt_pk_bf16_f32 v132, v91, v93
	ds_read_b128 v[56:59], v152 offset:21760
	ds_read_b128 v[76:79], v152 offset:21824
	s_waitcnt lgkmcnt(1)
	v_mfma_f32_16x16x32_bf16 v[56:59], v[56:59], v[20:23], 0
	s_waitcnt lgkmcnt(0)
	v_mfma_f32_16x16x32_bf16 v[56:59], v[76:79], v[24:27], v[56:59]
	ds_read_b128 v[76:79], v152 offset:21888
	ds_read_b128 v[80:83], v152 offset:21952
	s_waitcnt lgkmcnt(1)
	v_mfma_f32_16x16x32_bf16 v[56:59], v[76:79], v[28:31], v[56:59]
	v_mov_b64_e32 v[76:77], v[232:233]
	s_waitcnt lgkmcnt(0)
	v_mfma_f32_16x16x32_bf16 v[56:59], v[80:83], v[16:19], v[56:59]
	s_nop 7
	v_pk_add_f32 v[56:57], v[54:55], v[56:57] op_sel_hi:[0,1]
	v_pk_add_f32 v[78:79], v[54:55], v[58:59] op_sel_hi:[0,1]
	s_waitcnt vmcnt(0)
	v_lshlrev_b32_e32 v58, 16, v76
	v_and_b32_e32 v59, 0xffff0000, v76
	v_lshlrev_b32_e32 v76, 16, v77
	v_and_b32_e32 v77, 0xffff0000, v77
	v_pk_mul_f32 v[58:59], v[56:57], v[58:59]
	v_pk_mul_f32 v[94:95], v[78:79], v[76:77]
	v_cvt_pk_bf16_f32 v130, v58, v59
	s_nop 0
	v_cvt_pk_bf16_f32 v129, v94, v95
	ds_read_b128 v[76:79], v152 offset:26112
	ds_read_b128 v[80:83], v152 offset:26176
	s_waitcnt lgkmcnt(1)
	v_mfma_f32_16x16x32_bf16 v[76:79], v[76:79], v[20:23], 0
	s_waitcnt lgkmcnt(0)
	v_mfma_f32_16x16x32_bf16 v[76:79], v[80:83], v[24:27], v[76:79]
	ds_read_b128 v[80:83], v152 offset:26240
	ds_read_b128 v[96:99], v152 offset:26304
	v_mov_b64_e32 v[56:57], v[234:235]
	s_waitcnt vmcnt(0)
	v_lshlrev_b32_e32 v66, 16, v56
	s_waitcnt lgkmcnt(1)
	v_mfma_f32_16x16x32_bf16 v[76:79], v[80:83], v[28:31], v[76:79]
	v_and_b32_e32 v56, 0xffff0000, v56
	v_lshlrev_b32_e32 v70, 16, v57
	v_and_b32_e32 v57, 0xffff0000, v57
	s_waitcnt lgkmcnt(0)
	v_mfma_f32_16x16x32_bf16 v[76:79], v[96:99], v[16:19], v[76:79]
	s_nop 7
	v_add_f32_e32 v55, v54, v76
	v_add_f32_e32 v63, v54, v77
	v_add_f32_e32 v64, v54, v78
	v_add_f32_e32 v69, v54, v79
	v_mul_f32_e32 v96, v55, v66
	v_mul_f32_e32 v66, v63, v56
	v_mul_f32_e32 v98, v64, v70
	v_mul_f32_e32 v64, v69, v57
	v_cvt_pk_bf16_f32 v128, v96, v66
	v_cvt_pk_bf16_f32 v127, v98, v64
	ds_read_b128 v[76:79], v152 offset:30464
	ds_read_b128 v[80:83], v152 offset:30528
	s_waitcnt lgkmcnt(1)
	v_mfma_f32_16x16x32_bf16 v[20:23], v[76:79], v[20:23], 0
	v_mov_b32_e32 v76, v96
	v_mov_b32_e32 v78, v98
	v_and_b32_e32 v56, 0xffff0000, v12
	s_waitcnt lgkmcnt(0)
	v_mfma_f32_16x16x32_bf16 v[20:23], v[80:83], v[24:27], v[20:23]
	ds_read_b128 v[24:27], v152 offset:30592
	ds_read_b128 v[80:83], v152 offset:30656
	v_lshlrev_b32_e32 v63, 16, v13
	v_and_b32_e32 v69, 0xffff0000, v13
	s_waitcnt lgkmcnt(1)
	v_mfma_f32_16x16x32_bf16 v[20:23], v[24:27], v[28:31], v[20:23]
	v_mov_b64_e32 v[24:25], v[236:237]
	v_lshlrev_b32_e32 v70, 16, v14
	v_and_b32_e32 v14, 0xffff0000, v14
	s_waitcnt lgkmcnt(0)
	v_mfma_f32_16x16x32_bf16 v[16:19], v[80:83], v[16:19], v[20:23]
	s_waitcnt vmcnt(0)
	v_lshlrev_b32_e32 v77, 16, v25
	s_nop 5
	v_add_f32_e32 v16, v54, v16
	v_add_f32_e32 v17, v54, v17
	v_add_f32_e32 v97, v54, v18
	v_add_f32_e32 v99, v54, v19
	v_lshlrev_b32_e32 v18, 16, v24
	v_and_b32_e32 v19, 0xffff0000, v24
	v_and_b32_e32 v79, 0xffff0000, v25
	v_mul_f32_e32 v57, v16, v18
	v_mul_f32_e32 v55, v17, v19
	v_pk_mul_f32 v[80:81], v[96:97], v[76:77]
	v_pk_mul_f32 v[82:83], v[98:99], v[78:79]
	v_cvt_pk_bf16_f32 v126, v57, v55
	v_lshlrev_b32_e32 v54, 16, v12
	v_cvt_pk_bf16_f32 v125, v81, v83
	global_load_dwordx4 v[16:19], v157, s[48:49] offset:512
	global_load_dwordx4 v[20:23], v157, s[50:51] offset:512
	global_load_dwordx4 v[24:27], v157, s[48:49] offset:528
	global_load_dwordx4 v[28:31], v157, s[50:51] offset:528
	global_load_dwordx4 v[178:181], v157, s[48:49] offset:640
	global_load_dwordx4 v[182:185], v157, s[50:51] offset:640
	global_load_dwordx4 v[186:189], v157, s[48:49] offset:656
	global_load_dwordx4 v[190:193], v157, s[50:51] offset:656
	global_load_dwordx4 v[194:197], v157, s[48:49] offset:768
	global_load_dwordx4 v[198:201], v157, s[50:51] offset:768
	global_load_dwordx4 v[202:205], v157, s[48:49] offset:784
	global_load_dwordx4 v[206:209], v157, s[50:51] offset:784
	global_load_dwordx4 v[210:213], v157, s[48:49] offset:896
	global_load_dwordx4 v[214:217], v157, s[50:51] offset:896
	global_load_dwordx4 v[218:221], v157, s[48:49] offset:912
	global_load_dwordx4 v[238:241], v157, s[50:51] offset:912
	ds_read_b64 v[12:13], v160
	v_and_b32_e32 v96, 0xffff0000, v0
	v_lshlrev_b32_e32 v98, 16, v1
	v_mov_b32_e32 v76, v66
	v_mov_b32_e32 v78, v64
	s_waitcnt lgkmcnt(0)
	v_sub_f32_e32 v54, v54, v12
	v_sub_f32_e32 v15, v15, v12
	v_sub_f32_e32 v56, v56, v12
	v_mul_f32_e32 v54, v13, v54
	v_mul_f32_e32 v15, v13, v15
	v_sub_f32_e32 v63, v63, v12
	v_mul_f32_e32 v56, v13, v56
	v_sub_f32_e32 v69, v69, v12
	v_sub_f32_e32 v14, v14, v12
	v_mul_f32_e32 v63, v13, v63
	v_sub_f32_e32 v70, v70, v12
	v_mul_f32_e32 v69, v13, v69
	v_mul_f32_e32 v14, v13, v14
	v_sub_f32_e32 v72, v72, v12
	v_mul_f32_e32 v70, v13, v70
	v_mul_f32_e32 v72, v13, v72
	s_waitcnt vmcnt(2)
	v_fma_f32 v16, v16, v54, v20
	v_fma_f32 v17, v17, v56, v21
	s_waitcnt vmcnt(0)
	v_fmac_f32_e32 v31, v27, v15
	v_cvt_pk_bf16_f32 v15, v16, v33
	ds_write_b16 v155, v15 offset:34816
	v_cvt_pk_bf16_f32 v15, v17, v33
	v_fma_f32 v18, v18, v63, v22
	ds_write_b16 v155, v15 offset:35088
	v_cvt_pk_bf16_f32 v15, v18, v33
	v_fmac_f32_e32 v23, v19, v69
	v_fma_f32 v14, v25, v14, v29
	ds_write_b16 v155, v15 offset:35360
	v_cvt_pk_bf16_f32 v15, v23, v33
	v_fma_f32 v19, v24, v70, v28
	ds_write_b16 v155, v15 offset:35632
	v_cvt_pk_bf16_f32 v15, v19, v33
	ds_write_b16 v155, v15 offset:35904
	v_cvt_pk_bf16_f32 v14, v14, v33
	v_fma_f32 v20, v26, v72, v30
	ds_write_b16 v155, v14 offset:36176
	v_cvt_pk_bf16_f32 v14, v20, v33
	ds_write_b16 v155, v14 offset:36448
	v_cvt_pk_bf16_f32 v30, v31, v33
	v_mov_b64_e32 v[14:15], v[178:179]
	v_mov_b64_e32 v[16:17], v[180:181]
	v_mov_b64_e32 v[18:19], v[182:183]
	v_mov_b64_e32 v[20:21], v[184:185]
	v_mov_b64_e32 v[22:23], v[186:187]
	v_mov_b64_e32 v[24:25], v[188:189]
	v_mov_b64_e32 v[26:27], v[190:191]
	v_mov_b64_e32 v[28:29], v[192:193]
	v_lshlrev_b32_e32 v31, 16, v8
	v_and_b32_e32 v8, 0xffff0000, v8
	v_lshlrev_b32_e32 v63, 16, v11
	v_and_b32_e32 v11, 0xffff0000, v11
	v_sub_f32_e32 v8, v8, v12
	v_lshlrev_b32_e32 v54, 16, v9
	v_sub_f32_e32 v31, v31, v12
	v_sub_f32_e32 v11, v11, v12
	v_mul_f32_e32 v8, v13, v8
	v_and_b32_e32 v9, 0xffff0000, v9
	v_sub_f32_e32 v54, v54, v12
	v_mul_f32_e32 v31, v13, v31
	v_mul_f32_e32 v11, v13, v11
	v_lshlrev_b32_e32 v56, 16, v10
	v_sub_f32_e32 v9, v9, v12
	v_mul_f32_e32 v54, v13, v54
	ds_write_b16 v155, v30 offset:36720
	v_and_b32_e32 v10, 0xffff0000, v10
	v_sub_f32_e32 v56, v56, v12
	v_mul_f32_e32 v9, v13, v9
	v_sub_f32_e32 v10, v10, v12
	v_mul_f32_e32 v56, v13, v56
	v_sub_f32_e32 v63, v63, v12
	v_mul_f32_e32 v10, v13, v10
	v_mul_f32_e32 v63, v13, v63
	v_lshlrev_b32_e32 v30, 16, v7
	v_and_b32_e32 v7, 0xffff0000, v7
	v_sub_f32_e32 v7, v7, v12
	v_mul_f32_e32 v7, v13, v7
	v_sub_f32_e32 v30, v30, v12
	v_mul_f32_e32 v30, v13, v30
	v_mov_b32_e32 v69, v65
	v_mov_b32_e32 v70, v68
	v_mov_b32_e32 v72, v62
	v_mov_b32_e32 v65, v99
	s_waitcnt vmcnt(2)
	v_fma_f32 v8, v8, v15, v19
	v_fma_f32 v14, v31, v14, v18
	s_waitcnt vmcnt(0)
	v_fmac_f32_e32 v29, v11, v25
	v_cvt_pk_bf16_f32 v11, v14, v33
	ds_write_b16 v155, v11 offset:43520
	v_cvt_pk_bf16_f32 v8, v8, v33
	v_fma_f32 v15, v54, v16, v20
	ds_write_b16 v155, v8 offset:43792
	v_cvt_pk_bf16_f32 v8, v15, v33
	v_fmac_f32_e32 v21, v9, v17
	ds_write_b16 v155, v8 offset:44064
	v_cvt_pk_bf16_f32 v8, v21, v33
	v_fma_f32 v9, v56, v22, v26
	ds_write_b16 v155, v8 offset:44336
	v_cvt_pk_bf16_f32 v8, v9, v33
	v_fma_f32 v10, v10, v23, v27
	ds_write_b16 v155, v8 offset:44608
	v_cvt_pk_bf16_f32 v8, v10, v33
	v_fma_f32 v16, v63, v24, v28
	ds_write_b16 v155, v8 offset:44880
	v_cvt_pk_bf16_f32 v8, v16, v33
	ds_write_b16 v155, v8 offset:45152
	v_cvt_pk_bf16_f32 v26, v29, v33
	v_mov_b64_e32 v[8:9], v[194:195]
	v_mov_b64_e32 v[10:11], v[196:197]
	v_mov_b64_e32 v[14:15], v[198:199]
	v_mov_b64_e32 v[16:17], v[200:201]
	v_mov_b64_e32 v[18:19], v[202:203]
	v_mov_b64_e32 v[20:21], v[204:205]
	v_mov_b64_e32 v[22:23], v[206:207]
	v_mov_b64_e32 v[24:25], v[208:209]
	v_lshlrev_b32_e32 v27, 16, v4
	v_and_b32_e32 v4, 0xffff0000, v4
	v_sub_f32_e32 v4, v4, v12
	v_lshlrev_b32_e32 v28, 16, v5
	v_sub_f32_e32 v27, v27, v12
	v_mul_f32_e32 v4, v13, v4
	v_and_b32_e32 v5, 0xffff0000, v5
	v_sub_f32_e32 v28, v28, v12
	v_mul_f32_e32 v27, v13, v27
	v_lshlrev_b32_e32 v29, 16, v6
	v_sub_f32_e32 v5, v5, v12
	v_mul_f32_e32 v28, v13, v28
	ds_write_b16 v155, v26 offset:45424
	v_and_b32_e32 v6, 0xffff0000, v6
	v_sub_f32_e32 v29, v29, v12
	v_mul_f32_e32 v5, v13, v5
	v_sub_f32_e32 v6, v6, v12
	v_mul_f32_e32 v29, v13, v29
	v_mul_f32_e32 v6, v13, v6
	v_lshlrev_b32_e32 v56, 16, v0
	v_mul_f32_e32 v0, v51, v51
	v_pk_fma_f32 v[0:1], v[50:51], v[50:51], v[0:1] op_sel_hi:[1,1,0]
	v_mov_b32_e32 v63, v67
	v_mov_b32_e32 v67, v97
	s_waitcnt vmcnt(2)
	v_fma_f32 v4, v4, v9, v15
	v_fma_f32 v8, v27, v8, v14
	s_waitcnt vmcnt(0)
	v_fmac_f32_e32 v25, v7, v21
	v_cvt_pk_bf16_f32 v7, v8, v33
	ds_write_b16 v155, v7 offset:52224
	v_cvt_pk_bf16_f32 v4, v4, v33
	v_fma_f32 v9, v28, v10, v16
	ds_write_b16 v155, v4 offset:52496
	v_cvt_pk_bf16_f32 v4, v9, v33
	v_fmac_f32_e32 v17, v5, v11
	ds_write_b16 v155, v4 offset:52768
	v_cvt_pk_bf16_f32 v4, v17, v33
	v_fma_f32 v5, v29, v18, v22
	ds_write_b16 v155, v4 offset:53040
	v_cvt_pk_bf16_f32 v4, v5, v33
	v_fma_f32 v6, v6, v19, v23
	ds_write_b16 v155, v4 offset:53312
	v_cvt_pk_bf16_f32 v4, v6, v33
	v_fma_f32 v10, v30, v20, v24
	ds_write_b16 v155, v4 offset:53584
	v_cvt_pk_bf16_f32 v4, v10, v33
	ds_write_b16 v155, v4 offset:53856
	v_cvt_pk_bf16_f32 v54, v25, v33
	v_mov_b64_e32 v[4:5], v[210:211]
	v_mov_b64_e32 v[6:7], v[212:213]
	v_mov_b64_e32 v[8:9], v[214:215]
	v_mov_b64_e32 v[10:11], v[216:217]
	v_mov_b64_e32 v[14:15], v[218:219]
	v_mov_b64_e32 v[16:17], v[220:221]
	v_mov_b64_e32 v[18:19], v[238:239]
	v_mov_b64_e32 v[20:21], v[240:241]
	v_mov_b32_e32 v22, v0
	v_pk_add_f32 v[0:1], v[2:3], v[0:1]
	v_mul_f32_e32 v2, v61, v61
	v_mul_f32_e32 v24, v53, v53
	v_pk_fma_f32 v[2:3], v[60:61], v[60:61], v[2:3] op_sel_hi:[1,1,0]
	v_pk_fma_f32 v[24:25], v[52:53], v[52:53], v[24:25] op_sel_hi:[1,1,0]
	v_mov_b32_e32 v26, v2
	v_mov_b32_e32 v74, v24
	v_mov_b32_e32 v23, v85
	v_mov_b32_e32 v27, v75
	v_pk_add_f32 v[2:3], v[24:25], v[2:3]
	v_pk_fma_f32 v[24:25], v[68:69], v[70:71], v[86:87]
	v_pk_mul_f32 v[28:29], v[86:87], v[86:87]
	v_pk_fma_f32 v[30:31], v[62:63], v[72:73], v[88:89]
	v_pk_mul_f32 v[22:23], v[84:85], v[22:23]
	v_pk_mul_f32 v[26:27], v[74:75], v[26:27]
	v_mov_b32_e32 v25, v29
	v_mov_b32_e32 v31, v49
	v_mov_b32_e32 v1, v23
	v_mov_b32_e32 v3, v27
	v_pk_add_f32 v[22:23], v[24:25], v[30:31]
	v_pk_add_f32 v[0:1], v[0:1], v[2:3]
	v_sub_f32_e32 v2, v98, v12
	v_pk_add_f32 v[88:89], v[0:1], v[22:23]
	v_pk_mul_f32 v[0:1], v[92:93], v[92:93]
	ds_write_b16 v155, v54 offset:54128
	v_pk_fma_f32 v[0:1], v[90:91], v[90:91], v[0:1]
	v_sub_f32_e32 v3, v100, v12
	v_pk_add_f32 v[86:87], v[0:1], v[0:1] op_sel:[0,1] op_sel_hi:[1,0]
	v_mul_f32_e32 v0, v95, v95
	v_pk_fma_f32 v[84:85], v[94:95], v[94:95], v[0:1] op_sel_hi:[1,1,0]
	v_sub_f32_e32 v0, v56, v12
	v_mul_f32_e32 v0, v13, v0
	v_sub_f32_e32 v1, v96, v12
	v_mul_f32_e32 v1, v13, v1
	v_mul_f32_e32 v2, v13, v2
	v_sub_f32_e32 v22, v101, v12
	v_mul_f32_e32 v3, v13, v3
	v_sub_f32_e32 v23, v102, v12
	v_mul_f32_e32 v22, v13, v22
	v_sub_f32_e32 v24, v103, v12
	v_mul_f32_e32 v23, v13, v23
	v_sub_f32_e32 v12, v104, v12
	v_mul_f32_e32 v24, v13, v24
	v_mul_f32_e32 v12, v13, v12
	s_waitcnt vmcnt(2)
	v_fma_f32 v0, v0, v4, v8
	v_cvt_pk_bf16_f32 v0, v0, v33
	v_fma_f32 v1, v1, v5, v9
	ds_write_b16 v155, v0 offset:60928
	v_cvt_pk_bf16_f32 v0, v1, v33
	v_fma_f32 v2, v2, v6, v10
	ds_write_b16 v155, v0 offset:61200
	v_cvt_pk_bf16_f32 v0, v2, v33
	v_fmac_f32_e32 v11, v3, v7
	ds_write_b16 v155, v0 offset:61472
	v_cvt_pk_bf16_f32 v0, v11, v33
	s_waitcnt vmcnt(0)
	v_fma_f32 v3, v22, v14, v18
	ds_write_b16 v155, v0 offset:61744
	v_cvt_pk_bf16_f32 v0, v3, v33
	v_fma_f32 v4, v23, v15, v19
	ds_write_b16 v155, v0 offset:62016
	v_cvt_pk_bf16_f32 v0, v4, v33
	v_fma_f32 v5, v24, v16, v20
	ds_write_b16 v155, v0 offset:62288
	v_cvt_pk_bf16_f32 v0, v5, v33
	v_fmac_f32_e32 v21, v12, v17
	ds_write_b16 v155, v0 offset:62560
	v_cvt_pk_bf16_f32 v0, v21, v33
	ds_write_b16 v155, v0 offset:62832
	s_waitcnt lgkmcnt(0)
	s_barrier
	v_add_co_u32_e32 v0, vcc, s26, v42
	v_pk_fma_f32 v[66:67], v[66:67], v[76:77], v[80:81]
	s_nop 0
	v_addc_co_u32_e32 v1, vcc, 0, v43, vcc
	global_load_dwordx2 v[224:225], v[40:41], off offset:1312
	global_load_dwordx2 v[226:227], v[40:41], off offset:1344
	global_load_dwordx2 v[228:229], v[40:41], off offset:1376
	global_load_dwordx2 v[230:231], v[40:41], off offset:1408
	global_load_dwordx2 v[232:233], v[40:41], off offset:1440
	global_load_dwordx2 v[234:235], v[40:41], off offset:1472
	global_load_dwordx2 v[236:237], v[40:41], off offset:1504
	global_load_dwordx4 v[20:23], v[0:1], off
	global_load_dwordx4 v[24:27], v[0:1], off offset:64
	global_load_dwordx2 v[72:73], v[40:41], off offset:1280
	global_load_dwordx4 v[28:31], v[0:1], off offset:128
	global_load_dwordx4 v[16:19], v[0:1], off offset:192
	global_load_dword v48, v[44:45], off offset:512
	ds_read_b128 v[0:3], v152 offset:34816
	ds_read_b128 v[4:7], v152 offset:34880
	ds_read_b128 v[50:53], v152 offset:34944
	global_load_dwordx4 v[12:15], v[46:47], off offset:2560
	global_load_dwordx4 v[8:11], v[46:47], off offset:2624
	ds_read_b128 v[60:63], v152 offset:35008
	v_pk_mul_f32 v[76:77], v[80:81], v[80:81]
	v_pk_fma_f32 v[64:65], v[64:65], v[78:79], v[82:83]
	v_pk_mul_f32 v[78:79], v[82:83], v[82:83]
	v_mov_b32_e32 v67, v77
	v_mov_b32_e32 v65, v79
	s_waitcnt vmcnt(7) lgkmcnt(3)
	v_mfma_f32_16x16x32_bf16 v[0:3], v[0:3], v[20:23], 0
	s_waitcnt vmcnt(5)
	v_lshlrev_b32_e32 v75, 16, v73
	v_lshlrev_b32_e32 v74, 16, v72
	s_waitcnt lgkmcnt(2)
	v_mfma_f32_16x16x32_bf16 v[68:71], v[4:7], v[24:27], v[0:3]
	global_load_dwordx4 v[4:7], v[46:47], off offset:2688
	s_nop 1
	global_load_dwordx4 v[0:3], v[46:47], off offset:2752
	s_waitcnt vmcnt(0)
	v_and_b32_e32 v76, 0xffff0000, v1
	s_waitcnt lgkmcnt(1)
	v_mfma_f32_16x16x32_bf16 v[50:53], v[50:53], v[28:31], v[68:71]
	v_lshlrev_b32_e32 v77, 16, v2
	v_and_b32_e32 v78, 0xffff0000, v2
	v_lshlrev_b32_e32 v79, 16, v3
	s_waitcnt lgkmcnt(0)
	v_mfma_f32_16x16x32_bf16 v[50:53], v[60:63], v[16:19], v[50:53]
	v_and_b32_e32 v69, 0xffff0000, v73
	v_and_b32_e32 v68, 0xffff0000, v72
	v_and_b32_e32 v80, 0xffff0000, v3
	s_nop 4
	v_mov_b32_e32 v60, v50
	v_mov_b32_e32 v61, v52
	v_mov_b32_e32 v52, v51
	v_pk_add_f32 v[50:51], v[48:49], v[60:61] op_sel_hi:[0,1]
	v_pk_add_f32 v[52:53], v[48:49], v[52:53] op_sel_hi:[0,1]
	v_pk_mul_f32 v[90:91], v[50:51], v[74:75]
	v_pk_mul_f32 v[92:93], v[52:53], v[68:69]
	s_nop 0
	v_cvt_pk_bf16_f32 v156, v90, v92
	v_cvt_pk_bf16_f32 v154, v91, v93
	ds_read_b128 v[50:53], v152 offset:39168
	ds_read_b128 v[60:63], v152 offset:39232
	s_waitcnt lgkmcnt(1)
	v_mfma_f32_16x16x32_bf16 v[50:53], v[50:53], v[20:23], 0
	s_waitcnt lgkmcnt(0)
	v_mfma_f32_16x16x32_bf16 v[50:53], v[60:63], v[24:27], v[50:53]
	ds_read_b128 v[60:63], v152 offset:39296
	ds_read_b128 v[68:71], v152 offset:39360
	s_waitcnt lgkmcnt(1)
	v_mfma_f32_16x16x32_bf16 v[50:53], v[60:63], v[28:31], v[50:53]
	v_mov_b64_e32 v[60:61], v[224:225]
	s_waitcnt vmcnt(0)
	v_lshlrev_b32_e32 v62, 16, v60
	s_waitcnt lgkmcnt(0)
	v_mfma_f32_16x16x32_bf16 v[50:53], v[68:71], v[16:19], v[50:53]
	v_and_b32_e32 v63, 0xffff0000, v60
	v_lshlrev_b32_e32 v60, 16, v61
	v_and_b32_e32 v61, 0xffff0000, v61
	s_nop 4
	v_pk_add_f32 v[50:51], v[48:49], v[50:51] op_sel_hi:[0,1]
	v_pk_add_f32 v[52:53], v[48:49], v[52:53] op_sel_hi:[0,1]
	v_pk_mul_f32 v[94:95], v[50:51], v[62:63]
	v_pk_mul_f32 v[96:97], v[52:53], v[60:61]
	v_cvt_pk_bf16_f32 v153, v94, v95
	s_nop 0
	v_cvt_pk_bf16_f32 v151, v96, v97
	ds_read_b128 v[50:53], v152 offset:43520
	ds_read_b128 v[60:63], v152 offset:43584
	s_waitcnt lgkmcnt(1)
	v_mfma_f32_16x16x32_bf16 v[50:53], v[50:53], v[20:23], 0
	s_waitcnt lgkmcnt(0)
	v_mfma_f32_16x16x32_bf16 v[50:53], v[60:63], v[24:27], v[50:53]
	ds_read_b128 v[60:63], v152 offset:43648
	ds_read_b128 v[68:71], v152 offset:43712
	s_waitcnt lgkmcnt(1)
	v_mfma_f32_16x16x32_bf16 v[50:53], v[60:63], v[28:31], v[50:53]
	v_mov_b64_e32 v[60:61], v[226:227]
	s_waitcnt vmcnt(0)
	v_and_b32_e32 v54, 0xffff0000, v60
	s_waitcnt lgkmcnt(0)
	v_mfma_f32_16x16x32_bf16 v[50:53], v[68:71], v[16:19], v[50:53]
	v_lshlrev_b32_e32 v56, 16, v61
	v_and_b32_e32 v61, 0xffff0000, v61
	s_nop 5
	v_add_f32_e32 v49, v48, v50
	v_add_f32_e32 v50, v48, v51
	v_add_f32_e32 v51, v48, v52
	v_add_f32_e32 v52, v48, v53
	v_lshlrev_b32_e32 v53, 16, v60
	v_mul_f32_e32 v60, v49, v53
	v_mul_f32_e32 v100, v50, v54
	v_mul_f32_e32 v62, v51, v56
	v_mul_f32_e32 v98, v52, v61
	v_cvt_pk_bf16_f32 v149, v60, v100
	v_cvt_pk_bf16_f32 v147, v62, v98
	ds_read_b128 v[50:53], v152 offset:47872
	ds_read_b128 v[68:71], v152 offset:47936
	s_waitcnt lgkmcnt(1)
	v_mfma_f32_16x16x32_bf16 v[50:53], v[50:53], v[20:23], 0
	v_mov_b32_e32 v102, v60
	v_mov_b32_e32 v104, v62
	s_waitcnt lgkmcnt(0)
	v_mfma_f32_16x16x32_bf16 v[50:53], v[68:71], v[24:27], v[50:53]
	ds_read_b128 v[68:71], v152 offset:48000
	ds_read_b128 v[72:75], v152 offset:48064
	s_waitcnt lgkmcnt(1)
	v_mfma_f32_16x16x32_bf16 v[50:53], v[68:71], v[28:31], v[50:53]
	v_mov_b64_e32 v[68:69], v[228:229]
	s_waitcnt vmcnt(0)
	v_lshlrev_b32_e32 v103, 16, v69
	s_waitcnt lgkmcnt(0)
	v_mfma_f32_16x16x32_bf16 v[50:53], v[72:75], v[16:19], v[50:53]
	v_and_b32_e32 v105, 0xffff0000, v69
	s_nop 6
	v_add_f32_e32 v49, v48, v50
	v_add_f32_e32 v50, v48, v51
	v_add_f32_e32 v61, v48, v52
	v_add_f32_e32 v63, v48, v53
	v_lshlrev_b32_e32 v51, 16, v68
	v_and_b32_e32 v52, 0xffff0000, v68
	v_mul_f32_e32 v109, v49, v51
	v_mul_f32_e32 v107, v50, v52
	v_pk_mul_f32 v[110:111], v[60:61], v[102:103]
	v_pk_mul_f32 v[112:113], v[62:63], v[104:105]
	v_cvt_pk_bf16_f32 v146, v109, v107
	v_mov_b32_e32 v101, v61
	v_cvt_pk_bf16_f32 v143, v111, v113
	ds_read_b128 v[50:53], v152 offset:52224
	ds_read_b128 v[68:71], v152 offset:52288
	s_waitcnt lgkmcnt(1)
	v_mfma_f32_16x16x32_bf16 v[50:53], v[50:53], v[20:23], 0
	v_mov_b32_e32 v99, v63
	v_mov_b32_e32 v102, v100
	v_mov_b32_e32 v104, v98
	s_waitcnt lgkmcnt(0)
	v_mfma_f32_16x16x32_bf16 v[50:53], v[68:71], v[24:27], v[50:53]
	ds_read_b128 v[68:71], v152 offset:52352
	ds_read_b128 v[72:75], v152 offset:52416
	v_mov_b32_e32 v3, v109
	s_waitcnt lgkmcnt(1)
	v_mfma_f32_16x16x32_bf16 v[50:53], v[68:71], v[28:31], v[50:53]
	v_mov_b64_e32 v[68:69], v[230:231]
	s_waitcnt lgkmcnt(0)
	v_mfma_f32_16x16x32_bf16 v[50:53], v[72:75], v[16:19], v[50:53]
	s_nop 7
	v_mov_b32_e32 v70, v50
	v_mov_b32_e32 v71, v52
	v_mov_b32_e32 v52, v51
	v_pk_add_f32 v[50:51], v[48:49], v[70:71] op_sel_hi:[0,1]
	v_pk_add_f32 v[52:53], v[48:49], v[52:53] op_sel_hi:[0,1]
	s_waitcnt vmcnt(0)
	v_lshlrev_b32_e32 v71, 16, v69
	v_lshlrev_b32_e32 v70, 16, v68
	v_and_b32_e32 v69, 0xffff0000, v69
	v_and_b32_e32 v68, 0xffff0000, v68
	v_pk_mul_f32 v[114:115], v[50:51], v[70:71]
	v_pk_mul_f32 v[116:117], v[52:53], v[68:69]
	s_nop 0
	v_cvt_pk_bf16_f32 v144, v114, v116
	v_cvt_pk_bf16_f32 v141, v115, v117
	ds_read_b128 v[50:53], v152 offset:56576
	ds_read_b128 v[68:71], v152 offset:56640
	s_waitcnt lgkmcnt(1)
	v_mfma_f32_16x16x32_bf16 v[50:53], v[50:53], v[20:23], 0
	s_waitcnt lgkmcnt(0)
	v_mfma_f32_16x16x32_bf16 v[50:53], v[68:71], v[24:27], v[50:53]
	ds_read_b128 v[68:71], v152 offset:56704
	ds_read_b128 v[72:75], v152 offset:56768
	s_waitcnt lgkmcnt(1)
	v_mfma_f32_16x16x32_bf16 v[50:53], v[68:71], v[28:31], v[50:53]
	v_mov_b64_e32 v[68:69], v[232:233]
	s_waitcnt lgkmcnt(0)
	v_mfma_f32_16x16x32_bf16 v[50:53], v[72:75], v[16:19], v[50:53]
	s_nop 7
	v_pk_add_f32 v[50:51], v[48:49], v[50:51] op_sel_hi:[0,1]
	v_pk_add_f32 v[70:71], v[48:49], v[52:53] op_sel_hi:[0,1]
	s_waitcnt vmcnt(0)
	v_lshlrev_b32_e32 v52, 16, v68
	v_and_b32_e32 v53, 0xffff0000, v68
	v_lshlrev_b32_e32 v68, 16, v69
	v_and_b32_e32 v69, 0xffff0000, v69
	v_pk_mul_f32 v[52:53], v[50:51], v[52:53]
	v_pk_mul_f32 v[118:119], v[70:71], v[68:69]
	v_cvt_pk_bf16_f32 v140, v52, v53
	s_nop 0
	v_cvt_pk_bf16_f32 v138, v118, v119
	ds_read_b128 v[68:71], v152 offset:60928
	ds_read_b128 v[72:75], v152 offset:60992
	s_waitcnt lgkmcnt(1)
	v_mfma_f32_16x16x32_bf16 v[68:71], v[68:71], v[20:23], 0
	s_waitcnt lgkmcnt(0)
	v_mfma_f32_16x16x32_bf16 v[68:71], v[72:75], v[24:27], v[68:71]
	ds_read_b128 v[72:75], v152 offset:61056
	ds_read_b128 v[120:123], v152 offset:61120
	v_mov_b64_e32 v[50:51], v[234:235]
	s_waitcnt vmcnt(0)
	v_lshlrev_b32_e32 v62, 16, v50
	s_waitcnt lgkmcnt(1)
	v_mfma_f32_16x16x32_bf16 v[68:71], v[72:75], v[28:31], v[68:71]
	v_and_b32_e32 v50, 0xffff0000, v50
	s_waitcnt lgkmcnt(0)
	v_mfma_f32_16x16x32_bf16 v[68:71], v[120:123], v[16:19], v[68:71]
	s_nop 7
	v_add_f32_e32 v49, v48, v68
	v_add_f32_e32 v54, v48, v69
	v_add_f32_e32 v56, v48, v70
	v_add_f32_e32 v60, v48, v71
	v_lshlrev_b32_e32 v68, 16, v51
	v_and_b32_e32 v51, 0xffff0000, v51
	v_mul_f32_e32 v120, v49, v62
	v_mul_f32_e32 v62, v54, v50
	v_mul_f32_e32 v122, v56, v68
	v_mul_f32_e32 v60, v60, v51
	v_cvt_pk_bf16_f32 v135, v120, v62
	v_cvt_pk_bf16_f32 v131, v122, v60
	ds_read_b128 v[68:71], v152 offset:65280
	ds_read_b128 v[72:75], v152 offset:65344
	s_waitcnt lgkmcnt(1)
	v_mfma_f32_16x16x32_bf16 v[20:23], v[68:71], v[20:23], 0
	v_mov_b32_e32 v68, v120
	v_mov_b32_e32 v70, v122
	v_and_b32_e32 v50, 0xffff0000, v12
	s_waitcnt lgkmcnt(0)
	v_mfma_f32_16x16x32_bf16 v[20:23], v[72:75], v[24:27], v[20:23]
	ds_read_b128 v[24:27], v152 offset:65408
	ds_read_b128 v[72:75], v152 offset:65472
	v_lshlrev_b32_e32 v54, 16, v13
	v_and_b32_e32 v56, 0xffff0000, v13
	s_waitcnt lgkmcnt(1)
	v_mfma_f32_16x16x32_bf16 v[20:23], v[24:27], v[28:31], v[20:23]
	v_mov_b64_e32 v[24:25], v[236:237]
	s_waitcnt vmcnt(0)
	v_lshlrev_b32_e32 v69, 16, v25
	s_waitcnt lgkmcnt(0)
	v_mfma_f32_16x16x32_bf16 v[16:19], v[72:75], v[16:19], v[20:23]
	v_and_b32_e32 v71, 0xffff0000, v25
	s_nop 6
	v_add_f32_e32 v16, v48, v16
	v_add_f32_e32 v17, v48, v17
	v_add_f32_e32 v121, v48, v18
	v_add_f32_e32 v123, v48, v19
	v_lshlrev_b32_e32 v18, 16, v24
	v_and_b32_e32 v19, 0xffff0000, v24
	v_mul_f32_e32 v51, v16, v18
	v_mul_f32_e32 v49, v17, v19
	v_pk_mul_f32 v[72:73], v[120:121], v[68:69]
	v_pk_mul_f32 v[74:75], v[122:123], v[70:71]
	v_cvt_pk_bf16_f32 v122, v51, v49
	v_lshlrev_b32_e32 v48, 16, v12
	v_cvt_pk_bf16_f32 v120, v73, v75
	global_load_dwordx4 v[16:19], v157, s[48:49] offset:1024
	global_load_dwordx4 v[20:23], v157, s[50:51] offset:1024
	global_load_dwordx4 v[24:27], v157, s[48:49] offset:1040
	global_load_dwordx4 v[28:31], v157, s[50:51] offset:1040
	global_load_dwordx4 v[178:181], v157, s[48:49] offset:1152
	global_load_dwordx4 v[182:185], v157, s[50:51] offset:1152
	global_load_dwordx4 v[186:189], v157, s[48:49] offset:1168
	global_load_dwordx4 v[190:193], v157, s[50:51] offset:1168
	global_load_dwordx4 v[194:197], v157, s[48:49] offset:1280
	global_load_dwordx4 v[198:201], v157, s[50:51] offset:1280
	global_load_dwordx4 v[202:205], v157, s[48:49] offset:1296
	global_load_dwordx4 v[206:209], v157, s[50:51] offset:1296
	global_load_dwordx4 v[210:213], v157, s[48:49] offset:1408
	global_load_dwordx4 v[214:217], v157, s[50:51] offset:1408
	global_load_dwordx4 v[218:221], v157, s[48:49] offset:1424
	global_load_dwordx4 v[238:241], v157, s[50:51] offset:1424
	ds_read_b64 v[12:13], v160
	v_lshlrev_b32_e32 v70, 16, v15
	v_and_b32_e32 v15, 0xffff0000, v15
	v_lshlrev_b32_e32 v68, 16, v14
	v_and_b32_e32 v14, 0xffff0000, v14
	s_waitcnt lgkmcnt(0)
	v_sub_f32_e32 v48, v48, v12
	v_sub_f32_e32 v15, v15, v12
	v_sub_f32_e32 v50, v50, v12
	v_mul_f32_e32 v48, v13, v48
	v_mul_f32_e32 v15, v13, v15
	v_sub_f32_e32 v54, v54, v12
	v_mul_f32_e32 v50, v13, v50
	v_sub_f32_e32 v56, v56, v12
	v_sub_f32_e32 v14, v14, v12
	v_mul_f32_e32 v54, v13, v54
	v_sub_f32_e32 v68, v68, v12
	v_mul_f32_e32 v56, v13, v56
	v_mul_f32_e32 v14, v13, v14
	v_sub_f32_e32 v70, v70, v12
	v_mul_f32_e32 v68, v13, v68
	v_mul_f32_e32 v70, v13, v70
	v_mov_b32_e32 v63, v121
	v_mov_b32_e32 v61, v123
	s_waitcnt vmcnt(2)
	v_fma_f32 v16, v16, v48, v20
	v_fma_f32 v17, v17, v50, v21
	s_waitcnt vmcnt(0)
	v_fmac_f32_e32 v31, v27, v15
	v_cvt_pk_bf16_f32 v15, v16, v33
	ds_write_b16 v155, v15
	v_cvt_pk_bf16_f32 v15, v17, v33
	v_fma_f32 v18, v18, v54, v22
	ds_write_b16 v155, v15 offset:272
	v_cvt_pk_bf16_f32 v15, v18, v33
	v_fmac_f32_e32 v23, v19, v56
	v_fma_f32 v14, v25, v14, v29
	ds_write_b16 v155, v15 offset:544
	v_cvt_pk_bf16_f32 v15, v23, v33
	v_fma_f32 v19, v24, v68, v28
	ds_write_b16 v155, v15 offset:816
	v_cvt_pk_bf16_f32 v15, v19, v33
	ds_write_b16 v155, v15 offset:1088
	v_cvt_pk_bf16_f32 v14, v14, v33
	v_fma_f32 v20, v26, v70, v30
	ds_write_b16 v155, v14 offset:1360
	v_cvt_pk_bf16_f32 v14, v20, v33
	ds_write_b16 v155, v14 offset:1632
	v_cvt_pk_bf16_f32 v30, v31, v33
	v_mov_b64_e32 v[14:15], v[178:179]
	v_mov_b64_e32 v[16:17], v[180:181]
	v_mov_b64_e32 v[18:19], v[182:183]
	v_mov_b64_e32 v[20:21], v[184:185]
	v_mov_b64_e32 v[22:23], v[186:187]
	v_mov_b64_e32 v[24:25], v[188:189]
	v_mov_b64_e32 v[26:27], v[190:191]
	v_mov_b64_e32 v[28:29], v[192:193]
	v_lshlrev_b32_e32 v31, 16, v8
	v_and_b32_e32 v8, 0xffff0000, v8
	v_lshlrev_b32_e32 v54, 16, v11
	v_and_b32_e32 v11, 0xffff0000, v11
	v_sub_f32_e32 v8, v8, v12
	v_lshlrev_b32_e32 v48, 16, v9
	v_sub_f32_e32 v31, v31, v12
	v_sub_f32_e32 v11, v11, v12
	v_mul_f32_e32 v8, v13, v8
	v_and_b32_e32 v9, 0xffff0000, v9
	v_sub_f32_e32 v48, v48, v12
	v_mul_f32_e32 v31, v13, v31
	v_mul_f32_e32 v11, v13, v11
	v_lshlrev_b32_e32 v50, 16, v10
	v_sub_f32_e32 v9, v9, v12
	v_mul_f32_e32 v48, v13, v48
	ds_write_b16 v155, v30 offset:1904
	v_and_b32_e32 v10, 0xffff0000, v10
	v_sub_f32_e32 v50, v50, v12
	v_mul_f32_e32 v9, v13, v9
	v_sub_f32_e32 v10, v10, v12
	v_mul_f32_e32 v50, v13, v50
	v_sub_f32_e32 v54, v54, v12
	v_mul_f32_e32 v10, v13, v10
	v_mul_f32_e32 v54, v13, v54
	v_mul_f32_e32 v30, v59, v59
	v_mov_b32_e32 v68, v62
	v_mov_b32_e32 v70, v60
	s_waitcnt vmcnt(2)
	v_fma_f32 v8, v8, v15, v19
	v_fma_f32 v14, v31, v14, v18
	s_waitcnt vmcnt(0)
	v_fmac_f32_e32 v29, v11, v25
	v_cvt_pk_bf16_f32 v11, v14, v33
	ds_write_b16 v155, v11 offset:8704
	v_cvt_pk_bf16_f32 v8, v8, v33
	v_fma_f32 v15, v48, v16, v20
	ds_write_b16 v155, v8 offset:8976
	v_cvt_pk_bf16_f32 v8, v15, v33
	v_fmac_f32_e32 v21, v9, v17
	ds_write_b16 v155, v8 offset:9248
	v_cvt_pk_bf16_f32 v8, v21, v33
	v_fma_f32 v9, v50, v22, v26
	ds_write_b16 v155, v8 offset:9520
	v_cvt_pk_bf16_f32 v8, v9, v33
	v_fma_f32 v10, v10, v23, v27
	ds_write_b16 v155, v8 offset:9792
	v_cvt_pk_bf16_f32 v8, v10, v33
	v_fma_f32 v16, v54, v24, v28
	ds_write_b16 v155, v8 offset:10064
	v_cvt_pk_bf16_f32 v8, v16, v33
	ds_write_b16 v155, v8 offset:10336
	v_cvt_pk_bf16_f32 v48, v29, v33
	v_mov_b64_e32 v[8:9], v[194:195]
	v_mov_b64_e32 v[10:11], v[196:197]
	v_mov_b64_e32 v[14:15], v[198:199]
	v_mov_b64_e32 v[16:17], v[200:201]
	v_mov_b64_e32 v[18:19], v[202:203]
	v_mov_b64_e32 v[20:21], v[204:205]
	v_mov_b64_e32 v[22:23], v[206:207]
	v_mov_b64_e32 v[24:25], v[208:209]
	v_pk_add_f32 v[26:27], v[88:89], v[88:89] op_sel:[0,1] op_sel_hi:[1,0]
	v_pk_fma_f32 v[30:31], v[58:59], v[58:59], v[30:31] op_sel_hi:[1,1,0]
	v_mov_b32_e32 v56, v26
	v_pk_add_f32 v[26:27], v[26:27], v[86:87]
	v_lshlrev_b32_e32 v58, 16, v7
	v_lshlrev_b32_e32 v27, 16, v4
	v_and_b32_e32 v4, 0xffff0000, v4
	v_and_b32_e32 v7, 0xffff0000, v7
	v_sub_f32_e32 v4, v4, v12
	v_lshlrev_b32_e32 v50, 16, v5
	v_sub_f32_e32 v27, v27, v12
	v_sub_f32_e32 v7, v7, v12
	v_mul_f32_e32 v4, v13, v4
	v_and_b32_e32 v5, 0xffff0000, v5
	v_sub_f32_e32 v50, v50, v12
	v_mul_f32_e32 v27, v13, v27
	v_mul_f32_e32 v7, v13, v7
	v_lshlrev_b32_e32 v54, 16, v6
	v_sub_f32_e32 v5, v5, v12
	v_mul_f32_e32 v50, v13, v50
	ds_write_b16 v155, v48 offset:10608
	v_and_b32_e32 v6, 0xffff0000, v6
	v_sub_f32_e32 v54, v54, v12
	v_mul_f32_e32 v5, v13, v5
	v_sub_f32_e32 v6, v6, v12
	v_mul_f32_e32 v54, v13, v54
	v_sub_f32_e32 v58, v58, v12
	v_mul_f32_e32 v6, v13, v6
	v_mul_f32_e32 v58, v13, v58
	v_mov_b32_e32 v28, v86
	v_mov_b32_e32 v29, v57
	v_mov_b32_e32 v88, v84
	v_mov_b32_e32 v89, v55
	s_waitcnt vmcnt(2)
	v_fma_f32 v4, v4, v9, v15
	v_fma_f32 v8, v27, v8, v14
	s_waitcnt vmcnt(0)
	v_fmac_f32_e32 v25, v7, v21
	v_cvt_pk_bf16_f32 v7, v8, v33
	ds_write_b16 v155, v7 offset:17408
	v_cvt_pk_bf16_f32 v4, v4, v33
	v_fma_f32 v9, v50, v10, v16
	ds_write_b16 v155, v4 offset:17680
	v_cvt_pk_bf16_f32 v4, v9, v33
	v_fmac_f32_e32 v17, v5, v11
	ds_write_b16 v155, v4 offset:17952
	v_cvt_pk_bf16_f32 v4, v17, v33
	v_fma_f32 v5, v54, v18, v22
	ds_write_b16 v155, v4 offset:18224
	v_cvt_pk_bf16_f32 v4, v5, v33
	v_fma_f32 v6, v6, v19, v23
	ds_write_b16 v155, v4 offset:18496
	v_cvt_pk_bf16_f32 v4, v6, v33
	v_fma_f32 v10, v58, v20, v24
	ds_write_b16 v155, v4 offset:18768
	v_cvt_pk_bf16_f32 v4, v10, v33
	ds_write_b16 v155, v4 offset:19040
	v_cvt_pk_bf16_f32 v48, v25, v33
	v_mov_b64_e32 v[4:5], v[210:211]
	v_mov_b64_e32 v[6:7], v[212:213]
	v_mov_b64_e32 v[8:9], v[214:215]
	v_mov_b64_e32 v[10:11], v[216:217]
	v_mov_b64_e32 v[14:15], v[218:219]
	v_mov_b64_e32 v[16:17], v[220:221]
	v_mov_b64_e32 v[18:19], v[238:239]
	v_mov_b64_e32 v[20:21], v[240:241]
	v_pk_mul_f32 v[22:23], v[56:57], v[28:29]
	v_mov_b32_e32 v54, v30
	v_pk_add_f32 v[24:25], v[30:31], v[84:85]
	v_mov_b32_e32 v27, v23
	v_pk_mul_f32 v[22:23], v[54:55], v[88:89]
	v_pk_add_f32 v[28:29], v[66:67], v[64:65]
	v_mov_b32_e32 v25, v23
	v_pk_add_f32 v[22:23], v[26:27], v[24:25]
	v_lshlrev_b32_e32 v50, 16, v0
	v_and_b32_e32 v56, 0xffff0000, v0
	v_lshlrev_b32_e32 v57, 16, v1
	v_pk_mul_f32 v[0:1], v[92:93], v[92:93]
	v_pk_add_f32 v[22:23], v[22:23], v[28:29]
	v_pk_fma_f32 v[0:1], v[90:91], v[90:91], v[0:1]
	v_pk_add_f32 v[22:23], v[22:23], v[22:23] op_sel:[0,1] op_sel_hi:[1,0]
	v_pk_add_f32 v[0:1], v[0:1], v[0:1] op_sel:[0,1] op_sel_hi:[1,0]
	v_mov_b32_e32 v108, v22
	v_mov_b32_e32 v2, v0
	v_pk_add_f32 v[0:1], v[22:23], v[0:1]
	v_mul_f32_e32 v22, v97, v97
	v_mul_f32_e32 v24, v95, v95
	v_pk_fma_f32 v[22:23], v[96:97], v[96:97], v[22:23] op_sel_hi:[1,1,0]
	v_pk_fma_f32 v[24:25], v[94:95], v[94:95], v[24:25] op_sel_hi:[1,1,0]
	v_mov_b32_e32 v26, v22
	v_mov_b32_e32 v106, v24
	v_mov_b32_e32 v27, v107
	v_pk_add_f32 v[22:23], v[24:25], v[22:23]
	v_pk_fma_f32 v[24:25], v[100:101], v[102:103], v[110:111]
	v_pk_mul_f32 v[28:29], v[110:111], v[110:111]
	v_pk_fma_f32 v[30:31], v[98:99], v[104:105], v[112:113]
	v_pk_mul_f32 v[54:55], v[112:113], v[112:113]
	v_pk_mul_f32 v[2:3], v[108:109], v[2:3]
	v_pk_mul_f32 v[26:27], v[106:107], v[26:27]
	v_mov_b32_e32 v25, v29
	v_mov_b32_e32 v31, v55
	v_mov_b32_e32 v1, v3
	v_mov_b32_e32 v23, v27
	v_pk_add_f32 v[2:3], v[24:25], v[30:31]
	v_pk_add_f32 v[0:1], v[0:1], v[22:23]
	ds_write_b16 v155, v48 offset:19312
	v_pk_add_f32 v[66:67], v[0:1], v[2:3]
	v_pk_mul_f32 v[0:1], v[116:117], v[116:117]
	v_sub_f32_e32 v2, v57, v12
	v_pk_fma_f32 v[0:1], v[114:115], v[114:115], v[0:1]
	v_sub_f32_e32 v3, v76, v12
	v_pk_add_f32 v[64:65], v[0:1], v[0:1] op_sel:[0,1] op_sel_hi:[1,0]
	v_mul_f32_e32 v0, v119, v119
	v_pk_fma_f32 v[58:59], v[118:119], v[118:119], v[0:1] op_sel_hi:[1,1,0]
	v_sub_f32_e32 v0, v50, v12
	v_mul_f32_e32 v0, v13, v0
	v_sub_f32_e32 v1, v56, v12
	v_mul_f32_e32 v1, v13, v1
	v_mul_f32_e32 v2, v13, v2
	v_sub_f32_e32 v22, v77, v12
	v_mul_f32_e32 v3, v13, v3
	v_sub_f32_e32 v23, v78, v12
	v_mul_f32_e32 v22, v13, v22
	v_sub_f32_e32 v24, v79, v12
	v_mul_f32_e32 v23, v13, v23
	v_sub_f32_e32 v12, v80, v12
	v_mul_f32_e32 v24, v13, v24
	v_mul_f32_e32 v12, v13, v12
	s_waitcnt vmcnt(2)
	v_fma_f32 v0, v0, v4, v8
	v_cvt_pk_bf16_f32 v0, v0, v33
	v_fma_f32 v1, v1, v5, v9
	ds_write_b16 v155, v0 offset:26112
	v_cvt_pk_bf16_f32 v0, v1, v33
	v_fma_f32 v2, v2, v6, v10
	ds_write_b16 v155, v0 offset:26384
	v_cvt_pk_bf16_f32 v0, v2, v33
	v_fmac_f32_e32 v11, v3, v7
	ds_write_b16 v155, v0 offset:26656
	v_cvt_pk_bf16_f32 v0, v11, v33
	s_waitcnt vmcnt(0)
	v_fma_f32 v3, v22, v14, v18
	ds_write_b16 v155, v0 offset:26928
	v_cvt_pk_bf16_f32 v0, v3, v33
	v_fma_f32 v4, v23, v15, v19
	ds_write_b16 v155, v0 offset:27200
	v_cvt_pk_bf16_f32 v0, v4, v33
	v_fma_f32 v5, v24, v16, v20
	ds_write_b16 v155, v0 offset:27472
	v_cvt_pk_bf16_f32 v0, v5, v33
	v_fmac_f32_e32 v21, v12, v17
	ds_write_b16 v155, v0 offset:27744
	v_cvt_pk_bf16_f32 v0, v21, v33
	ds_write_b16 v155, v0 offset:28016
	s_waitcnt lgkmcnt(0)
	s_barrier
	v_add_co_u32_e32 v0, vcc, s27, v42
	v_pk_fma_f32 v[68:69], v[62:63], v[68:69], v[72:73]
	s_nop 0
	v_addc_co_u32_e32 v1, vcc, 0, v43, vcc
	global_load_dwordx2 v[224:225], v[40:41], off offset:1568
	global_load_dwordx2 v[226:227], v[40:41], off offset:1600
	global_load_dwordx2 v[228:229], v[40:41], off offset:1632
	global_load_dwordx2 v[230:231], v[40:41], off offset:1664
	global_load_dwordx2 v[232:233], v[40:41], off offset:1696
	global_load_dwordx2 v[234:235], v[40:41], off offset:1728
	global_load_dwordx2 v[236:237], v[40:41], off offset:1760
	global_load_dwordx4 v[20:23], v[0:1], off
	global_load_dwordx4 v[24:27], v[0:1], off offset:64
	global_load_dwordx2 v[84:85], v[40:41], off offset:1536
	global_load_dwordx4 v[28:31], v[0:1], off offset:128
	global_load_dwordx4 v[16:19], v[0:1], off offset:192
	global_load_dword v48, v[44:45], off offset:1024
	ds_read_b128 v[0:3], v152
	ds_read_b128 v[4:7], v152 offset:64
	ds_read_b128 v[54:57], v152 offset:128
	global_load_dwordx4 v[12:15], v[46:47], off offset:2816
	global_load_dwordx4 v[8:11], v[46:47], off offset:2880
	ds_read_b128 v[76:79], v152 offset:192
	v_pk_mul_f32 v[62:63], v[72:73], v[72:73]
	v_pk_fma_f32 v[70:71], v[60:61], v[70:71], v[74:75]
	v_pk_mul_f32 v[60:61], v[74:75], v[74:75]
	v_mov_b32_e32 v69, v63
	v_mov_b32_e32 v71, v61
	s_waitcnt vmcnt(7) lgkmcnt(3)
	v_mfma_f32_16x16x32_bf16 v[0:3], v[0:3], v[20:23], 0
	s_waitcnt vmcnt(6) lgkmcnt(2)
	v_mfma_f32_16x16x32_bf16 v[80:83], v[4:7], v[24:27], v[0:3]
	global_load_dwordx4 v[4:7], v[46:47], off offset:2944
	s_nop 4
	global_load_dwordx4 v[0:3], v[46:47], off offset:3008
	s_waitcnt vmcnt(7)
	v_lshlrev_b32_e32 v47, 16, v85
	v_lshlrev_b32_e32 v46, 16, v84
	s_waitcnt vmcnt(6) lgkmcnt(1)
	v_mfma_f32_16x16x32_bf16 v[54:57], v[54:57], v[28:31], v[80:83]
	s_waitcnt vmcnt(0)
	v_and_b32_e32 v72, 0xffff0000, v2
	s_waitcnt lgkmcnt(0)
	v_mfma_f32_16x16x32_bf16 v[54:57], v[76:79], v[16:19], v[54:57]
	v_and_b32_e32 v81, 0xffff0000, v85
	v_and_b32_e32 v80, 0xffff0000, v84
	v_lshlrev_b32_e32 v73, 16, v3
	v_and_b32_e32 v74, 0xffff0000, v3
	s_nop 3
	v_mov_b32_e32 v76, v54
	v_mov_b32_e32 v77, v56
	v_mov_b32_e32 v56, v55
	v_pk_add_f32 v[54:55], v[48:49], v[76:77] op_sel_hi:[0,1]
	v_pk_add_f32 v[56:57], v[48:49], v[56:57] op_sel_hi:[0,1]
	v_pk_mul_f32 v[76:77], v[54:55], v[46:47]
	v_pk_mul_f32 v[78:79], v[56:57], v[80:81]
	s_nop 0
	v_cvt_pk_bf16_f32 v159, v76, v78
	v_cvt_pk_bf16_f32 v158, v77, v79
	ds_read_b128 v[54:57], v152 offset:4352
	ds_read_b128 v[80:83], v152 offset:4416
	s_waitcnt lgkmcnt(1)
	v_mfma_f32_16x16x32_bf16 v[54:57], v[54:57], v[20:23], 0
	s_waitcnt lgkmcnt(0)
	v_mfma_f32_16x16x32_bf16 v[54:57], v[80:83], v[24:27], v[54:57]
	ds_read_b128 v[80:83], v152 offset:4480
	ds_read_b128 v[84:87], v152 offset:4544
	v_mov_b64_e32 v[46:47], v[224:225]
	s_waitcnt lgkmcnt(1)
	v_mfma_f32_16x16x32_bf16 v[54:57], v[80:83], v[28:31], v[54:57]
	s_waitcnt vmcnt(0)
	v_lshlrev_b32_e32 v80, 16, v46
	s_waitcnt lgkmcnt(0)
	v_mfma_f32_16x16x32_bf16 v[54:57], v[84:87], v[16:19], v[54:57]
	v_and_b32_e32 v81, 0xffff0000, v46
	v_lshlrev_b32_e32 v46, 16, v47
	v_and_b32_e32 v47, 0xffff0000, v47
	s_nop 4
	v_pk_add_f32 v[54:55], v[48:49], v[54:55] op_sel_hi:[0,1]
	v_pk_add_f32 v[56:57], v[48:49], v[56:57] op_sel_hi:[0,1]
	v_pk_mul_f32 v[80:81], v[54:55], v[80:81]
	v_pk_mul_f32 v[82:83], v[56:57], v[46:47]
	v_cvt_pk_bf16_f32 v123, v80, v81
	s_nop 0
	v_cvt_pk_bf16_f32 v121, v82, v83
	ds_read_b128 v[54:57], v152 offset:8704
	ds_read_b128 v[84:87], v152 offset:8768
	s_waitcnt lgkmcnt(1)
	v_mfma_f32_16x16x32_bf16 v[54:57], v[54:57], v[20:23], 0
	s_waitcnt lgkmcnt(0)
	v_mfma_f32_16x16x32_bf16 v[54:57], v[84:87], v[24:27], v[54:57]
	ds_read_b128 v[84:87], v152 offset:8832
	ds_read_b128 v[88:91], v152 offset:8896
	v_mov_b64_e32 v[46:47], v[226:227]
	s_waitcnt lgkmcnt(1)
	v_mfma_f32_16x16x32_bf16 v[54:57], v[84:87], v[28:31], v[54:57]
	s_waitcnt vmcnt(0)
	v_lshlrev_b32_e32 v84, 16, v47
	s_waitcnt lgkmcnt(0)
	v_mfma_f32_16x16x32_bf16 v[54:57], v[88:91], v[16:19], v[54:57]
	v_and_b32_e32 v47, 0xffff0000, v47
	s_nop 6
	v_add_f32_e32 v50, v48, v54
	v_add_f32_e32 v55, v48, v55
	v_add_f32_e32 v56, v48, v56
	v_add_f32_e32 v57, v48, v57
	v_lshlrev_b32_e32 v54, 16, v46
	v_and_b32_e32 v46, 0xffff0000, v46
	v_mul_f32_e32 v54, v50, v54
	v_mul_f32_e32 v86, v55, v46
	v_mul_f32_e32 v56, v56, v84
	v_mul_f32_e32 v84, v57, v47
	v_cvt_pk_bf16_f32 v119, v54, v86
	v_cvt_pk_bf16_f32 v118, v56, v84
	ds_read_b128 v[88:91], v152 offset:13056
	ds_read_b128 v[92:95], v152 offset:13120
	s_waitcnt lgkmcnt(1)
	v_mfma_f32_16x16x32_bf16 v[88:91], v[88:91], v[20:23], 0
	s_waitcnt lgkmcnt(0)
	v_mfma_f32_16x16x32_bf16 v[88:91], v[92:95], v[24:27], v[88:91]
	ds_read_b128 v[92:95], v152 offset:13184
	ds_read_b128 v[96:99], v152 offset:13248
	v_mov_b64_e32 v[46:47], v[228:229]
	s_waitcnt vmcnt(0)
	v_lshlrev_b32_e32 v87, 16, v46
	s_waitcnt lgkmcnt(1)
	v_mfma_f32_16x16x32_bf16 v[92:95], v[92:95], v[28:31], v[88:91]
	v_and_b32_e32 v46, 0xffff0000, v46
	s_waitcnt lgkmcnt(0)
	v_mfma_f32_16x16x32_bf16 v[92:95], v[96:99], v[16:19], v[92:95]
	v_mov_b32_e32 v88, v54
	v_mov_b32_e32 v90, v56
	v_lshlrev_b32_e32 v89, 16, v47
	v_and_b32_e32 v91, 0xffff0000, v47
	s_nop 3
	v_add_f32_e32 v50, v48, v92
	v_add_f32_e32 v85, v48, v93
	v_add_f32_e32 v55, v48, v94
	v_add_f32_e32 v57, v48, v95
	v_mul_f32_e32 v95, v50, v87
	v_mul_f32_e32 v93, v85, v46
	v_pk_mul_f32 v[96:97], v[54:55], v[88:89]
	v_pk_mul_f32 v[98:99], v[56:57], v[90:91]
	v_cvt_pk_bf16_f32 v117, v95, v93
	v_mov_b32_e32 v3, v95
	v_cvt_pk_bf16_f32 v115, v97, v99
	ds_read_b128 v[100:103], v152 offset:17408
	ds_read_b128 v[104:107], v152 offset:17472
	s_waitcnt lgkmcnt(1)
	v_mfma_f32_16x16x32_bf16 v[100:103], v[100:103], v[20:23], 0
	s_waitcnt lgkmcnt(0)
	v_mfma_f32_16x16x32_bf16 v[100:103], v[104:107], v[24:27], v[100:103]
	ds_read_b128 v[104:107], v152 offset:17536
	ds_read_b128 v[108:111], v152 offset:17600
	v_mov_b64_e32 v[46:47], v[230:231]
	s_waitcnt lgkmcnt(1)
	v_mfma_f32_16x16x32_bf16 v[100:103], v[104:107], v[28:31], v[100:103]
	s_waitcnt lgkmcnt(0)
	v_mfma_f32_16x16x32_bf16 v[100:103], v[108:111], v[16:19], v[100:103]
	s_nop 7
	v_mov_b32_e32 v104, v100
	v_mov_b32_e32 v105, v102
	v_mov_b32_e32 v102, v101
	v_pk_add_f32 v[100:101], v[48:49], v[104:105] op_sel_hi:[0,1]
	v_pk_add_f32 v[102:103], v[48:49], v[102:103] op_sel_hi:[0,1]
	s_waitcnt vmcnt(0)
	v_lshlrev_b32_e32 v105, 16, v47
	v_lshlrev_b32_e32 v104, 16, v46
	v_and_b32_e32 v47, 0xffff0000, v47
	v_and_b32_e32 v46, 0xffff0000, v46
	v_pk_mul_f32 v[100:101], v[100:101], v[104:105]
	v_pk_mul_f32 v[102:103], v[102:103], v[46:47]
	s_nop 0
	v_cvt_pk_bf16_f32 v116, v100, v102
	v_cvt_pk_bf16_f32 v114, v101, v103
	ds_read_b128 v[104:107], v152 offset:21760
	ds_read_b128 v[108:111], v152 offset:21824
	s_waitcnt lgkmcnt(1)
	v_mfma_f32_16x16x32_bf16 v[104:107], v[104:107], v[20:23], 0
	s_waitcnt lgkmcnt(0)
	v_mfma_f32_16x16x32_bf16 v[104:107], v[108:111], v[24:27], v[104:107]
	ds_read_b128 v[108:111], v152 offset:21888
	ds_read_b128 v[162:165], v152 offset:21952
	v_mov_b64_e32 v[46:47], v[232:233]
	s_waitcnt lgkmcnt(1)
	v_mfma_f32_16x16x32_bf16 v[104:107], v[108:111], v[28:31], v[104:107]
	s_waitcnt vmcnt(0)
	v_lshlrev_b32_e32 v108, 16, v46
	s_waitcnt lgkmcnt(0)
	v_mfma_f32_16x16x32_bf16 v[104:107], v[162:165], v[16:19], v[104:107]
	v_and_b32_e32 v109, 0xffff0000, v46
	v_lshlrev_b32_e32 v110, 16, v47
	v_and_b32_e32 v111, 0xffff0000, v47
	s_nop 4
	v_pk_add_f32 v[104:105], v[48:49], v[104:105] op_sel_hi:[0,1]
	v_pk_add_f32 v[106:107], v[48:49], v[106:107] op_sel_hi:[0,1]
	v_pk_mul_f32 v[46:47], v[104:105], v[108:109]
	v_pk_mul_f32 v[104:105], v[106:107], v[110:111]
	v_cvt_pk_bf16_f32 v113, v46, v47
	s_nop 0
	v_cvt_pk_bf16_f32 v112, v104, v105
	ds_read_b128 v[106:109], v152 offset:26112
	ds_read_b128 v[162:165], v152 offset:26176
	s_waitcnt lgkmcnt(1)
	v_mfma_f32_16x16x32_bf16 v[106:109], v[106:109], v[20:23], 0
	s_waitcnt lgkmcnt(0)
	v_mfma_f32_16x16x32_bf16 v[106:109], v[162:165], v[24:27], v[106:109]
	ds_read_b128 v[162:165], v152 offset:26240
	ds_read_b128 v[166:169], v152 offset:26304
	v_mov_b64_e32 v[110:111], v[234:235]
	s_waitcnt vmcnt(0)
	v_lshlrev_b32_e32 v56, 16, v110
	s_waitcnt lgkmcnt(1)
	v_mfma_f32_16x16x32_bf16 v[106:109], v[162:165], v[28:31], v[106:109]
	v_and_b32_e32 v88, 0xffff0000, v110
	v_lshlrev_b32_e32 v90, 16, v111
	v_and_b32_e32 v92, 0xffff0000, v111
	s_waitcnt lgkmcnt(0)
	v_mfma_f32_16x16x32_bf16 v[106:109], v[166:169], v[16:19], v[106:109]
	s_nop 7
	v_add_f32_e32 v50, v48, v106
	v_add_f32_e32 v54, v48, v107
	v_add_f32_e32 v85, v48, v108
	v_add_f32_e32 v87, v48, v109
	v_mul_f32_e32 v106, v50, v56
	v_mul_f32_e32 v56, v54, v88
	v_mul_f32_e32 v108, v85, v90
	v_mul_f32_e32 v54, v87, v92
	v_cvt_pk_bf16_f32 v111, v106, v56
	v_cvt_pk_bf16_f32 v110, v108, v54
	ds_read_b128 v[162:165], v152 offset:30464
	ds_read_b128 v[166:169], v152 offset:30528
	s_waitcnt lgkmcnt(1)
	v_mfma_f32_16x16x32_bf16 v[20:23], v[162:165], v[20:23], 0
	v_mov_b32_e32 v87, v55
	v_mov_b32_e32 v85, v57
	v_mov_b32_e32 v88, v86
	s_waitcnt lgkmcnt(0)
	v_mfma_f32_16x16x32_bf16 v[20:23], v[166:169], v[24:27], v[20:23]
	ds_read_b128 v[24:27], v152 offset:30592
	ds_read_b128 v[162:165], v152 offset:30656
	v_mov_b32_e32 v90, v84
	s_waitcnt lgkmcnt(1)
	v_mfma_f32_16x16x32_bf16 v[24:27], v[24:27], v[28:31], v[20:23]
	v_mov_b64_e32 v[28:29], v[236:237]
	v_lshlrev_b32_e32 v30, 16, v15
	s_nop 0
	v_mov_b32_e32 v20, v106
	s_waitcnt lgkmcnt(0)
	v_mfma_f32_16x16x32_bf16 v[16:19], v[162:165], v[16:19], v[24:27]
	v_mov_b32_e32 v22, v108
	v_and_b32_e32 v15, 0xffff0000, v15
	v_mov_b32_e32 v31, v51
	s_waitcnt vmcnt(0)
	v_and_b32_e32 v24, 0xffff0000, v28
	s_nop 2
	v_add_f32_e32 v16, v48, v16
	v_add_f32_e32 v17, v48, v17
	v_add_f32_e32 v107, v48, v18
	v_add_f32_e32 v109, v48, v19
	v_lshlrev_b32_e32 v18, 16, v28
	v_lshlrev_b32_e32 v21, 16, v29
	v_and_b32_e32 v23, 0xffff0000, v29
	v_mul_f32_e32 v19, v16, v18
	v_mul_f32_e32 v17, v17, v24
	v_pk_mul_f32 v[26:27], v[106:107], v[20:21]
	v_pk_mul_f32 v[24:25], v[108:109], v[22:23]
	v_cvt_pk_bf16_f32 v106, v19, v17
	v_lshlrev_b32_e32 v16, 16, v12
	v_cvt_pk_bf16_f32 v29, v27, v25
	global_load_dwordx4 v[162:165], v157, s[48:49] offset:1536
	global_load_dwordx4 v[166:169], v157, s[50:51] offset:1536
	global_load_dwordx4 v[170:173], v157, s[48:49] offset:1552
	global_load_dwordx4 v[174:177], v157, s[50:51] offset:1552
	global_load_dwordx4 v[178:181], v157, s[48:49] offset:1664
	global_load_dwordx4 v[182:185], v157, s[50:51] offset:1664
	global_load_dwordx4 v[186:189], v157, s[48:49] offset:1680
	global_load_dwordx4 v[190:193], v157, s[50:51] offset:1680
	global_load_dwordx4 v[194:197], v157, s[48:49] offset:1792
	global_load_dwordx4 v[198:201], v157, s[50:51] offset:1792
	global_load_dwordx4 v[202:205], v157, s[48:49] offset:1808
	global_load_dwordx4 v[206:209], v157, s[50:51] offset:1808
	global_load_dwordx4 v[210:213], v157, s[48:49] offset:1920
	global_load_dwordx4 v[214:217], v157, s[50:51] offset:1920
	global_load_dwordx4 v[218:221], v157, s[48:49] offset:1936
	global_load_dwordx4 v[238:241], v157, s[50:51] offset:1936
	v_and_b32_e32 v18, 0xffff0000, v12
	v_lshlrev_b32_e32 v20, 16, v13
	v_and_b32_e32 v22, 0xffff0000, v13
	ds_read_b64 v[12:13], v160
	v_lshlrev_b32_e32 v28, 16, v14
	v_and_b32_e32 v14, 0xffff0000, v14
	v_mov_b32_e32 v57, v107
	v_mov_b32_e32 v55, v109
	s_waitcnt lgkmcnt(0)
	v_sub_f32_e32 v16, v16, v12
	v_sub_f32_e32 v15, v15, v12
	v_sub_f32_e32 v18, v18, v12
	v_mul_f32_e32 v16, v13, v16
	v_mul_f32_e32 v15, v13, v15
	v_sub_f32_e32 v20, v20, v12
	v_mul_f32_e32 v18, v13, v18
	v_sub_f32_e32 v22, v22, v12
	v_sub_f32_e32 v14, v14, v12
	v_mul_f32_e32 v20, v13, v20
	v_sub_f32_e32 v28, v28, v12
	v_mul_f32_e32 v22, v13, v22
	v_mul_f32_e32 v14, v13, v14
	v_sub_f32_e32 v30, v30, v12
	v_mul_f32_e32 v28, v13, v28
	v_mul_f32_e32 v30, v13, v30
	s_waitcnt vmcnt(2)
	v_fma_f32 v16, v162, v16, v166
	v_fma_f32 v18, v163, v18, v167
	s_waitcnt vmcnt(0)
	v_fmac_f32_e32 v177, v173, v15
	v_cvt_pk_bf16_f32 v15, v16, v33
	ds_write_b16 v155, v15 offset:34816
	v_cvt_pk_bf16_f32 v15, v18, v33
	v_fma_f32 v20, v164, v20, v168
	ds_write_b16 v155, v15 offset:35088
	v_cvt_pk_bf16_f32 v15, v20, v33
	v_fmac_f32_e32 v169, v165, v22
	v_fma_f32 v14, v171, v14, v175
	ds_write_b16 v155, v15 offset:35360
	v_cvt_pk_bf16_f32 v15, v169, v33
	v_fma_f32 v22, v170, v28, v174
	ds_write_b16 v155, v15 offset:35632
	v_cvt_pk_bf16_f32 v15, v22, v33
	ds_write_b16 v155, v15 offset:35904
	v_cvt_pk_bf16_f32 v14, v14, v33
	v_fma_f32 v28, v172, v30, v176
	ds_write_b16 v155, v14 offset:36176
	v_cvt_pk_bf16_f32 v14, v28, v33
	ds_write_b16 v155, v14 offset:36448
	v_cvt_pk_bf16_f32 v14, v177, v33
	v_mov_b64_e32 v[160:161], v[178:179]
	v_mov_b64_e32 v[162:163], v[180:181]
	v_mov_b64_e32 v[164:165], v[182:183]
	v_mov_b64_e32 v[166:167], v[184:185]
	v_mov_b64_e32 v[168:169], v[186:187]
	v_mov_b64_e32 v[170:171], v[188:189]
	v_mov_b64_e32 v[172:173], v[190:191]
	v_mov_b64_e32 v[174:175], v[192:193]
	v_lshlrev_b32_e32 v15, 16, v8
	v_and_b32_e32 v8, 0xffff0000, v8
	v_lshlrev_b32_e32 v20, 16, v11
	v_and_b32_e32 v11, 0xffff0000, v11
	v_sub_f32_e32 v8, v8, v12
	v_lshlrev_b32_e32 v16, 16, v9
	v_sub_f32_e32 v15, v15, v12
	v_sub_f32_e32 v11, v11, v12
	v_mul_f32_e32 v8, v13, v8
	v_and_b32_e32 v9, 0xffff0000, v9
	v_sub_f32_e32 v16, v16, v12
	v_mul_f32_e32 v15, v13, v15
	v_mul_f32_e32 v11, v13, v11
	v_lshlrev_b32_e32 v18, 16, v10
	v_sub_f32_e32 v9, v9, v12
	v_mul_f32_e32 v16, v13, v16
	ds_write_b16 v155, v14 offset:36720
	v_and_b32_e32 v10, 0xffff0000, v10
	v_sub_f32_e32 v18, v18, v12
	v_mul_f32_e32 v9, v13, v9
	v_sub_f32_e32 v10, v10, v12
	v_mul_f32_e32 v18, v13, v18
	v_sub_f32_e32 v20, v20, v12
	v_mul_f32_e32 v10, v13, v10
	v_mul_f32_e32 v20, v13, v20
	v_lshlrev_b32_e32 v22, 16, v7
	v_and_b32_e32 v7, 0xffff0000, v7
	v_sub_f32_e32 v7, v7, v12
	v_mul_f32_e32 v7, v13, v7
	v_sub_f32_e32 v22, v22, v12
	v_mul_f32_e32 v22, v13, v22
	v_mov_b32_e32 v30, v64
	v_lshlrev_b32_e32 v28, 16, v0
	s_waitcnt vmcnt(2)
	v_fma_f32 v8, v8, v161, v165
	v_fma_f32 v14, v15, v160, v164
	s_waitcnt vmcnt(0)
	v_fmac_f32_e32 v175, v11, v171
	v_cvt_pk_bf16_f32 v11, v14, v33
	ds_write_b16 v155, v11 offset:43520
	v_cvt_pk_bf16_f32 v8, v8, v33
	v_fma_f32 v15, v16, v162, v166
	ds_write_b16 v155, v8 offset:43792
	v_cvt_pk_bf16_f32 v8, v15, v33
	v_fmac_f32_e32 v167, v9, v163
	ds_write_b16 v155, v8 offset:44064
	v_cvt_pk_bf16_f32 v8, v167, v33
	v_fma_f32 v9, v18, v168, v172
	ds_write_b16 v155, v8 offset:44336
	v_cvt_pk_bf16_f32 v8, v9, v33
	v_fma_f32 v10, v10, v169, v173
	ds_write_b16 v155, v8 offset:44608
	v_cvt_pk_bf16_f32 v8, v10, v33
	v_fma_f32 v16, v20, v170, v174
	ds_write_b16 v155, v8 offset:44880
	v_cvt_pk_bf16_f32 v8, v16, v33
	ds_write_b16 v155, v8 offset:45152
	v_cvt_pk_bf16_f32 v18, v175, v33
	v_mov_b64_e32 v[8:9], v[194:195]
	v_mov_b64_e32 v[10:11], v[196:197]
	v_mov_b64_e32 v[160:161], v[198:199]
	v_mov_b64_e32 v[162:163], v[200:201]
	v_mov_b64_e32 v[164:165], v[202:203]
	v_mov_b64_e32 v[166:167], v[204:205]
	v_mov_b64_e32 v[168:169], v[206:207]
	v_mov_b64_e32 v[170:171], v[208:209]
	v_pk_add_f32 v[14:15], v[66:67], v[66:67] op_sel:[0,1] op_sel_hi:[1,0]
	v_mul_f32_e32 v16, v53, v53
	v_mov_b32_e32 v50, v14
	v_pk_add_f32 v[14:15], v[14:15], v[64:65]
	v_pk_fma_f32 v[52:53], v[52:53], v[52:53], v[16:17] op_sel_hi:[1,1,0]
	v_lshlrev_b32_e32 v15, 16, v4
	v_and_b32_e32 v4, 0xffff0000, v4
	v_sub_f32_e32 v4, v4, v12
	v_lshlrev_b32_e32 v16, 16, v5
	v_sub_f32_e32 v15, v15, v12
	v_mul_f32_e32 v4, v13, v4
	v_and_b32_e32 v5, 0xffff0000, v5
	v_sub_f32_e32 v16, v16, v12
	v_mul_f32_e32 v15, v13, v15
	v_lshlrev_b32_e32 v20, 16, v6
	v_sub_f32_e32 v5, v5, v12
	v_mul_f32_e32 v16, v13, v16
	ds_write_b16 v155, v18 offset:45424
	v_and_b32_e32 v6, 0xffff0000, v6
	v_sub_f32_e32 v20, v20, v12
	v_mul_f32_e32 v5, v13, v5
	v_sub_f32_e32 v6, v6, v12
	v_mul_f32_e32 v20, v13, v20
	v_mul_f32_e32 v6, v13, v6
	v_mov_b32_e32 v172, v58
	v_mov_b32_e32 v173, v49
	v_pk_mul_f32 v[30:31], v[50:51], v[30:31]
	v_mov_b32_e32 v48, v52
	v_pk_add_f32 v[50:51], v[52:53], v[58:59]
	v_pk_add_f32 v[52:53], v[68:69], v[70:71]
	v_and_b32_e32 v68, 0xffff0000, v0
	v_lshlrev_b32_e32 v69, 16, v1
	v_and_b32_e32 v70, 0xffff0000, v1
	v_pk_mul_f32 v[0:1], v[78:79], v[78:79]
	v_lshlrev_b32_e32 v71, 16, v2
	v_pk_fma_f32 v[0:1], v[76:77], v[76:77], v[0:1]
	v_pk_mul_f32 v[58:59], v[98:99], v[98:99]
	v_pk_add_f32 v[0:1], v[0:1], v[0:1] op_sel:[0,1] op_sel_hi:[1,0]
	s_waitcnt vmcnt(2)
	v_fma_f32 v4, v4, v9, v161
	v_fma_f32 v8, v15, v8, v160
	s_waitcnt vmcnt(0)
	v_fmac_f32_e32 v171, v7, v167
	v_cvt_pk_bf16_f32 v7, v8, v33
	ds_write_b16 v155, v7 offset:52224
	v_cvt_pk_bf16_f32 v4, v4, v33
	v_fma_f32 v9, v16, v10, v162
	ds_write_b16 v155, v4 offset:52496
	v_cvt_pk_bf16_f32 v4, v9, v33
	v_fmac_f32_e32 v163, v5, v11
	ds_write_b16 v155, v4 offset:52768
	v_cvt_pk_bf16_f32 v4, v163, v33
	v_fma_f32 v5, v20, v164, v168
	ds_write_b16 v155, v4 offset:53040
	v_cvt_pk_bf16_f32 v4, v5, v33
	v_fma_f32 v6, v6, v165, v169
	ds_write_b16 v155, v4 offset:53312
	v_cvt_pk_bf16_f32 v4, v6, v33
	v_fma_f32 v10, v22, v166, v170
	ds_write_b16 v155, v4 offset:53584
	v_cvt_pk_bf16_f32 v4, v10, v33
	ds_write_b16 v155, v4 offset:53856
	v_cvt_pk_bf16_f32 v18, v171, v33
	v_mov_b64_e32 v[4:5], v[210:211]
	v_mov_b64_e32 v[6:7], v[212:213]
	v_mov_b64_e32 v[8:9], v[214:215]
	v_mov_b64_e32 v[10:11], v[216:217]
	v_mov_b64_e32 v[60:61], v[218:219]
	v_mov_b64_e32 v[62:63], v[220:221]
	v_mov_b64_e32 v[64:65], v[238:239]
	v_mov_b64_e32 v[66:67], v[240:241]
	v_mov_b32_e32 v15, v31
	v_pk_mul_f32 v[30:31], v[48:49], v[172:173]
	v_mov_b32_e32 v2, v0
	v_mov_b32_e32 v51, v31
	v_pk_add_f32 v[14:15], v[14:15], v[50:51]
	v_mul_f32_e32 v16, v81, v81
	v_pk_add_f32 v[14:15], v[14:15], v[52:53]
	v_pk_fma_f32 v[30:31], v[80:81], v[80:81], v[16:17] op_sel_hi:[1,1,0]
	v_pk_add_f32 v[14:15], v[14:15], v[14:15] op_sel:[0,1] op_sel_hi:[1,0]
	v_mov_b32_e32 v92, v30
	v_mov_b32_e32 v94, v14
	v_pk_add_f32 v[0:1], v[14:15], v[0:1]
	v_mul_f32_e32 v14, v83, v83
	v_pk_fma_f32 v[14:15], v[82:83], v[82:83], v[14:15] op_sel_hi:[1,1,0]
	v_mov_b32_e32 v49, v93
	v_mov_b32_e32 v48, v14
	v_pk_add_f32 v[14:15], v[30:31], v[14:15]
	v_pk_fma_f32 v[30:31], v[86:87], v[88:89], v[96:97]
	v_pk_mul_f32 v[50:51], v[96:97], v[96:97]
	v_pk_fma_f32 v[52:53], v[84:85], v[90:91], v[98:99]
	v_pk_mul_f32 v[2:3], v[94:95], v[2:3]
	v_pk_mul_f32 v[48:49], v[92:93], v[48:49]
	v_mov_b32_e32 v31, v51
	v_mov_b32_e32 v53, v59
	v_mov_b32_e32 v1, v3
	v_mov_b32_e32 v15, v49
	v_pk_add_f32 v[2:3], v[30:31], v[52:53]
	v_pk_add_f32 v[0:1], v[0:1], v[14:15]
	ds_write_b16 v155, v18 offset:54128
	v_pk_add_f32 v[50:51], v[0:1], v[2:3]
	v_pk_mul_f32 v[0:1], v[102:103], v[102:103]
	v_sub_f32_e32 v2, v69, v12
	v_pk_fma_f32 v[0:1], v[100:101], v[100:101], v[0:1]
	v_sub_f32_e32 v3, v70, v12
	v_pk_add_f32 v[48:49], v[0:1], v[0:1] op_sel:[0,1] op_sel_hi:[1,0]
	v_mul_f32_e32 v0, v105, v105
	v_pk_fma_f32 v[30:31], v[104:105], v[104:105], v[0:1] op_sel_hi:[1,1,0]
	v_sub_f32_e32 v0, v28, v12
	v_mul_f32_e32 v0, v13, v0
	v_sub_f32_e32 v1, v68, v12
	v_mul_f32_e32 v1, v13, v1
	v_mul_f32_e32 v2, v13, v2
	v_sub_f32_e32 v14, v71, v12
	v_mul_f32_e32 v3, v13, v3
	v_sub_f32_e32 v15, v72, v12
	v_mul_f32_e32 v14, v13, v14
	v_sub_f32_e32 v16, v73, v12
	v_mul_f32_e32 v15, v13, v15
	v_sub_f32_e32 v12, v74, v12
	v_mul_f32_e32 v16, v13, v16
	v_mul_f32_e32 v12, v13, v12
	v_mov_b32_e32 v20, v56
	v_mov_b32_e32 v22, v54
	s_waitcnt vmcnt(2)
	v_fma_f32 v0, v0, v4, v8
	v_cvt_pk_bf16_f32 v0, v0, v33
	v_fma_f32 v1, v1, v5, v9
	ds_write_b16 v155, v0 offset:60928
	v_cvt_pk_bf16_f32 v0, v1, v33
	v_fma_f32 v2, v2, v6, v10
	ds_write_b16 v155, v0 offset:61200
	v_cvt_pk_bf16_f32 v0, v2, v33
	v_fmac_f32_e32 v11, v3, v7
	ds_write_b16 v155, v0 offset:61472
	v_cvt_pk_bf16_f32 v0, v11, v33
	s_waitcnt vmcnt(0)
	v_fma_f32 v3, v14, v60, v64
	ds_write_b16 v155, v0 offset:61744
	v_cvt_pk_bf16_f32 v0, v3, v33
	v_fma_f32 v4, v15, v61, v65
	ds_write_b16 v155, v0 offset:62016
	v_cvt_pk_bf16_f32 v0, v4, v33
	v_fma_f32 v5, v16, v62, v66
	ds_write_b16 v155, v0 offset:62288
	v_cvt_pk_bf16_f32 v0, v5, v33
	v_fmac_f32_e32 v67, v12, v63
	ds_write_b16 v155, v0 offset:62560
	v_cvt_pk_bf16_f32 v0, v67, v33
	ds_write_b16 v155, v0 offset:62832
	s_waitcnt lgkmcnt(0)
	s_barrier
	v_add_co_u32_e32 v4, vcc, s28, v42
	v_pk_fma_f32 v[56:57], v[56:57], v[20:21], v[26:27]
	s_nop 0
	v_addc_co_u32_e32 v5, vcc, 0, v43, vcc
	global_load_dwordx2 v[224:225], v[40:41], off offset:1824
	global_load_dwordx2 v[226:227], v[40:41], off offset:1856
	global_load_dwordx2 v[228:229], v[40:41], off offset:1888
	global_load_dwordx2 v[230:231], v[40:41], off offset:1920
	global_load_dwordx2 v[232:233], v[40:41], off offset:1952
	global_load_dwordx2 v[234:235], v[40:41], off offset:1984
	global_load_dwordx2 v[236:237], v[40:41], off offset:2016
	global_load_dwordx4 v[8:11], v[4:5], off
	global_load_dwordx4 v[0:3], v[4:5], off offset:64
	global_load_dwordx2 v[52:53], v[40:41], off offset:1792
	global_load_dwordx4 v[12:15], v[4:5], off offset:128
	s_nop 0
	global_load_dwordx4 v[4:7], v[4:5], off offset:192
	s_nop 0
	global_load_dword v28, v[44:45], off offset:1536
	ds_read_b128 v[42:45], v152 offset:34816
	ds_read_b128 v[58:61], v152 offset:34880
	ds_read_b128 v[62:65], v152 offset:34944
	v_pk_fma_f32 v[54:55], v[54:55], v[22:23], v[24:25]
	v_pk_mul_f32 v[24:25], v[24:25], v[24:25]
	v_pk_mul_f32 v[26:27], v[26:27], v[26:27]
	v_pk_add_f32 v[50:51], v[50:51], v[50:51] op_sel:[0,1] op_sel_hi:[1,0]
	v_mov_b32_e32 v168, v48
	v_mov_b32_e32 v169, v19
	v_mov_b32_e32 v170, v30
	v_mov_b32_e32 v171, v17
	s_waitcnt vmcnt(5) lgkmcnt(2)
	v_mfma_f32_16x16x32_bf16 v[42:45], v[42:45], v[8:11], 0
	s_waitcnt vmcnt(3)
	v_lshlrev_b32_e32 v67, 16, v53
	v_lshlrev_b32_e32 v66, 16, v52
	s_waitcnt lgkmcnt(1)
	v_mfma_f32_16x16x32_bf16 v[42:45], v[58:61], v[0:3], v[42:45]
	ds_read_b128 v[58:61], v152 offset:35008
	v_and_b32_e32 v53, 0xffff0000, v53
	v_and_b32_e32 v52, 0xffff0000, v52
	s_waitcnt vmcnt(2) lgkmcnt(1)
	v_mfma_f32_16x16x32_bf16 v[42:45], v[62:65], v[12:15], v[42:45]
	s_waitcnt vmcnt(1) lgkmcnt(0)
	v_mfma_f32_16x16x32_bf16 v[42:45], v[58:61], v[4:7], v[42:45]
	s_nop 7
	v_mov_b32_e32 v58, v42
	v_mov_b32_e32 v59, v44
	v_mov_b32_e32 v44, v43
	s_waitcnt vmcnt(0)
	v_pk_add_f32 v[42:43], v[28:29], v[58:59] op_sel_hi:[0,1]
	v_pk_add_f32 v[44:45], v[28:29], v[44:45] op_sel_hi:[0,1]
	v_pk_mul_f32 v[42:43], v[42:43], v[66:67]
	v_pk_mul_f32 v[44:45], v[44:45], v[52:53]
	s_nop 0
	v_cvt_pk_bf16_f32 v77, v42, v44
	v_cvt_pk_bf16_f32 v76, v43, v45
	ds_read_b128 v[58:61], v152 offset:39168
	ds_read_b128 v[62:65], v152 offset:39232
	s_waitcnt lgkmcnt(1)
	v_mfma_f32_16x16x32_bf16 v[58:61], v[58:61], v[8:11], 0
	s_waitcnt lgkmcnt(0)
	v_mfma_f32_16x16x32_bf16 v[58:61], v[62:65], v[0:3], v[58:61]
	ds_read_b128 v[62:65], v152 offset:39296
	ds_read_b128 v[66:69], v152 offset:39360
	v_mov_b64_e32 v[52:53], v[224:225]
	s_waitcnt lgkmcnt(1)
	v_mfma_f32_16x16x32_bf16 v[58:61], v[62:65], v[12:15], v[58:61]
	s_waitcnt vmcnt(0)
	v_lshlrev_b32_e32 v62, 16, v52
	s_waitcnt lgkmcnt(0)
	v_mfma_f32_16x16x32_bf16 v[58:61], v[66:69], v[4:7], v[58:61]
	v_and_b32_e32 v63, 0xffff0000, v52
	v_lshlrev_b32_e32 v64, 16, v53
	v_and_b32_e32 v65, 0xffff0000, v53
	s_nop 4
	v_pk_add_f32 v[58:59], v[28:29], v[58:59] op_sel_hi:[0,1]
	v_pk_add_f32 v[60:61], v[28:29], v[60:61] op_sel_hi:[0,1]
	v_pk_mul_f32 v[52:53], v[58:59], v[62:63]
	v_pk_mul_f32 v[58:59], v[60:61], v[64:65]
	v_cvt_pk_bf16_f32 v75, v52, v53
	s_nop 0
	v_cvt_pk_bf16_f32 v74, v58, v59
	ds_read_b128 v[60:63], v152 offset:43520
	ds_read_b128 v[64:67], v152 offset:43584
	s_waitcnt lgkmcnt(1)
	v_mfma_f32_16x16x32_bf16 v[60:63], v[60:63], v[8:11], 0
	s_waitcnt lgkmcnt(0)
	v_mfma_f32_16x16x32_bf16 v[60:63], v[64:67], v[0:3], v[60:63]
	ds_read_b128 v[64:67], v152 offset:43648
	ds_read_b128 v[68:71], v152 offset:43712
	s_waitcnt lgkmcnt(1)
	v_mfma_f32_16x16x32_bf16 v[60:63], v[64:67], v[12:15], v[60:63]
	v_mov_b64_e32 v[64:65], v[226:227]
	s_waitcnt vmcnt(0)
	v_lshlrev_b32_e32 v66, 16, v65
	s_waitcnt lgkmcnt(0)
	v_mfma_f32_16x16x32_bf16 v[60:63], v[68:71], v[4:7], v[60:63]
	v_and_b32_e32 v65, 0xffff0000, v65
	s_nop 6
	v_add_f32_e32 v16, v28, v60
	v_add_f32_e32 v18, v28, v61
	v_add_f32_e32 v60, v28, v62
	v_add_f32_e32 v61, v28, v63
	v_lshlrev_b32_e32 v62, 16, v64
	v_and_b32_e32 v63, 0xffff0000, v64
	v_mul_f32_e32 v64, v16, v62
	v_mul_f32_e32 v62, v18, v63
	v_mul_f32_e32 v66, v60, v66
	v_mul_f32_e32 v60, v61, v65
	v_cvt_pk_bf16_f32 v73, v64, v62
	v_cvt_pk_bf16_f32 v72, v66, v60
	ds_read_b128 v[68:71], v152 offset:47872
	ds_read_b128 v[78:81], v152 offset:47936
	s_waitcnt lgkmcnt(1)
	v_mfma_f32_16x16x32_bf16 v[68:71], v[68:71], v[8:11], 0
	v_mov_b32_e32 v94, v64
	v_mov_b32_e32 v96, v66
	s_waitcnt lgkmcnt(0)
	v_mfma_f32_16x16x32_bf16 v[68:71], v[78:81], v[0:3], v[68:71]
	ds_read_b128 v[78:81], v152 offset:48000
	ds_read_b128 v[82:85], v152 offset:48064
	s_waitcnt lgkmcnt(1)
	v_mfma_f32_16x16x32_bf16 v[68:71], v[78:81], v[12:15], v[68:71]
	v_mov_b64_e32 v[78:79], v[228:229]
	s_waitcnt vmcnt(0)
	v_lshlrev_b32_e32 v61, 16, v78
	s_waitcnt lgkmcnt(0)
	v_mfma_f32_16x16x32_bf16 v[68:71], v[82:85], v[4:7], v[68:71]
	v_and_b32_e32 v63, 0xffff0000, v78
	v_lshlrev_b32_e32 v95, 16, v79
	v_and_b32_e32 v97, 0xffff0000, v79
	s_nop 4
	v_add_f32_e32 v16, v28, v68
	v_add_f32_e32 v18, v28, v69
	v_add_f32_e32 v65, v28, v70
	v_add_f32_e32 v67, v28, v71
	v_mul_f32_e32 v99, v16, v61
	v_mul_f32_e32 v101, v18, v63
	v_pk_mul_f32 v[102:103], v[64:65], v[94:95]
	v_pk_mul_f32 v[104:105], v[66:67], v[96:97]
	v_cvt_pk_bf16_f32 v71, v99, v101
	v_mul_f32_e32 v16, v47, v47
	v_cvt_pk_bf16_f32 v69, v103, v105
	ds_read_b128 v[78:81], v152 offset:52224
	ds_read_b128 v[82:85], v152 offset:52288
	s_waitcnt lgkmcnt(1)
	v_mfma_f32_16x16x32_bf16 v[78:81], v[78:81], v[8:11], 0
	v_mov_b32_e32 v18, v50
	v_pk_mul_f32 v[18:19], v[18:19], v[168:169]
	v_mov_b32_e32 v63, v65
	s_waitcnt lgkmcnt(0)
	v_mfma_f32_16x16x32_bf16 v[78:81], v[82:85], v[0:3], v[78:81]
	ds_read_b128 v[82:85], v152 offset:52352
	ds_read_b128 v[86:89], v152 offset:52416
	v_mov_b32_e32 v94, v62
	v_mov_b32_e32 v96, v60
	s_waitcnt lgkmcnt(1)
	v_mfma_f32_16x16x32_bf16 v[78:81], v[82:85], v[12:15], v[78:81]
	v_mov_b64_e32 v[82:83], v[230:231]
	s_waitcnt lgkmcnt(0)
	v_mfma_f32_16x16x32_bf16 v[78:81], v[86:89], v[4:7], v[78:81]
	s_nop 7
	v_mov_b32_e32 v84, v78
	v_mov_b32_e32 v85, v80
	v_mov_b32_e32 v80, v79
	v_pk_add_f32 v[78:79], v[28:29], v[84:85] op_sel_hi:[0,1]
	v_pk_add_f32 v[80:81], v[28:29], v[80:81] op_sel_hi:[0,1]
	s_waitcnt vmcnt(0)
	v_lshlrev_b32_e32 v85, 16, v83
	v_lshlrev_b32_e32 v84, 16, v82
	v_and_b32_e32 v83, 0xffff0000, v83
	v_and_b32_e32 v82, 0xffff0000, v82
	v_pk_mul_f32 v[108:109], v[78:79], v[84:85]
	v_pk_mul_f32 v[160:161], v[80:81], v[82:83]
	s_nop 0
	v_cvt_pk_bf16_f32 v70, v108, v160
	v_cvt_pk_bf16_f32 v68, v109, v161
	ds_read_b128 v[78:81], v152 offset:56576
	ds_read_b128 v[82:85], v152 offset:56640
	s_waitcnt lgkmcnt(1)
	v_mfma_f32_16x16x32_bf16 v[78:81], v[78:81], v[8:11], 0
	s_waitcnt lgkmcnt(0)
	v_mfma_f32_16x16x32_bf16 v[78:81], v[82:85], v[0:3], v[78:81]
	ds_read_b128 v[82:85], v152 offset:56704
	ds_read_b128 v[86:89], v152 offset:56768
	s_waitcnt lgkmcnt(1)
	v_mfma_f32_16x16x32_bf16 v[78:81], v[82:85], v[12:15], v[78:81]
	v_mov_b64_e32 v[82:83], v[232:233]
	s_waitcnt vmcnt(0)
	v_lshlrev_b32_e32 v84, 16, v82
	s_waitcnt lgkmcnt(0)
	v_mfma_f32_16x16x32_bf16 v[78:81], v[86:89], v[4:7], v[78:81]
	v_and_b32_e32 v85, 0xffff0000, v82
	v_lshlrev_b32_e32 v82, 16, v83
	v_and_b32_e32 v83, 0xffff0000, v83
	s_nop 4
	v_pk_add_f32 v[78:79], v[28:29], v[78:79] op_sel_hi:[0,1]
	v_pk_add_f32 v[80:81], v[28:29], v[80:81] op_sel_hi:[0,1]
	v_pk_mul_f32 v[162:163], v[78:79], v[84:85]
	v_pk_mul_f32 v[164:165], v[80:81], v[82:83]
	v_cvt_pk_bf16_f32 v66, v162, v163
	s_nop 0
	v_cvt_pk_bf16_f32 v64, v164, v165
	v_mov_b64_e32 v[166:167], v[234:235]
	ds_read_b128 v[78:81], v152 offset:60928
	ds_read_b128 v[82:85], v152 offset:60992
	ds_read_b128 v[86:89], v152 offset:61056
	ds_read_b128 v[90:93], v152 offset:61120
	s_waitcnt lgkmcnt(3)
	v_mfma_f32_16x16x32_bf16 v[78:81], v[78:81], v[8:11], 0
	s_waitcnt vmcnt(0)
	v_lshlrev_b32_e32 v24, 16, v166
	s_waitcnt lgkmcnt(2)
	v_mfma_f32_16x16x32_bf16 v[78:81], v[82:85], v[0:3], v[78:81]
	v_and_b32_e32 v55, 0xffff0000, v166
	v_lshlrev_b32_e32 v57, 16, v167
	v_and_b32_e32 v61, 0xffff0000, v167
	s_waitcnt lgkmcnt(1)
	v_mfma_f32_16x16x32_bf16 v[78:81], v[86:89], v[12:15], v[78:81]
	s_waitcnt lgkmcnt(0)
	v_mfma_f32_16x16x32_bf16 v[20:23], v[90:93], v[4:7], v[78:81]
	s_nop 7
	v_add_f32_e32 v20, v28, v20
	v_add_f32_e32 v21, v28, v21
	v_add_f32_e32 v22, v28, v22
	v_add_f32_e32 v23, v28, v23
	v_mul_f32_e32 v26, v20, v24
	v_mul_f32_e32 v78, v21, v55
	v_mul_f32_e32 v80, v22, v57
	v_mul_f32_e32 v82, v23, v61
	v_cvt_pk_bf16_f32 v21, v26, v78
	v_cvt_pk_bf16_f32 v20, v80, v82
	v_mov_b64_e32 v[84:85], v[236:237]
	v_pk_fma_f32 v[40:41], v[46:47], v[46:47], v[16:17] op_sel_hi:[1,1,0]
	v_pk_add_f32 v[22:23], v[50:51], v[48:49]
	v_mov_b32_e32 v16, v40
	v_mov_b32_e32 v55, v25
	v_pk_add_f32 v[24:25], v[40:41], v[30:31]
	v_pk_mul_f32 v[16:17], v[16:17], v[170:171]
	v_mov_b32_e32 v57, v27
	v_mov_b32_e32 v23, v19
	v_mov_b32_e32 v25, v17
	v_pk_add_f32 v[30:31], v[56:57], v[54:55]
	v_pk_add_f32 v[16:17], v[22:23], v[24:25]
	v_pk_mul_f32 v[18:19], v[44:45], v[44:45]
	v_pk_add_f32 v[16:17], v[16:17], v[30:31]
	v_pk_fma_f32 v[18:19], v[42:43], v[42:43], v[18:19]
	v_pk_add_f32 v[16:17], v[16:17], v[16:17] op_sel:[0,1] op_sel_hi:[1,0]
	v_pk_add_f32 v[18:19], v[18:19], v[18:19] op_sel:[0,1] op_sel_hi:[1,0]
	v_mov_b32_e32 v98, v16
	v_mov_b32_e32 v22, v18
	v_pk_add_f32 v[16:17], v[16:17], v[18:19]
	v_mul_f32_e32 v18, v59, v59
	v_mul_f32_e32 v24, v53, v53
	v_pk_fma_f32 v[18:19], v[58:59], v[58:59], v[18:19] op_sel_hi:[1,1,0]
	v_pk_fma_f32 v[24:25], v[52:53], v[52:53], v[24:25] op_sel_hi:[1,1,0]
	v_mov_b32_e32 v30, v18
	v_mov_b32_e32 v100, v24
	v_mov_b32_e32 v61, v67
	v_mov_b32_e32 v23, v99
	v_mov_b32_e32 v31, v101
	v_pk_add_f32 v[18:19], v[24:25], v[18:19]
	v_pk_fma_f32 v[24:25], v[62:63], v[94:95], v[102:103]
	v_pk_mul_f32 v[40:41], v[102:103], v[102:103]
	v_pk_fma_f32 v[42:43], v[60:61], v[96:97], v[104:105]
	v_pk_mul_f32 v[44:45], v[104:105], v[104:105]
	v_pk_mul_f32 v[22:23], v[98:99], v[22:23]
	v_pk_mul_f32 v[30:31], v[100:101], v[30:31]
	v_mov_b32_e32 v25, v41
	v_mov_b32_e32 v43, v45
	v_mov_b32_e32 v17, v23
	v_mov_b32_e32 v19, v31
	v_pk_add_f32 v[22:23], v[24:25], v[42:43]
	v_pk_add_f32 v[16:17], v[16:17], v[18:19]
	v_mul_f32_e32 v48, v165, v165
	v_pk_add_f32 v[16:17], v[16:17], v[22:23]
	v_pk_mul_f32 v[22:23], v[160:161], v[160:161]
	v_pk_add_f32 v[30:31], v[16:17], v[16:17] op_sel:[0,1] op_sel_hi:[1,0]
	ds_read_b128 v[16:19], v152 offset:65280
	v_pk_fma_f32 v[22:23], v[108:109], v[108:109], v[22:23]
	v_mov_b32_e32 v44, v30
	v_pk_add_f32 v[40:41], v[22:23], v[22:23] op_sel:[0,1] op_sel_hi:[1,0]
	ds_read_b128 v[22:25], v152 offset:65344
	v_mov_b32_e32 v46, v40
	v_pk_add_f32 v[30:31], v[30:31], v[40:41]
	ds_read_b128 v[40:43], v152 offset:65408
	s_waitcnt lgkmcnt(2)
	v_mfma_f32_16x16x32_bf16 v[8:11], v[16:19], v[8:11], 0
	ds_read_b128 v[16:19], v152 offset:65472
	v_mul_f32_e32 v50, v163, v163
	v_pk_fma_f32 v[48:49], v[164:165], v[164:165], v[48:49] op_sel_hi:[1,1,0]
	s_waitcnt lgkmcnt(2)
	v_mfma_f32_16x16x32_bf16 v[0:3], v[22:25], v[0:3], v[8:11]
	v_mov_b32_e32 v22, v48
	s_waitcnt lgkmcnt(1)
	v_mfma_f32_16x16x32_bf16 v[0:3], v[40:43], v[12:15], v[0:3]
	v_fma_f32 v8, v162, v162, v50
	v_fma_f32 v9, v163, v163, v50
	v_mov_b32_e32 v12, v26
	v_mov_b32_e32 v14, v80
	s_waitcnt lgkmcnt(0)
	v_mfma_f32_16x16x32_bf16 v[0:3], v[16:19], v[4:7], v[0:3]
	v_mov_b32_e32 v10, v8
	v_pk_add_f32 v[8:9], v[8:9], v[48:49]
	s_waitcnt vmcnt(0)
	v_lshlrev_b32_e32 v13, 16, v85
	s_nop 3
	v_add_f32_e32 v0, v28, v0
	v_add_f32_e32 v1, v28, v1
	v_add_f32_e32 v27, v28, v2
	v_add_f32_e32 v81, v28, v3
	v_lshlrev_b32_e32 v2, 16, v84
	v_and_b32_e32 v3, 0xffff0000, v84
	v_and_b32_e32 v15, 0xffff0000, v85
	v_mul_f32_e32 v45, v0, v2
	v_mul_f32_e32 v11, v1, v3
	v_mov_b32_e32 v79, v27
	v_mov_b32_e32 v83, v81
	v_pk_mul_f32 v[0:1], v[26:27], v[12:13]
	v_mov_b32_e32 v12, v78
	v_pk_mul_f32 v[2:3], v[80:81], v[14:15]
	v_mov_b32_e32 v14, v82
	v_mov_b32_e32 v47, v45
	v_mov_b32_e32 v23, v11
	v_cvt_pk_bf16_f32 v7, v45, v11
	v_cvt_pk_bf16_f32 v6, v1, v3
	v_pk_fma_f32 v[4:5], v[78:79], v[12:13], v[0:1]
	v_pk_mul_f32 v[0:1], v[0:1], v[0:1]
	v_pk_fma_f32 v[12:13], v[82:83], v[14:15], v[2:3]
	v_pk_mul_f32 v[2:3], v[2:3], v[2:3]
	v_pk_mul_f32 v[14:15], v[44:45], v[46:47]
	v_pk_mul_f32 v[10:11], v[10:11], v[22:23]
	v_mov_b32_e32 v5, v1
	v_mov_b32_e32 v13, v3
	v_mov_b32_e32 v31, v15
	v_mov_b32_e32 v9, v11
	v_pk_add_f32 v[0:1], v[4:5], v[12:13]
	v_pk_add_f32 v[2:3], v[30:31], v[8:9]
	s_nop 0
	v_pk_add_f32 v[0:1], v[2:3], v[0:1]
	s_barrier
	v_add_f32_e32 v8, v0, v1
	v_lshl_add_u64 v[4:5], v[38:39], 0, s[10:11]
	v_lshl_add_u64 v[0:1], v[4:5], 0, v[32:33]
	global_load_dwordx2 v[0:1], v[0:1], off
	v_or_b32_e32 v160, 0x20, v32
	v_mov_b32_e32 v161, v33
	v_lshl_add_u64 v[160:161], v[4:5], 0, v[160:161]
	global_load_dwordx2 v[160:161], v[160:161], off
	v_or_b32_e32 v162, 0x40, v32
	v_mov_b32_e32 v163, v33
	v_lshl_add_u64 v[162:163], v[4:5], 0, v[162:163]
	global_load_dwordx2 v[162:163], v[162:163], off
	v_or_b32_e32 v164, 0x60, v32
	v_mov_b32_e32 v165, v33
	v_lshl_add_u64 v[164:165], v[4:5], 0, v[164:165]
	global_load_dwordx2 v[164:165], v[164:165], off
	v_or_b32_e32 v166, 0x80, v32
	v_mov_b32_e32 v167, v33
	v_lshl_add_u64 v[166:167], v[4:5], 0, v[166:167]
	global_load_dwordx2 v[166:167], v[166:167], off
	v_or_b32_e32 v168, 0xa0, v32
	v_mov_b32_e32 v169, v33
	v_lshl_add_u64 v[168:169], v[4:5], 0, v[168:169]
	global_load_dwordx2 v[168:169], v[168:169], off
	v_or_b32_e32 v170, 0xc0, v32
	v_mov_b32_e32 v171, v33
	v_lshl_add_u64 v[170:171], v[4:5], 0, v[170:171]
	global_load_dwordx2 v[170:171], v[170:171], off
	v_or_b32_e32 v172, 0xe0, v32
	v_mov_b32_e32 v173, v33
	v_lshl_add_u64 v[172:173], v[4:5], 0, v[172:173]
	global_load_dwordx2 v[172:173], v[172:173], off
	v_or_b32_e32 v174, 0x100, v32
	v_mov_b32_e32 v175, v33
	v_lshl_add_u64 v[174:175], v[4:5], 0, v[174:175]
	global_load_dwordx2 v[174:175], v[174:175], off
	v_or_b32_e32 v176, 0x120, v32
	v_mov_b32_e32 v177, v33
	v_lshl_add_u64 v[176:177], v[4:5], 0, v[176:177]
	global_load_dwordx2 v[176:177], v[176:177], off
	v_or_b32_e32 v178, 0x140, v32
	v_mov_b32_e32 v179, v33
	v_lshl_add_u64 v[178:179], v[4:5], 0, v[178:179]
	global_load_dwordx2 v[178:179], v[178:179], off
	v_or_b32_e32 v180, 0x160, v32
	v_mov_b32_e32 v181, v33
	v_lshl_add_u64 v[180:181], v[4:5], 0, v[180:181]
	global_load_dwordx2 v[180:181], v[180:181], off
	v_or_b32_e32 v182, 0x180, v32
	v_mov_b32_e32 v183, v33
	v_lshl_add_u64 v[182:183], v[4:5], 0, v[182:183]
	global_load_dwordx2 v[182:183], v[182:183], off
	v_or_b32_e32 v184, 0x1a0, v32
	v_mov_b32_e32 v185, v33
	v_lshl_add_u64 v[184:185], v[4:5], 0, v[184:185]
	global_load_dwordx2 v[184:185], v[184:185], off
	v_or_b32_e32 v186, 0x1c0, v32
	v_mov_b32_e32 v187, v33
	v_lshl_add_u64 v[186:187], v[4:5], 0, v[186:187]
	global_load_dwordx2 v[186:187], v[186:187], off
	v_or_b32_e32 v188, 0x1e0, v32
	v_mov_b32_e32 v189, v33
	v_lshl_add_u64 v[188:189], v[4:5], 0, v[188:189]
	global_load_dwordx2 v[188:189], v[188:189], off
	v_or_b32_e32 v190, 0x200, v32
	v_mov_b32_e32 v191, v33
	v_lshl_add_u64 v[190:191], v[4:5], 0, v[190:191]
	global_load_dwordx2 v[190:191], v[190:191], off
	v_or_b32_e32 v192, 0x220, v32
	v_mov_b32_e32 v193, v33
	v_lshl_add_u64 v[192:193], v[4:5], 0, v[192:193]
	global_load_dwordx2 v[192:193], v[192:193], off
	v_or_b32_e32 v194, 0x240, v32
	v_mov_b32_e32 v195, v33
	v_lshl_add_u64 v[194:195], v[4:5], 0, v[194:195]
	global_load_dwordx2 v[194:195], v[194:195], off
	v_or_b32_e32 v196, 0x260, v32
	v_mov_b32_e32 v197, v33
	v_lshl_add_u64 v[196:197], v[4:5], 0, v[196:197]
	global_load_dwordx2 v[196:197], v[196:197], off
	v_or_b32_e32 v198, 0x280, v32
	v_mov_b32_e32 v199, v33
	v_lshl_add_u64 v[198:199], v[4:5], 0, v[198:199]
	global_load_dwordx2 v[198:199], v[198:199], off
	v_or_b32_e32 v200, 0x2a0, v32
	v_mov_b32_e32 v201, v33
	v_lshl_add_u64 v[200:201], v[4:5], 0, v[200:201]
	global_load_dwordx2 v[200:201], v[200:201], off
	v_or_b32_e32 v202, 0x2c0, v32
	v_mov_b32_e32 v203, v33
	v_lshl_add_u64 v[202:203], v[4:5], 0, v[202:203]
	global_load_dwordx2 v[202:203], v[202:203], off
	v_or_b32_e32 v204, 0x2e0, v32
	v_mov_b32_e32 v205, v33
	v_lshl_add_u64 v[204:205], v[4:5], 0, v[204:205]
	global_load_dwordx2 v[204:205], v[204:205], off
	v_or_b32_e32 v206, 0x300, v32
	v_mov_b32_e32 v207, v33
	v_lshl_add_u64 v[206:207], v[4:5], 0, v[206:207]
	global_load_dwordx2 v[206:207], v[206:207], off
	v_or_b32_e32 v208, 0x320, v32
	v_mov_b32_e32 v209, v33
	v_lshl_add_u64 v[208:209], v[4:5], 0, v[208:209]
	global_load_dwordx2 v[208:209], v[208:209], off
	v_or_b32_e32 v210, 0x340, v32
	v_mov_b32_e32 v211, v33
	v_lshl_add_u64 v[210:211], v[4:5], 0, v[210:211]
	global_load_dwordx2 v[210:211], v[210:211], off
	v_or_b32_e32 v212, 0x360, v32
	v_mov_b32_e32 v213, v33
	v_lshl_add_u64 v[212:213], v[4:5], 0, v[212:213]
	global_load_dwordx2 v[212:213], v[212:213], off
	v_or_b32_e32 v214, 0x380, v32
	v_mov_b32_e32 v215, v33
	v_lshl_add_u64 v[214:215], v[4:5], 0, v[214:215]
	global_load_dwordx2 v[214:215], v[214:215], off
	v_or_b32_e32 v216, 0x3a0, v32
	v_mov_b32_e32 v217, v33
	v_lshl_add_u64 v[216:217], v[4:5], 0, v[216:217]
	global_load_dwordx2 v[216:217], v[216:217], off
	v_or_b32_e32 v218, 0x3c0, v32
	v_mov_b32_e32 v219, v33
	v_lshl_add_u64 v[218:219], v[4:5], 0, v[218:219]
	global_load_dwordx2 v[218:219], v[218:219], off
	v_or_b32_e32 v220, 0x3e0, v32
	v_mov_b32_e32 v221, v33
	v_lshl_add_u64 v[220:221], v[4:5], 0, v[220:221]
	global_load_dwordx2 v[220:221], v[220:221], off
	v_lshlrev_b64 v[2:3], 11, v[36:37]
	v_lshl_add_u64 v[18:19], s[86:87], 0, v[2:3]
	v_lshlrev_b32_e32 v9, 16, v150
	v_and_b32_e32 v11, 0xffff0000, v150
	s_waitcnt lgkmcnt(0)
	v_mov_b32_e32 v10, v8
	s_nop 1
	v_permlane16_swap_b32_e32 v8, v10
	v_add_f32_e32 v8, v8, v10
	v_mov_b32_e32 v10, v8
	s_nop 1
	v_permlane32_swap_b32_e32 v8, v10
	v_add_f32_e32 v8, v8, v10
	v_fmamk_f32 v8, v8, 0x3b000000, v124
	v_mul_f32_e32 v10, 0x4b800000, v8
	v_cmp_gt_f32_e32 vcc, s3, v8
	v_lshlrev_b32_e32 v13, 16, v148
	v_and_b32_e32 v15, 0xffff0000, v148
	v_cndmask_b32_e32 v8, v8, v10, vcc
	v_rsq_f32_e32 v8, v8
	v_or_b32_e32 v16, 32, v32
	v_mov_b32_e32 v17, v33
	v_lshl_add_u64 v[16:17], v[4:5], 0, v[16:17]
	v_mul_f32_e32 v2, 0x45800000, v8
	v_cndmask_b32_e32 v3, v8, v2, vcc
	v_mov_b32_e32 v24, v3
	v_mov_b32_e32 v26, v3
	v_mov_b32_e32 v30, v3
	s_add_i32 s54, s54, s52
	s_add_u32 s4, s4, s6
	s_addc_u32 s5, s5, s7
	s_cmpk_gt_i32 s54, 0xff
	s_waitcnt vmcnt(0)
	v_lshlrev_b32_e32 v8, 16, v0
	v_and_b32_e32 v10, 0xffff0000, v0
	v_mul_f32_e32 v0, 0xbfb8aa3b, v8
	v_exp_f32_e32 v0, v0
	v_lshlrev_b32_e32 v12, 16, v1
	v_and_b32_e32 v14, 0xffff0000, v1
	v_mul_f32_e32 v1, 0xbfb8aa3b, v10
	v_exp_f32_e32 v1, v1
	v_add_f32_e32 v0, 1.0, v0
	v_rcp_f32_e32 v2, v0
	v_mul_f32_e32 v0, 0xbfb8aa3b, v12
	v_exp_f32_e32 v0, v0
	v_add_f32_e32 v1, 1.0, v1
	v_pk_mul_f32 v[8:9], v[2:3], v[8:9]
	v_rcp_f32_e32 v2, v1
	v_mul_f32_e32 v1, 0xbfb8aa3b, v14
	v_exp_f32_e32 v22, v1
	v_add_f32_e32 v0, 1.0, v0
	v_pk_mul_f32 v[10:11], v[2:3], v[10:11]
	v_rcp_f32_e32 v2, v0
	v_lshl_add_u64 v[0:1], v[18:19], 0, v[32:33]
	v_add_f32_e32 v18, 1.0, v22
	v_mul_f32_e32 v19, v8, v9
	v_pk_mul_f32 v[8:9], v[2:3], v[12:13]
	v_rcp_f32_e32 v2, v18
	v_mul_f32_e32 v10, v10, v11
	v_mul_f32_e32 v11, v8, v9
	v_cvt_pk_bf16_f32 v10, v19, v10
	v_pk_mul_f32 v[8:9], v[2:3], v[14:15]
	v_and_b32_e32 v12, 0xffff0000, v145
	v_mul_f32_e32 v2, v8, v9
	v_cvt_pk_bf16_f32 v11, v11, v2
	global_store_dwordx2 v[0:1], v[10:11], off offset:1024
	v_mov_b64_e32 v[8:9], v[160:161]
	v_lshlrev_b32_e32 v10, 16, v145
	v_lshlrev_b32_e32 v14, 16, v142
	v_mov_b32_e32 v22, v3
	v_and_b32_e32 v16, 0xffff0000, v142
	v_or_b32_e32 v18, 64, v32
	v_mov_b32_e32 v19, v33
	v_lshl_add_u64 v[18:19], v[4:5], 0, v[18:19]
	v_lshlrev_b32_e32 v11, 16, v8
	v_and_b32_e32 v13, 0xffff0000, v8
	v_lshlrev_b32_e32 v15, 16, v9
	v_and_b32_e32 v17, 0xffff0000, v9
	v_mul_f32_e32 v2, 0xbfb8aa3b, v11
	v_mul_f32_e32 v8, 0xbfb8aa3b, v13
	v_mul_f32_e32 v9, 0xbfb8aa3b, v15
	v_mul_f32_e32 v23, 0xbfb8aa3b, v17
	v_exp_f32_e32 v2, v2
	v_exp_f32_e32 v8, v8
	v_exp_f32_e32 v9, v9
	v_exp_f32_e32 v23, v23
	v_add_f32_e32 v2, 1.0, v2
	v_add_f32_e32 v8, 1.0, v8
	v_add_f32_e32 v9, 1.0, v9
	v_add_f32_e32 v28, 1.0, v23
	v_rcp_f32_e32 v23, v2
	v_rcp_f32_e32 v25, v8
	v_rcp_f32_e32 v27, v9
	v_rcp_f32_e32 v31, v28
	v_pk_mul_f32 v[8:9], v[22:23], v[10:11]
	v_pk_mul_f32 v[10:11], v[24:25], v[12:13]
	v_pk_mul_f32 v[12:13], v[26:27], v[14:15]
	v_pk_mul_f32 v[14:15], v[30:31], v[16:17]
	v_mul_f32_e32 v2, v8, v9
	v_mul_f32_e32 v8, v10, v11
	v_mul_f32_e32 v9, v12, v13
	v_mul_f32_e32 v10, v14, v15
	v_cvt_pk_bf16_f32 v8, v2, v8
	v_cvt_pk_bf16_f32 v9, v9, v10
	global_store_dwordx2 v[0:1], v[8:9], off offset:1056
	v_mov_b64_e32 v[8:9], v[162:163]
	v_lshlrev_b32_e32 v10, 16, v139
	v_and_b32_e32 v12, 0xffff0000, v139
	v_lshlrev_b32_e32 v14, 16, v137
	v_and_b32_e32 v16, 0xffff0000, v137
	v_or_b32_e32 v18, 0x60, v32
	v_mov_b32_e32 v19, v33
	v_lshl_add_u64 v[18:19], v[4:5], 0, v[18:19]
	v_lshlrev_b32_e32 v11, 16, v8
	v_and_b32_e32 v13, 0xffff0000, v8
	v_lshlrev_b32_e32 v15, 16, v9
	v_and_b32_e32 v17, 0xffff0000, v9
	v_mul_f32_e32 v2, 0xbfb8aa3b, v11
	v_mul_f32_e32 v8, 0xbfb8aa3b, v13
	v_mul_f32_e32 v9, 0xbfb8aa3b, v15
	v_mul_f32_e32 v23, 0xbfb8aa3b, v17
	v_exp_f32_e32 v2, v2
	v_exp_f32_e32 v8, v8
	v_exp_f32_e32 v9, v9
	v_exp_f32_e32 v23, v23
	v_add_f32_e32 v2, 1.0, v2
	v_add_f32_e32 v8, 1.0, v8
	v_add_f32_e32 v9, 1.0, v9
	v_add_f32_e32 v28, 1.0, v23
	v_rcp_f32_e32 v23, v2
	v_rcp_f32_e32 v25, v8
	v_rcp_f32_e32 v27, v9
	v_rcp_f32_e32 v31, v28
	v_pk_mul_f32 v[8:9], v[22:23], v[10:11]
	v_pk_mul_f32 v[10:11], v[24:25], v[12:13]
	v_pk_mul_f32 v[12:13], v[26:27], v[14:15]
	v_pk_mul_f32 v[14:15], v[30:31], v[16:17]
	v_mul_f32_e32 v2, v8, v9
	v_mul_f32_e32 v8, v10, v11
	v_mul_f32_e32 v9, v12, v13
	v_mul_f32_e32 v10, v14, v15
	v_cvt_pk_bf16_f32 v8, v2, v8
	v_cvt_pk_bf16_f32 v9, v9, v10
	global_store_dwordx2 v[0:1], v[8:9], off offset:1088
	v_mov_b64_e32 v[8:9], v[164:165]
	v_lshlrev_b32_e32 v10, 16, v136
	v_and_b32_e32 v12, 0xffff0000, v136
	v_lshlrev_b32_e32 v14, 16, v133
	v_and_b32_e32 v16, 0xffff0000, v133
	v_or_b32_e32 v18, 0x80, v32
	v_mov_b32_e32 v19, v33
	v_lshl_add_u64 v[18:19], v[4:5], 0, v[18:19]
	v_lshlrev_b32_e32 v11, 16, v8
	v_and_b32_e32 v13, 0xffff0000, v8
	v_lshlrev_b32_e32 v15, 16, v9
	v_and_b32_e32 v17, 0xffff0000, v9
	v_mul_f32_e32 v2, 0xbfb8aa3b, v11
	v_mul_f32_e32 v8, 0xbfb8aa3b, v13
	v_mul_f32_e32 v9, 0xbfb8aa3b, v15
	v_mul_f32_e32 v23, 0xbfb8aa3b, v17
	v_exp_f32_e32 v2, v2
	v_exp_f32_e32 v8, v8
	v_exp_f32_e32 v9, v9
	v_exp_f32_e32 v23, v23
	v_add_f32_e32 v2, 1.0, v2
	v_add_f32_e32 v8, 1.0, v8
	v_add_f32_e32 v9, 1.0, v9
	v_add_f32_e32 v28, 1.0, v23
	v_rcp_f32_e32 v23, v2
	v_rcp_f32_e32 v25, v8
	v_rcp_f32_e32 v27, v9
	v_rcp_f32_e32 v31, v28
	v_pk_mul_f32 v[8:9], v[22:23], v[10:11]
	v_pk_mul_f32 v[10:11], v[24:25], v[12:13]
	v_pk_mul_f32 v[12:13], v[26:27], v[14:15]
	v_pk_mul_f32 v[14:15], v[30:31], v[16:17]
	v_mul_f32_e32 v2, v8, v9
	v_mul_f32_e32 v8, v10, v11
	v_mul_f32_e32 v9, v12, v13
	v_mul_f32_e32 v10, v14, v15
	v_cvt_pk_bf16_f32 v8, v2, v8
	v_cvt_pk_bf16_f32 v9, v9, v10
	global_store_dwordx2 v[0:1], v[8:9], off offset:1120
	v_mov_b64_e32 v[8:9], v[166:167]
	v_lshlrev_b32_e32 v10, 16, v134
	v_and_b32_e32 v12, 0xffff0000, v134
	v_lshlrev_b32_e32 v14, 16, v132
	v_and_b32_e32 v16, 0xffff0000, v132
	v_or_b32_e32 v18, 0xa0, v32
	v_mov_b32_e32 v19, v33
	v_lshl_add_u64 v[18:19], v[4:5], 0, v[18:19]
	v_lshlrev_b32_e32 v11, 16, v8
	v_and_b32_e32 v13, 0xffff0000, v8
	v_lshlrev_b32_e32 v15, 16, v9
	v_and_b32_e32 v17, 0xffff0000, v9
	v_mul_f32_e32 v2, 0xbfb8aa3b, v11
	v_mul_f32_e32 v8, 0xbfb8aa3b, v13
	v_mul_f32_e32 v9, 0xbfb8aa3b, v15
	v_mul_f32_e32 v23, 0xbfb8aa3b, v17
	v_exp_f32_e32 v2, v2
	v_exp_f32_e32 v8, v8
	v_exp_f32_e32 v9, v9
	v_exp_f32_e32 v23, v23
	v_add_f32_e32 v2, 1.0, v2
	v_add_f32_e32 v8, 1.0, v8
	v_add_f32_e32 v9, 1.0, v9
	v_add_f32_e32 v28, 1.0, v23
	v_rcp_f32_e32 v23, v2
	v_rcp_f32_e32 v25, v8
	v_rcp_f32_e32 v27, v9
	v_rcp_f32_e32 v31, v28
	v_pk_mul_f32 v[8:9], v[22:23], v[10:11]
	v_pk_mul_f32 v[10:11], v[24:25], v[12:13]
	v_pk_mul_f32 v[12:13], v[26:27], v[14:15]
	v_pk_mul_f32 v[14:15], v[30:31], v[16:17]
	v_mul_f32_e32 v2, v8, v9
	v_mul_f32_e32 v8, v10, v11
	v_mul_f32_e32 v9, v12, v13
	v_mul_f32_e32 v10, v14, v15
	v_cvt_pk_bf16_f32 v8, v2, v8
	v_cvt_pk_bf16_f32 v9, v9, v10
	global_store_dwordx2 v[0:1], v[8:9], off offset:1152
	v_mov_b64_e32 v[8:9], v[168:169]
	v_lshlrev_b32_e32 v10, 16, v130
	v_and_b32_e32 v12, 0xffff0000, v130
	v_lshlrev_b32_e32 v14, 16, v129
	v_and_b32_e32 v16, 0xffff0000, v129
	v_or_b32_e32 v18, 0xc0, v32
	v_mov_b32_e32 v19, v33
	v_lshl_add_u64 v[18:19], v[4:5], 0, v[18:19]
	v_lshlrev_b32_e32 v11, 16, v8
	v_and_b32_e32 v13, 0xffff0000, v8
	v_lshlrev_b32_e32 v15, 16, v9
	v_and_b32_e32 v17, 0xffff0000, v9
	v_mul_f32_e32 v2, 0xbfb8aa3b, v11
	v_mul_f32_e32 v8, 0xbfb8aa3b, v13
	v_mul_f32_e32 v9, 0xbfb8aa3b, v15
	v_mul_f32_e32 v23, 0xbfb8aa3b, v17
	v_exp_f32_e32 v2, v2
	v_exp_f32_e32 v8, v8
	v_exp_f32_e32 v9, v9
	v_exp_f32_e32 v23, v23
	v_add_f32_e32 v2, 1.0, v2
	v_add_f32_e32 v8, 1.0, v8
	v_add_f32_e32 v9, 1.0, v9
	v_add_f32_e32 v28, 1.0, v23
	v_rcp_f32_e32 v23, v2
	v_rcp_f32_e32 v25, v8
	v_rcp_f32_e32 v27, v9
	v_rcp_f32_e32 v31, v28
	v_pk_mul_f32 v[8:9], v[22:23], v[10:11]
	v_pk_mul_f32 v[10:11], v[24:25], v[12:13]
	v_pk_mul_f32 v[12:13], v[26:27], v[14:15]
	v_pk_mul_f32 v[14:15], v[30:31], v[16:17]
	v_mul_f32_e32 v2, v8, v9
	v_mul_f32_e32 v8, v10, v11
	v_mul_f32_e32 v9, v12, v13
	v_mul_f32_e32 v10, v14, v15
	v_cvt_pk_bf16_f32 v8, v2, v8
	v_cvt_pk_bf16_f32 v9, v9, v10
	global_store_dwordx2 v[0:1], v[8:9], off offset:1184
	v_mov_b64_e32 v[8:9], v[170:171]
	v_lshlrev_b32_e32 v10, 16, v128
	v_and_b32_e32 v12, 0xffff0000, v128
	v_lshlrev_b32_e32 v14, 16, v127
	v_and_b32_e32 v16, 0xffff0000, v127
	v_or_b32_e32 v18, 0xe0, v32
	v_mov_b32_e32 v19, v33
	v_lshl_add_u64 v[18:19], v[4:5], 0, v[18:19]
	v_lshlrev_b32_e32 v11, 16, v8
	v_and_b32_e32 v13, 0xffff0000, v8
	v_lshlrev_b32_e32 v15, 16, v9
	v_and_b32_e32 v17, 0xffff0000, v9
	v_mul_f32_e32 v2, 0xbfb8aa3b, v11
	v_mul_f32_e32 v8, 0xbfb8aa3b, v13
	v_mul_f32_e32 v9, 0xbfb8aa3b, v15
	v_mul_f32_e32 v23, 0xbfb8aa3b, v17
	v_exp_f32_e32 v2, v2
	v_exp_f32_e32 v8, v8
	v_exp_f32_e32 v9, v9
	v_exp_f32_e32 v23, v23
	v_add_f32_e32 v2, 1.0, v2
	v_add_f32_e32 v8, 1.0, v8
	v_add_f32_e32 v9, 1.0, v9
	v_add_f32_e32 v28, 1.0, v23
	v_rcp_f32_e32 v23, v2
	v_rcp_f32_e32 v25, v8
	v_rcp_f32_e32 v27, v9
	v_rcp_f32_e32 v31, v28
	v_pk_mul_f32 v[8:9], v[22:23], v[10:11]
	v_pk_mul_f32 v[10:11], v[24:25], v[12:13]
	v_pk_mul_f32 v[12:13], v[26:27], v[14:15]
	v_pk_mul_f32 v[14:15], v[30:31], v[16:17]
	v_mul_f32_e32 v2, v8, v9
	v_mul_f32_e32 v8, v10, v11
	v_mul_f32_e32 v9, v12, v13
	v_mul_f32_e32 v10, v14, v15
	v_cvt_pk_bf16_f32 v8, v2, v8
	v_cvt_pk_bf16_f32 v9, v9, v10
	global_store_dwordx2 v[0:1], v[8:9], off offset:1216
	v_mov_b64_e32 v[8:9], v[172:173]
	v_lshlrev_b32_e32 v10, 16, v126
	v_and_b32_e32 v12, 0xffff0000, v126
	v_lshlrev_b32_e32 v14, 16, v125
	v_and_b32_e32 v16, 0xffff0000, v125
	v_or_b32_e32 v18, 0x100, v32
	v_mov_b32_e32 v19, v33
	v_lshl_add_u64 v[18:19], v[4:5], 0, v[18:19]
	v_lshlrev_b32_e32 v11, 16, v8
	v_and_b32_e32 v13, 0xffff0000, v8
	v_lshlrev_b32_e32 v15, 16, v9
	v_and_b32_e32 v17, 0xffff0000, v9
	v_mul_f32_e32 v2, 0xbfb8aa3b, v11
	v_mul_f32_e32 v8, 0xbfb8aa3b, v13
	v_mul_f32_e32 v9, 0xbfb8aa3b, v15
	v_mul_f32_e32 v23, 0xbfb8aa3b, v17
	v_exp_f32_e32 v2, v2
	v_exp_f32_e32 v8, v8
	v_exp_f32_e32 v9, v9
	v_exp_f32_e32 v23, v23
	v_add_f32_e32 v2, 1.0, v2
	v_add_f32_e32 v8, 1.0, v8
	v_add_f32_e32 v9, 1.0, v9
	v_add_f32_e32 v28, 1.0, v23
	v_rcp_f32_e32 v23, v2
	v_rcp_f32_e32 v25, v8
	v_rcp_f32_e32 v27, v9
	v_rcp_f32_e32 v31, v28
	v_pk_mul_f32 v[8:9], v[22:23], v[10:11]
	v_pk_mul_f32 v[10:11], v[24:25], v[12:13]
	v_pk_mul_f32 v[12:13], v[26:27], v[14:15]
	v_pk_mul_f32 v[14:15], v[30:31], v[16:17]
	v_mul_f32_e32 v2, v8, v9
	v_mul_f32_e32 v8, v10, v11
	v_mul_f32_e32 v9, v12, v13
	v_mul_f32_e32 v10, v14, v15
	v_cvt_pk_bf16_f32 v8, v2, v8
	v_cvt_pk_bf16_f32 v9, v9, v10
	global_store_dwordx2 v[0:1], v[8:9], off offset:1248
	v_mov_b64_e32 v[8:9], v[174:175]
	v_lshlrev_b32_e32 v10, 16, v156
	v_and_b32_e32 v12, 0xffff0000, v156
	v_lshlrev_b32_e32 v14, 16, v154
	v_and_b32_e32 v16, 0xffff0000, v154
	v_or_b32_e32 v18, 0x120, v32
	v_mov_b32_e32 v19, v33
	v_lshl_add_u64 v[18:19], v[4:5], 0, v[18:19]
	v_lshlrev_b32_e32 v11, 16, v8
	v_and_b32_e32 v13, 0xffff0000, v8
	v_lshlrev_b32_e32 v15, 16, v9
	v_and_b32_e32 v17, 0xffff0000, v9
	v_mul_f32_e32 v2, 0xbfb8aa3b, v11
	v_mul_f32_e32 v8, 0xbfb8aa3b, v13
	v_mul_f32_e32 v9, 0xbfb8aa3b, v15
	v_mul_f32_e32 v23, 0xbfb8aa3b, v17
	v_exp_f32_e32 v2, v2
	v_exp_f32_e32 v8, v8
	v_exp_f32_e32 v9, v9
	v_exp_f32_e32 v23, v23
	v_add_f32_e32 v2, 1.0, v2
	v_add_f32_e32 v8, 1.0, v8
	v_add_f32_e32 v9, 1.0, v9
	v_add_f32_e32 v28, 1.0, v23
	v_rcp_f32_e32 v23, v2
	v_rcp_f32_e32 v25, v8
	v_rcp_f32_e32 v27, v9
	v_rcp_f32_e32 v31, v28
	v_pk_mul_f32 v[8:9], v[22:23], v[10:11]
	v_pk_mul_f32 v[10:11], v[24:25], v[12:13]
	v_pk_mul_f32 v[12:13], v[26:27], v[14:15]
	v_pk_mul_f32 v[14:15], v[30:31], v[16:17]
	v_mul_f32_e32 v2, v8, v9
	v_mul_f32_e32 v8, v10, v11
	v_mul_f32_e32 v9, v12, v13
	v_mul_f32_e32 v10, v14, v15
	v_cvt_pk_bf16_f32 v8, v2, v8
	v_cvt_pk_bf16_f32 v9, v9, v10
	global_store_dwordx2 v[0:1], v[8:9], off offset:1280
	v_mov_b64_e32 v[8:9], v[176:177]
	v_lshlrev_b32_e32 v10, 16, v153
	v_and_b32_e32 v12, 0xffff0000, v153
	v_lshlrev_b32_e32 v14, 16, v151
	v_and_b32_e32 v16, 0xffff0000, v151
	v_or_b32_e32 v18, 0x140, v32
	v_mov_b32_e32 v19, v33
	v_lshl_add_u64 v[18:19], v[4:5], 0, v[18:19]
	v_lshlrev_b32_e32 v11, 16, v8
	v_and_b32_e32 v13, 0xffff0000, v8
	v_lshlrev_b32_e32 v15, 16, v9
	v_and_b32_e32 v17, 0xffff0000, v9
	v_mul_f32_e32 v2, 0xbfb8aa3b, v11
	v_mul_f32_e32 v8, 0xbfb8aa3b, v13
	v_mul_f32_e32 v9, 0xbfb8aa3b, v15
	v_mul_f32_e32 v23, 0xbfb8aa3b, v17
	v_exp_f32_e32 v2, v2
	v_exp_f32_e32 v8, v8
	v_exp_f32_e32 v9, v9
	v_exp_f32_e32 v23, v23
	v_add_f32_e32 v2, 1.0, v2
	v_add_f32_e32 v8, 1.0, v8
	v_add_f32_e32 v9, 1.0, v9
	v_add_f32_e32 v28, 1.0, v23
	v_rcp_f32_e32 v23, v2
	v_rcp_f32_e32 v25, v8
	v_rcp_f32_e32 v27, v9
	v_rcp_f32_e32 v31, v28
	v_pk_mul_f32 v[8:9], v[22:23], v[10:11]
	v_pk_mul_f32 v[10:11], v[24:25], v[12:13]
	v_pk_mul_f32 v[12:13], v[26:27], v[14:15]
	v_pk_mul_f32 v[14:15], v[30:31], v[16:17]
	v_mul_f32_e32 v2, v8, v9
	v_mul_f32_e32 v8, v10, v11
	v_mul_f32_e32 v9, v12, v13
	v_mul_f32_e32 v10, v14, v15
	v_cvt_pk_bf16_f32 v8, v2, v8
	v_cvt_pk_bf16_f32 v9, v9, v10
	global_store_dwordx2 v[0:1], v[8:9], off offset:1312
	v_mov_b64_e32 v[8:9], v[178:179]
	v_lshlrev_b32_e32 v10, 16, v149
	v_and_b32_e32 v12, 0xffff0000, v149
	v_lshlrev_b32_e32 v14, 16, v147
	v_and_b32_e32 v16, 0xffff0000, v147
	v_or_b32_e32 v18, 0x160, v32
	v_mov_b32_e32 v19, v33
	v_lshl_add_u64 v[18:19], v[4:5], 0, v[18:19]
	v_lshlrev_b32_e32 v11, 16, v8
	v_and_b32_e32 v13, 0xffff0000, v8
	v_lshlrev_b32_e32 v15, 16, v9
	v_and_b32_e32 v17, 0xffff0000, v9
	v_mul_f32_e32 v2, 0xbfb8aa3b, v11
	v_mul_f32_e32 v8, 0xbfb8aa3b, v13
	v_mul_f32_e32 v9, 0xbfb8aa3b, v15
	v_mul_f32_e32 v23, 0xbfb8aa3b, v17
	v_exp_f32_e32 v2, v2
	v_exp_f32_e32 v8, v8
	v_exp_f32_e32 v9, v9
	v_exp_f32_e32 v23, v23
	v_add_f32_e32 v2, 1.0, v2
	v_add_f32_e32 v8, 1.0, v8
	v_add_f32_e32 v9, 1.0, v9
	v_add_f32_e32 v28, 1.0, v23
	v_rcp_f32_e32 v23, v2
	v_rcp_f32_e32 v25, v8
	v_rcp_f32_e32 v27, v9
	v_rcp_f32_e32 v31, v28
	v_pk_mul_f32 v[8:9], v[22:23], v[10:11]
	v_pk_mul_f32 v[10:11], v[24:25], v[12:13]
	v_pk_mul_f32 v[12:13], v[26:27], v[14:15]
	v_pk_mul_f32 v[14:15], v[30:31], v[16:17]
	v_mul_f32_e32 v2, v8, v9
	v_mul_f32_e32 v8, v10, v11
	v_mul_f32_e32 v9, v12, v13
	v_mul_f32_e32 v10, v14, v15
	v_cvt_pk_bf16_f32 v8, v2, v8
	v_cvt_pk_bf16_f32 v9, v9, v10
	global_store_dwordx2 v[0:1], v[8:9], off offset:1344
	v_mov_b64_e32 v[8:9], v[180:181]
	v_lshlrev_b32_e32 v10, 16, v146
	v_and_b32_e32 v12, 0xffff0000, v146
	v_lshlrev_b32_e32 v14, 16, v143
	v_and_b32_e32 v16, 0xffff0000, v143
	v_or_b32_e32 v18, 0x180, v32
	v_mov_b32_e32 v19, v33
	v_lshl_add_u64 v[18:19], v[4:5], 0, v[18:19]
	v_lshlrev_b32_e32 v11, 16, v8
	v_and_b32_e32 v13, 0xffff0000, v8
	v_lshlrev_b32_e32 v15, 16, v9
	v_and_b32_e32 v17, 0xffff0000, v9
	v_mul_f32_e32 v2, 0xbfb8aa3b, v11
	v_mul_f32_e32 v8, 0xbfb8aa3b, v13
	v_mul_f32_e32 v9, 0xbfb8aa3b, v15
	v_mul_f32_e32 v23, 0xbfb8aa3b, v17
	v_exp_f32_e32 v2, v2
	v_exp_f32_e32 v8, v8
	v_exp_f32_e32 v9, v9
	v_exp_f32_e32 v23, v23
	v_add_f32_e32 v2, 1.0, v2
	v_add_f32_e32 v8, 1.0, v8
	v_add_f32_e32 v9, 1.0, v9
	v_add_f32_e32 v28, 1.0, v23
	v_rcp_f32_e32 v23, v2
	v_rcp_f32_e32 v25, v8
	v_rcp_f32_e32 v27, v9
	v_rcp_f32_e32 v31, v28
	v_pk_mul_f32 v[8:9], v[22:23], v[10:11]
	v_pk_mul_f32 v[10:11], v[24:25], v[12:13]
	v_pk_mul_f32 v[12:13], v[26:27], v[14:15]
	v_pk_mul_f32 v[14:15], v[30:31], v[16:17]
	v_mul_f32_e32 v2, v8, v9
	v_mul_f32_e32 v8, v10, v11
	v_mul_f32_e32 v9, v12, v13
	v_mul_f32_e32 v10, v14, v15
	v_cvt_pk_bf16_f32 v8, v2, v8
	v_cvt_pk_bf16_f32 v9, v9, v10
	global_store_dwordx2 v[0:1], v[8:9], off offset:1376
	v_mov_b64_e32 v[8:9], v[182:183]
	v_lshlrev_b32_e32 v10, 16, v144
	v_and_b32_e32 v12, 0xffff0000, v144
	v_lshlrev_b32_e32 v14, 16, v141
	v_and_b32_e32 v16, 0xffff0000, v141
	v_or_b32_e32 v18, 0x1a0, v32
	v_mov_b32_e32 v19, v33
	v_lshl_add_u64 v[18:19], v[4:5], 0, v[18:19]
	v_lshlrev_b32_e32 v11, 16, v8
	v_and_b32_e32 v13, 0xffff0000, v8
	v_lshlrev_b32_e32 v15, 16, v9
	v_and_b32_e32 v17, 0xffff0000, v9
	v_mul_f32_e32 v2, 0xbfb8aa3b, v11
	v_mul_f32_e32 v8, 0xbfb8aa3b, v13
	v_mul_f32_e32 v9, 0xbfb8aa3b, v15
	v_mul_f32_e32 v23, 0xbfb8aa3b, v17
	v_exp_f32_e32 v2, v2
	v_exp_f32_e32 v8, v8
	v_exp_f32_e32 v9, v9
	v_exp_f32_e32 v23, v23
	v_add_f32_e32 v2, 1.0, v2
	v_add_f32_e32 v8, 1.0, v8
	v_add_f32_e32 v9, 1.0, v9
	v_add_f32_e32 v28, 1.0, v23
	v_rcp_f32_e32 v23, v2
	v_rcp_f32_e32 v25, v8
	v_rcp_f32_e32 v27, v9
	v_rcp_f32_e32 v31, v28
	v_pk_mul_f32 v[8:9], v[22:23], v[10:11]
	v_pk_mul_f32 v[10:11], v[24:25], v[12:13]
	v_pk_mul_f32 v[12:13], v[26:27], v[14:15]
	v_pk_mul_f32 v[14:15], v[30:31], v[16:17]
	v_mul_f32_e32 v2, v8, v9
	v_mul_f32_e32 v8, v10, v11
	v_mul_f32_e32 v9, v12, v13
	v_mul_f32_e32 v10, v14, v15
	v_cvt_pk_bf16_f32 v8, v2, v8
	v_cvt_pk_bf16_f32 v9, v9, v10
	global_store_dwordx2 v[0:1], v[8:9], off offset:1408
	v_mov_b64_e32 v[8:9], v[184:185]
	v_lshlrev_b32_e32 v10, 16, v140
	v_and_b32_e32 v12, 0xffff0000, v140
	v_lshlrev_b32_e32 v14, 16, v138
	v_and_b32_e32 v16, 0xffff0000, v138
	v_or_b32_e32 v18, 0x1c0, v32
	v_mov_b32_e32 v19, v33
	v_lshl_add_u64 v[18:19], v[4:5], 0, v[18:19]
	v_lshlrev_b32_e32 v11, 16, v8
	v_and_b32_e32 v13, 0xffff0000, v8
	v_lshlrev_b32_e32 v15, 16, v9
	v_and_b32_e32 v17, 0xffff0000, v9
	v_mul_f32_e32 v2, 0xbfb8aa3b, v11
	v_mul_f32_e32 v8, 0xbfb8aa3b, v13
	v_mul_f32_e32 v9, 0xbfb8aa3b, v15
	v_mul_f32_e32 v23, 0xbfb8aa3b, v17
	v_exp_f32_e32 v2, v2
	v_exp_f32_e32 v8, v8
	v_exp_f32_e32 v9, v9
	v_exp_f32_e32 v23, v23
	v_add_f32_e32 v2, 1.0, v2
	v_add_f32_e32 v8, 1.0, v8
	v_add_f32_e32 v9, 1.0, v9
	v_add_f32_e32 v28, 1.0, v23
	v_rcp_f32_e32 v23, v2
	v_rcp_f32_e32 v25, v8
	v_rcp_f32_e32 v27, v9
	v_rcp_f32_e32 v31, v28
	v_pk_mul_f32 v[8:9], v[22:23], v[10:11]
	v_pk_mul_f32 v[10:11], v[24:25], v[12:13]
	v_pk_mul_f32 v[12:13], v[26:27], v[14:15]
	v_pk_mul_f32 v[14:15], v[30:31], v[16:17]
	v_mul_f32_e32 v2, v8, v9
	v_mul_f32_e32 v8, v10, v11
	v_mul_f32_e32 v9, v12, v13
	v_mul_f32_e32 v10, v14, v15
	v_cvt_pk_bf16_f32 v8, v2, v8
	v_cvt_pk_bf16_f32 v9, v9, v10
	global_store_dwordx2 v[0:1], v[8:9], off offset:1440
	v_mov_b64_e32 v[8:9], v[186:187]
	v_lshlrev_b32_e32 v10, 16, v135
	v_and_b32_e32 v12, 0xffff0000, v135
	v_lshlrev_b32_e32 v14, 16, v131
	v_and_b32_e32 v16, 0xffff0000, v131
	v_or_b32_e32 v18, 0x1e0, v32
	v_mov_b32_e32 v19, v33
	v_lshl_add_u64 v[18:19], v[4:5], 0, v[18:19]
	v_lshlrev_b32_e32 v11, 16, v8
	v_and_b32_e32 v13, 0xffff0000, v8
	v_lshlrev_b32_e32 v15, 16, v9
	v_and_b32_e32 v17, 0xffff0000, v9
	v_mul_f32_e32 v2, 0xbfb8aa3b, v11
	v_mul_f32_e32 v8, 0xbfb8aa3b, v13
	v_mul_f32_e32 v9, 0xbfb8aa3b, v15
	v_mul_f32_e32 v23, 0xbfb8aa3b, v17
	v_exp_f32_e32 v2, v2
	v_exp_f32_e32 v8, v8
	v_exp_f32_e32 v9, v9
	v_exp_f32_e32 v23, v23
	v_add_f32_e32 v2, 1.0, v2
	v_add_f32_e32 v8, 1.0, v8
	v_add_f32_e32 v9, 1.0, v9
	v_add_f32_e32 v28, 1.0, v23
	v_rcp_f32_e32 v23, v2
	v_rcp_f32_e32 v25, v8
	v_rcp_f32_e32 v27, v9
	v_rcp_f32_e32 v31, v28
	v_pk_mul_f32 v[8:9], v[22:23], v[10:11]
	v_pk_mul_f32 v[10:11], v[24:25], v[12:13]
	v_pk_mul_f32 v[12:13], v[26:27], v[14:15]
	v_pk_mul_f32 v[14:15], v[30:31], v[16:17]
	v_mul_f32_e32 v2, v8, v9
	v_mul_f32_e32 v8, v10, v11
	v_mul_f32_e32 v9, v12, v13
	v_mul_f32_e32 v10, v14, v15
	v_cvt_pk_bf16_f32 v8, v2, v8
	v_cvt_pk_bf16_f32 v9, v9, v10
	global_store_dwordx2 v[0:1], v[8:9], off offset:1472
	v_mov_b64_e32 v[8:9], v[188:189]
	v_lshlrev_b32_e32 v10, 16, v122
	v_and_b32_e32 v12, 0xffff0000, v122
	v_lshlrev_b32_e32 v14, 16, v120
	v_and_b32_e32 v16, 0xffff0000, v120
	v_or_b32_e32 v18, 0x200, v32
	v_mov_b32_e32 v19, v33
	v_lshl_add_u64 v[18:19], v[4:5], 0, v[18:19]
	v_lshlrev_b32_e32 v11, 16, v8
	v_and_b32_e32 v13, 0xffff0000, v8
	v_lshlrev_b32_e32 v15, 16, v9
	v_and_b32_e32 v17, 0xffff0000, v9
	v_mul_f32_e32 v2, 0xbfb8aa3b, v11
	v_mul_f32_e32 v8, 0xbfb8aa3b, v13
	v_mul_f32_e32 v9, 0xbfb8aa3b, v15
	v_mul_f32_e32 v23, 0xbfb8aa3b, v17
	v_exp_f32_e32 v2, v2
	v_exp_f32_e32 v8, v8
	v_exp_f32_e32 v9, v9
	v_exp_f32_e32 v23, v23
	v_add_f32_e32 v2, 1.0, v2
	v_add_f32_e32 v8, 1.0, v8
	v_add_f32_e32 v9, 1.0, v9
	v_add_f32_e32 v28, 1.0, v23
	v_rcp_f32_e32 v23, v2
	v_rcp_f32_e32 v25, v8
	v_rcp_f32_e32 v27, v9
	v_rcp_f32_e32 v31, v28
	v_pk_mul_f32 v[8:9], v[22:23], v[10:11]
	v_pk_mul_f32 v[10:11], v[24:25], v[12:13]
	v_pk_mul_f32 v[12:13], v[26:27], v[14:15]
	v_pk_mul_f32 v[14:15], v[30:31], v[16:17]
	v_mul_f32_e32 v2, v8, v9
	v_mul_f32_e32 v8, v10, v11
	v_mul_f32_e32 v9, v12, v13
	v_mul_f32_e32 v10, v14, v15
	v_cvt_pk_bf16_f32 v8, v2, v8
	v_cvt_pk_bf16_f32 v9, v9, v10
	global_store_dwordx2 v[0:1], v[8:9], off offset:1504
	v_mov_b64_e32 v[8:9], v[190:191]
	v_lshlrev_b32_e32 v10, 16, v159
	v_and_b32_e32 v12, 0xffff0000, v159
	v_lshlrev_b32_e32 v14, 16, v158
	v_and_b32_e32 v16, 0xffff0000, v158
	v_or_b32_e32 v18, 0x220, v32
	v_mov_b32_e32 v19, v33
	v_lshl_add_u64 v[18:19], v[4:5], 0, v[18:19]
	v_lshlrev_b32_e32 v11, 16, v8
	v_and_b32_e32 v13, 0xffff0000, v8
	v_lshlrev_b32_e32 v15, 16, v9
	v_and_b32_e32 v17, 0xffff0000, v9
	v_mul_f32_e32 v2, 0xbfb8aa3b, v11
	v_mul_f32_e32 v8, 0xbfb8aa3b, v13
	v_mul_f32_e32 v9, 0xbfb8aa3b, v15
	v_mul_f32_e32 v23, 0xbfb8aa3b, v17
	v_exp_f32_e32 v2, v2
	v_exp_f32_e32 v8, v8
	v_exp_f32_e32 v9, v9
	v_exp_f32_e32 v23, v23
	v_add_f32_e32 v2, 1.0, v2
	v_add_f32_e32 v8, 1.0, v8
	v_add_f32_e32 v9, 1.0, v9
	v_add_f32_e32 v28, 1.0, v23
	v_rcp_f32_e32 v23, v2
	v_rcp_f32_e32 v25, v8
	v_rcp_f32_e32 v27, v9
	v_rcp_f32_e32 v31, v28
	v_pk_mul_f32 v[8:9], v[22:23], v[10:11]
	v_pk_mul_f32 v[10:11], v[24:25], v[12:13]
	v_pk_mul_f32 v[12:13], v[26:27], v[14:15]
	v_pk_mul_f32 v[14:15], v[30:31], v[16:17]
	v_mul_f32_e32 v2, v8, v9
	v_mul_f32_e32 v8, v10, v11
	v_mul_f32_e32 v9, v12, v13
	v_mul_f32_e32 v10, v14, v15
	v_cvt_pk_bf16_f32 v8, v2, v8
	v_cvt_pk_bf16_f32 v9, v9, v10
	global_store_dwordx2 v[0:1], v[8:9], off offset:1536
	v_mov_b64_e32 v[8:9], v[192:193]
	v_lshlrev_b32_e32 v10, 16, v123
	v_and_b32_e32 v12, 0xffff0000, v123
	v_lshlrev_b32_e32 v14, 16, v121
	v_and_b32_e32 v16, 0xffff0000, v121
	v_or_b32_e32 v18, 0x240, v32
	v_mov_b32_e32 v19, v33
	v_lshl_add_u64 v[18:19], v[4:5], 0, v[18:19]
	v_lshlrev_b32_e32 v11, 16, v8
	v_and_b32_e32 v13, 0xffff0000, v8
	v_lshlrev_b32_e32 v15, 16, v9
	v_and_b32_e32 v17, 0xffff0000, v9
	v_mul_f32_e32 v2, 0xbfb8aa3b, v11
	v_mul_f32_e32 v8, 0xbfb8aa3b, v13
	v_mul_f32_e32 v9, 0xbfb8aa3b, v15
	v_mul_f32_e32 v23, 0xbfb8aa3b, v17
	v_exp_f32_e32 v2, v2
	v_exp_f32_e32 v8, v8
	v_exp_f32_e32 v9, v9
	v_exp_f32_e32 v23, v23
	v_add_f32_e32 v2, 1.0, v2
	v_add_f32_e32 v8, 1.0, v8
	v_add_f32_e32 v9, 1.0, v9
	v_add_f32_e32 v28, 1.0, v23
	v_rcp_f32_e32 v23, v2
	v_rcp_f32_e32 v25, v8
	v_rcp_f32_e32 v27, v9
	v_rcp_f32_e32 v31, v28
	v_pk_mul_f32 v[8:9], v[22:23], v[10:11]
	v_pk_mul_f32 v[10:11], v[24:25], v[12:13]
	v_pk_mul_f32 v[12:13], v[26:27], v[14:15]
	v_pk_mul_f32 v[14:15], v[30:31], v[16:17]
	v_mul_f32_e32 v2, v8, v9
	v_mul_f32_e32 v8, v10, v11
	v_mul_f32_e32 v9, v12, v13
	v_mul_f32_e32 v10, v14, v15
	v_cvt_pk_bf16_f32 v8, v2, v8
	v_cvt_pk_bf16_f32 v9, v9, v10
	global_store_dwordx2 v[0:1], v[8:9], off offset:1568
	v_mov_b64_e32 v[8:9], v[194:195]
	v_lshlrev_b32_e32 v10, 16, v119
	v_and_b32_e32 v12, 0xffff0000, v119
	v_lshlrev_b32_e32 v14, 16, v118
	v_and_b32_e32 v16, 0xffff0000, v118
	v_or_b32_e32 v18, 0x260, v32
	v_mov_b32_e32 v19, v33
	v_lshl_add_u64 v[18:19], v[4:5], 0, v[18:19]
	v_lshlrev_b32_e32 v11, 16, v8
	v_and_b32_e32 v13, 0xffff0000, v8
	v_lshlrev_b32_e32 v15, 16, v9
	v_and_b32_e32 v17, 0xffff0000, v9
	v_mul_f32_e32 v2, 0xbfb8aa3b, v11
	v_mul_f32_e32 v8, 0xbfb8aa3b, v13
	v_mul_f32_e32 v9, 0xbfb8aa3b, v15
	v_mul_f32_e32 v23, 0xbfb8aa3b, v17
	v_exp_f32_e32 v2, v2
	v_exp_f32_e32 v8, v8
	v_exp_f32_e32 v9, v9
	v_exp_f32_e32 v23, v23
	v_add_f32_e32 v2, 1.0, v2
	v_add_f32_e32 v8, 1.0, v8
	v_add_f32_e32 v9, 1.0, v9
	v_add_f32_e32 v28, 1.0, v23
	v_rcp_f32_e32 v23, v2
	v_rcp_f32_e32 v25, v8
	v_rcp_f32_e32 v27, v9
	v_rcp_f32_e32 v31, v28
	v_pk_mul_f32 v[8:9], v[22:23], v[10:11]
	v_pk_mul_f32 v[10:11], v[24:25], v[12:13]
	v_pk_mul_f32 v[12:13], v[26:27], v[14:15]
	v_pk_mul_f32 v[14:15], v[30:31], v[16:17]
	v_mul_f32_e32 v2, v8, v9
	v_mul_f32_e32 v8, v10, v11
	v_mul_f32_e32 v9, v12, v13
	v_mul_f32_e32 v10, v14, v15
	v_cvt_pk_bf16_f32 v8, v2, v8
	v_cvt_pk_bf16_f32 v9, v9, v10
	global_store_dwordx2 v[0:1], v[8:9], off offset:1600
	v_mov_b64_e32 v[8:9], v[196:197]
	v_lshlrev_b32_e32 v10, 16, v117
	v_and_b32_e32 v12, 0xffff0000, v117
	v_lshlrev_b32_e32 v14, 16, v115
	v_and_b32_e32 v16, 0xffff0000, v115
	v_or_b32_e32 v18, 0x280, v32
	v_mov_b32_e32 v19, v33
	v_lshl_add_u64 v[18:19], v[4:5], 0, v[18:19]
	v_lshlrev_b32_e32 v11, 16, v8
	v_and_b32_e32 v13, 0xffff0000, v8
	v_lshlrev_b32_e32 v15, 16, v9
	v_and_b32_e32 v17, 0xffff0000, v9
	v_mul_f32_e32 v2, 0xbfb8aa3b, v11
	v_mul_f32_e32 v8, 0xbfb8aa3b, v13
	v_mul_f32_e32 v9, 0xbfb8aa3b, v15
	v_mul_f32_e32 v23, 0xbfb8aa3b, v17
	v_exp_f32_e32 v2, v2
	v_exp_f32_e32 v8, v8
	v_exp_f32_e32 v9, v9
	v_exp_f32_e32 v23, v23
	v_add_f32_e32 v2, 1.0, v2
	v_add_f32_e32 v8, 1.0, v8
	v_add_f32_e32 v9, 1.0, v9
	v_add_f32_e32 v28, 1.0, v23
	v_rcp_f32_e32 v23, v2
	v_rcp_f32_e32 v25, v8
	v_rcp_f32_e32 v27, v9
	v_rcp_f32_e32 v31, v28
	v_pk_mul_f32 v[8:9], v[22:23], v[10:11]
	v_pk_mul_f32 v[10:11], v[24:25], v[12:13]
	v_pk_mul_f32 v[12:13], v[26:27], v[14:15]
	v_pk_mul_f32 v[14:15], v[30:31], v[16:17]
	v_mul_f32_e32 v2, v8, v9
	v_mul_f32_e32 v8, v10, v11
	v_mul_f32_e32 v9, v12, v13
	v_mul_f32_e32 v10, v14, v15
	v_cvt_pk_bf16_f32 v8, v2, v8
	v_cvt_pk_bf16_f32 v9, v9, v10
	global_store_dwordx2 v[0:1], v[8:9], off offset:1632
	v_mov_b64_e32 v[8:9], v[198:199]
	v_lshlrev_b32_e32 v10, 16, v116
	v_and_b32_e32 v12, 0xffff0000, v116
	v_lshlrev_b32_e32 v14, 16, v114
	v_and_b32_e32 v16, 0xffff0000, v114
	v_or_b32_e32 v18, 0x2a0, v32
	v_mov_b32_e32 v19, v33
	v_lshl_add_u64 v[18:19], v[4:5], 0, v[18:19]
	v_lshlrev_b32_e32 v11, 16, v8
	v_and_b32_e32 v13, 0xffff0000, v8
	v_lshlrev_b32_e32 v15, 16, v9
	v_and_b32_e32 v17, 0xffff0000, v9
	v_mul_f32_e32 v2, 0xbfb8aa3b, v11
	v_mul_f32_e32 v8, 0xbfb8aa3b, v13
	v_mul_f32_e32 v9, 0xbfb8aa3b, v15
	v_mul_f32_e32 v23, 0xbfb8aa3b, v17
	v_exp_f32_e32 v2, v2
	v_exp_f32_e32 v8, v8
	v_exp_f32_e32 v9, v9
	v_exp_f32_e32 v23, v23
	v_add_f32_e32 v2, 1.0, v2
	v_add_f32_e32 v8, 1.0, v8
	v_add_f32_e32 v9, 1.0, v9
	v_add_f32_e32 v28, 1.0, v23
	v_rcp_f32_e32 v23, v2
	v_rcp_f32_e32 v25, v8
	v_rcp_f32_e32 v27, v9
	v_rcp_f32_e32 v31, v28
	v_pk_mul_f32 v[8:9], v[22:23], v[10:11]
	v_pk_mul_f32 v[10:11], v[24:25], v[12:13]
	v_pk_mul_f32 v[12:13], v[26:27], v[14:15]
	v_pk_mul_f32 v[14:15], v[30:31], v[16:17]
	v_mul_f32_e32 v2, v8, v9
	v_mul_f32_e32 v8, v10, v11
	v_mul_f32_e32 v9, v12, v13
	v_mul_f32_e32 v10, v14, v15
	v_cvt_pk_bf16_f32 v8, v2, v8
	v_cvt_pk_bf16_f32 v9, v9, v10
	global_store_dwordx2 v[0:1], v[8:9], off offset:1664
	v_mov_b64_e32 v[8:9], v[200:201]
	v_lshlrev_b32_e32 v10, 16, v113
	v_and_b32_e32 v12, 0xffff0000, v113
	v_lshlrev_b32_e32 v14, 16, v112
	v_and_b32_e32 v16, 0xffff0000, v112
	v_or_b32_e32 v18, 0x2c0, v32
	v_mov_b32_e32 v19, v33
	v_lshl_add_u64 v[18:19], v[4:5], 0, v[18:19]
	v_lshlrev_b32_e32 v11, 16, v8
	v_and_b32_e32 v13, 0xffff0000, v8
	v_lshlrev_b32_e32 v15, 16, v9
	v_and_b32_e32 v17, 0xffff0000, v9
	v_mul_f32_e32 v2, 0xbfb8aa3b, v11
	v_mul_f32_e32 v8, 0xbfb8aa3b, v13
	v_mul_f32_e32 v9, 0xbfb8aa3b, v15
	v_mul_f32_e32 v23, 0xbfb8aa3b, v17
	v_exp_f32_e32 v2, v2
	v_exp_f32_e32 v8, v8
	v_exp_f32_e32 v9, v9
	v_exp_f32_e32 v23, v23
	v_add_f32_e32 v2, 1.0, v2
	v_add_f32_e32 v8, 1.0, v8
	v_add_f32_e32 v9, 1.0, v9
	v_add_f32_e32 v28, 1.0, v23
	v_rcp_f32_e32 v23, v2
	v_rcp_f32_e32 v25, v8
	v_rcp_f32_e32 v27, v9
	v_rcp_f32_e32 v31, v28
	v_pk_mul_f32 v[8:9], v[22:23], v[10:11]
	v_pk_mul_f32 v[10:11], v[24:25], v[12:13]
	v_pk_mul_f32 v[12:13], v[26:27], v[14:15]
	v_pk_mul_f32 v[14:15], v[30:31], v[16:17]
	v_mul_f32_e32 v2, v8, v9
	v_mul_f32_e32 v8, v10, v11
	v_mul_f32_e32 v9, v12, v13
	v_mul_f32_e32 v10, v14, v15
	v_cvt_pk_bf16_f32 v8, v2, v8
	v_cvt_pk_bf16_f32 v9, v9, v10
	global_store_dwordx2 v[0:1], v[8:9], off offset:1696
	v_mov_b64_e32 v[8:9], v[202:203]
	v_lshlrev_b32_e32 v10, 16, v111
	v_and_b32_e32 v12, 0xffff0000, v111
	v_lshlrev_b32_e32 v14, 16, v110
	v_and_b32_e32 v16, 0xffff0000, v110
	v_or_b32_e32 v18, 0x2e0, v32
	v_mov_b32_e32 v19, v33
	v_lshl_add_u64 v[18:19], v[4:5], 0, v[18:19]
	v_lshlrev_b32_e32 v11, 16, v8
	v_and_b32_e32 v13, 0xffff0000, v8
	v_lshlrev_b32_e32 v15, 16, v9
	v_and_b32_e32 v17, 0xffff0000, v9
	v_mul_f32_e32 v2, 0xbfb8aa3b, v11
	v_mul_f32_e32 v8, 0xbfb8aa3b, v13
	v_mul_f32_e32 v9, 0xbfb8aa3b, v15
	v_mul_f32_e32 v23, 0xbfb8aa3b, v17
	v_exp_f32_e32 v2, v2
	v_exp_f32_e32 v8, v8
	v_exp_f32_e32 v9, v9
	v_exp_f32_e32 v23, v23
	v_add_f32_e32 v2, 1.0, v2
	v_add_f32_e32 v8, 1.0, v8
	v_add_f32_e32 v9, 1.0, v9
	v_add_f32_e32 v28, 1.0, v23
	v_rcp_f32_e32 v23, v2
	v_rcp_f32_e32 v25, v8
	v_rcp_f32_e32 v27, v9
	v_rcp_f32_e32 v31, v28
	v_pk_mul_f32 v[8:9], v[22:23], v[10:11]
	v_pk_mul_f32 v[10:11], v[24:25], v[12:13]
	v_pk_mul_f32 v[12:13], v[26:27], v[14:15]
	v_pk_mul_f32 v[14:15], v[30:31], v[16:17]
	v_mul_f32_e32 v2, v8, v9
	v_mul_f32_e32 v8, v10, v11
	v_mul_f32_e32 v9, v12, v13
	v_mul_f32_e32 v10, v14, v15
	v_cvt_pk_bf16_f32 v8, v2, v8
	v_cvt_pk_bf16_f32 v9, v9, v10
	global_store_dwordx2 v[0:1], v[8:9], off offset:1728
	v_mov_b64_e32 v[8:9], v[204:205]
	v_lshlrev_b32_e32 v14, 16, v29
	v_and_b32_e32 v16, 0xffff0000, v29
	v_lshlrev_b32_e32 v10, 16, v106
	v_and_b32_e32 v12, 0xffff0000, v106
	v_mov_b32_e32 v28, v3
	v_or_b32_e32 v18, 0x300, v32
	v_mov_b32_e32 v19, v33
	v_lshl_add_u64 v[18:19], v[4:5], 0, v[18:19]
	v_lshlrev_b32_e32 v11, 16, v8
	v_and_b32_e32 v13, 0xffff0000, v8
	v_lshlrev_b32_e32 v15, 16, v9
	v_and_b32_e32 v17, 0xffff0000, v9
	v_mul_f32_e32 v2, 0xbfb8aa3b, v11
	v_mul_f32_e32 v8, 0xbfb8aa3b, v13
	v_mul_f32_e32 v9, 0xbfb8aa3b, v15
	v_mul_f32_e32 v23, 0xbfb8aa3b, v17
	v_exp_f32_e32 v2, v2
	v_exp_f32_e32 v8, v8
	v_exp_f32_e32 v9, v9
	v_exp_f32_e32 v23, v23
	v_add_f32_e32 v2, 1.0, v2
	v_add_f32_e32 v8, 1.0, v8
	v_add_f32_e32 v9, 1.0, v9
	v_add_f32_e32 v29, 1.0, v23
	v_rcp_f32_e32 v23, v2
	v_rcp_f32_e32 v25, v8
	v_rcp_f32_e32 v27, v9
	v_rcp_f32_e32 v29, v29
	v_pk_mul_f32 v[8:9], v[22:23], v[10:11]
	v_pk_mul_f32 v[10:11], v[24:25], v[12:13]
	v_pk_mul_f32 v[12:13], v[26:27], v[14:15]
	v_pk_mul_f32 v[14:15], v[28:29], v[16:17]
	v_mul_f32_e32 v2, v8, v9
	v_mul_f32_e32 v8, v10, v11
	v_mul_f32_e32 v9, v12, v13
	v_mul_f32_e32 v10, v14, v15
	v_cvt_pk_bf16_f32 v8, v2, v8
	v_cvt_pk_bf16_f32 v9, v9, v10
	global_store_dwordx2 v[0:1], v[8:9], off offset:1760
	v_mov_b64_e32 v[8:9], v[206:207]
	v_lshlrev_b32_e32 v10, 16, v77
	v_and_b32_e32 v12, 0xffff0000, v77
	v_lshlrev_b32_e32 v14, 16, v76
	v_and_b32_e32 v16, 0xffff0000, v76
	v_or_b32_e32 v18, 0x320, v32
	v_mov_b32_e32 v19, v33
	v_lshl_add_u64 v[18:19], v[4:5], 0, v[18:19]
	v_lshlrev_b32_e32 v11, 16, v8
	v_and_b32_e32 v13, 0xffff0000, v8
	v_lshlrev_b32_e32 v15, 16, v9
	v_and_b32_e32 v17, 0xffff0000, v9
	v_mul_f32_e32 v2, 0xbfb8aa3b, v11
	v_mul_f32_e32 v8, 0xbfb8aa3b, v13
	v_mul_f32_e32 v9, 0xbfb8aa3b, v15
	v_mul_f32_e32 v23, 0xbfb8aa3b, v17
	v_exp_f32_e32 v2, v2
	v_exp_f32_e32 v8, v8
	v_exp_f32_e32 v9, v9
	v_exp_f32_e32 v23, v23
	v_add_f32_e32 v2, 1.0, v2
	v_add_f32_e32 v8, 1.0, v8
	v_add_f32_e32 v9, 1.0, v9
	v_add_f32_e32 v29, 1.0, v23
	v_rcp_f32_e32 v23, v2
	v_rcp_f32_e32 v25, v8
	v_rcp_f32_e32 v27, v9
	v_rcp_f32_e32 v29, v29
	v_pk_mul_f32 v[8:9], v[22:23], v[10:11]
	v_pk_mul_f32 v[10:11], v[24:25], v[12:13]
	v_pk_mul_f32 v[12:13], v[26:27], v[14:15]
	v_pk_mul_f32 v[14:15], v[28:29], v[16:17]
	v_mul_f32_e32 v2, v8, v9
	v_mul_f32_e32 v8, v10, v11
	v_mul_f32_e32 v9, v12, v13
	v_mul_f32_e32 v10, v14, v15
	v_cvt_pk_bf16_f32 v8, v2, v8
	v_cvt_pk_bf16_f32 v9, v9, v10
	global_store_dwordx2 v[0:1], v[8:9], off offset:1792
	v_mov_b64_e32 v[8:9], v[208:209]
	v_lshlrev_b32_e32 v10, 16, v75
	v_and_b32_e32 v12, 0xffff0000, v75
	v_lshlrev_b32_e32 v14, 16, v74
	v_and_b32_e32 v16, 0xffff0000, v74
	v_or_b32_e32 v18, 0x340, v32
	v_mov_b32_e32 v19, v33
	v_lshl_add_u64 v[18:19], v[4:5], 0, v[18:19]
	v_lshlrev_b32_e32 v11, 16, v8
	v_and_b32_e32 v13, 0xffff0000, v8
	v_lshlrev_b32_e32 v15, 16, v9
	v_and_b32_e32 v17, 0xffff0000, v9
	v_mul_f32_e32 v2, 0xbfb8aa3b, v11
	v_mul_f32_e32 v8, 0xbfb8aa3b, v13
	v_mul_f32_e32 v9, 0xbfb8aa3b, v15
	v_mul_f32_e32 v23, 0xbfb8aa3b, v17
	v_exp_f32_e32 v2, v2
	v_exp_f32_e32 v8, v8
	v_exp_f32_e32 v9, v9
	v_exp_f32_e32 v23, v23
	v_add_f32_e32 v2, 1.0, v2
	v_add_f32_e32 v8, 1.0, v8
	v_add_f32_e32 v9, 1.0, v9
	v_add_f32_e32 v29, 1.0, v23
	v_rcp_f32_e32 v23, v2
	v_rcp_f32_e32 v25, v8
	v_rcp_f32_e32 v27, v9
	v_rcp_f32_e32 v29, v29
	v_pk_mul_f32 v[8:9], v[22:23], v[10:11]
	v_pk_mul_f32 v[10:11], v[24:25], v[12:13]
	v_pk_mul_f32 v[12:13], v[26:27], v[14:15]
	v_pk_mul_f32 v[14:15], v[28:29], v[16:17]
	v_mul_f32_e32 v2, v8, v9
	v_mul_f32_e32 v8, v10, v11
	v_mul_f32_e32 v9, v12, v13
	v_mul_f32_e32 v10, v14, v15
	v_cvt_pk_bf16_f32 v8, v2, v8
	v_cvt_pk_bf16_f32 v9, v9, v10
	global_store_dwordx2 v[0:1], v[8:9], off offset:1824
	v_mov_b64_e32 v[8:9], v[210:211]
	v_lshlrev_b32_e32 v10, 16, v73
	v_and_b32_e32 v12, 0xffff0000, v73
	v_lshlrev_b32_e32 v14, 16, v72
	v_and_b32_e32 v16, 0xffff0000, v72
	v_or_b32_e32 v18, 0x360, v32
	v_mov_b32_e32 v19, v33
	v_lshl_add_u64 v[18:19], v[4:5], 0, v[18:19]
	v_lshlrev_b32_e32 v11, 16, v8
	v_and_b32_e32 v13, 0xffff0000, v8
	v_lshlrev_b32_e32 v15, 16, v9
	v_and_b32_e32 v17, 0xffff0000, v9
	v_mul_f32_e32 v2, 0xbfb8aa3b, v11
	v_mul_f32_e32 v8, 0xbfb8aa3b, v13
	v_mul_f32_e32 v9, 0xbfb8aa3b, v15
	v_mul_f32_e32 v23, 0xbfb8aa3b, v17
	v_exp_f32_e32 v2, v2
	v_exp_f32_e32 v8, v8
	v_exp_f32_e32 v9, v9
	v_exp_f32_e32 v23, v23
	v_add_f32_e32 v2, 1.0, v2
	v_add_f32_e32 v8, 1.0, v8
	v_add_f32_e32 v9, 1.0, v9
	v_add_f32_e32 v29, 1.0, v23
	v_rcp_f32_e32 v23, v2
	v_rcp_f32_e32 v25, v8
	v_rcp_f32_e32 v27, v9
	v_rcp_f32_e32 v29, v29
	v_pk_mul_f32 v[8:9], v[22:23], v[10:11]
	v_pk_mul_f32 v[10:11], v[24:25], v[12:13]
	v_pk_mul_f32 v[12:13], v[26:27], v[14:15]
	v_pk_mul_f32 v[14:15], v[28:29], v[16:17]
	v_mul_f32_e32 v2, v8, v9
	v_mul_f32_e32 v8, v10, v11
	v_mul_f32_e32 v9, v12, v13
	v_mul_f32_e32 v10, v14, v15
	v_cvt_pk_bf16_f32 v8, v2, v8
	v_cvt_pk_bf16_f32 v9, v9, v10
	global_store_dwordx2 v[0:1], v[8:9], off offset:1856
	v_mov_b64_e32 v[8:9], v[212:213]
	v_lshlrev_b32_e32 v10, 16, v71
	v_and_b32_e32 v12, 0xffff0000, v71
	v_lshlrev_b32_e32 v14, 16, v69
	v_and_b32_e32 v16, 0xffff0000, v69
	v_or_b32_e32 v18, 0x380, v32
	v_mov_b32_e32 v19, v33
	v_lshl_add_u64 v[18:19], v[4:5], 0, v[18:19]
	v_lshlrev_b32_e32 v11, 16, v8
	v_and_b32_e32 v13, 0xffff0000, v8
	v_lshlrev_b32_e32 v15, 16, v9
	v_and_b32_e32 v17, 0xffff0000, v9
	v_mul_f32_e32 v2, 0xbfb8aa3b, v11
	v_mul_f32_e32 v8, 0xbfb8aa3b, v13
	v_mul_f32_e32 v9, 0xbfb8aa3b, v15
	v_mul_f32_e32 v23, 0xbfb8aa3b, v17
	v_exp_f32_e32 v2, v2
	v_exp_f32_e32 v8, v8
	v_exp_f32_e32 v9, v9
	v_exp_f32_e32 v23, v23
	v_add_f32_e32 v2, 1.0, v2
	v_add_f32_e32 v8, 1.0, v8
	v_add_f32_e32 v9, 1.0, v9
	v_add_f32_e32 v29, 1.0, v23
	v_rcp_f32_e32 v23, v2
	v_rcp_f32_e32 v25, v8
	v_rcp_f32_e32 v27, v9
	v_rcp_f32_e32 v29, v29
	v_pk_mul_f32 v[8:9], v[22:23], v[10:11]
	v_pk_mul_f32 v[10:11], v[24:25], v[12:13]
	v_pk_mul_f32 v[12:13], v[26:27], v[14:15]
	v_pk_mul_f32 v[14:15], v[28:29], v[16:17]
	v_mul_f32_e32 v2, v8, v9
	v_mul_f32_e32 v8, v10, v11
	v_mul_f32_e32 v9, v12, v13
	v_mul_f32_e32 v10, v14, v15
	v_cvt_pk_bf16_f32 v8, v2, v8
	v_cvt_pk_bf16_f32 v9, v9, v10
	global_store_dwordx2 v[0:1], v[8:9], off offset:1888
	v_mov_b64_e32 v[8:9], v[214:215]
	v_lshlrev_b32_e32 v10, 16, v70
	v_and_b32_e32 v12, 0xffff0000, v70
	v_lshlrev_b32_e32 v14, 16, v68
	v_and_b32_e32 v16, 0xffff0000, v68
	v_or_b32_e32 v18, 0x3a0, v32
	v_mov_b32_e32 v19, v33
	v_lshl_add_u64 v[18:19], v[4:5], 0, v[18:19]
	v_lshlrev_b32_e32 v11, 16, v8
	v_and_b32_e32 v13, 0xffff0000, v8
	v_lshlrev_b32_e32 v15, 16, v9
	v_and_b32_e32 v17, 0xffff0000, v9
	v_mul_f32_e32 v2, 0xbfb8aa3b, v11
	v_mul_f32_e32 v8, 0xbfb8aa3b, v13
	v_mul_f32_e32 v9, 0xbfb8aa3b, v15
	v_mul_f32_e32 v23, 0xbfb8aa3b, v17
	v_exp_f32_e32 v2, v2
	v_exp_f32_e32 v8, v8
	v_exp_f32_e32 v9, v9
	v_exp_f32_e32 v23, v23
	v_add_f32_e32 v2, 1.0, v2
	v_add_f32_e32 v8, 1.0, v8
	v_add_f32_e32 v9, 1.0, v9
	v_add_f32_e32 v29, 1.0, v23
	v_rcp_f32_e32 v23, v2
	v_rcp_f32_e32 v25, v8
	v_rcp_f32_e32 v27, v9
	v_rcp_f32_e32 v29, v29
	v_pk_mul_f32 v[8:9], v[22:23], v[10:11]
	v_pk_mul_f32 v[10:11], v[24:25], v[12:13]
	v_pk_mul_f32 v[12:13], v[26:27], v[14:15]
	v_pk_mul_f32 v[14:15], v[28:29], v[16:17]
	v_mul_f32_e32 v2, v8, v9
	v_mul_f32_e32 v8, v10, v11
	v_mul_f32_e32 v9, v12, v13
	v_mul_f32_e32 v10, v14, v15
	v_cvt_pk_bf16_f32 v8, v2, v8
	v_cvt_pk_bf16_f32 v9, v9, v10
	global_store_dwordx2 v[0:1], v[8:9], off offset:1920
	v_mov_b64_e32 v[8:9], v[216:217]
	v_lshlrev_b32_e32 v10, 16, v66
	v_and_b32_e32 v12, 0xffff0000, v66
	v_lshlrev_b32_e32 v14, 16, v64
	v_and_b32_e32 v16, 0xffff0000, v64
	v_or_b32_e32 v18, 0x3c0, v32
	v_mov_b32_e32 v19, v33
	v_lshl_add_u64 v[18:19], v[4:5], 0, v[18:19]
	v_or_b32_e32 v32, 0x3e0, v32
	v_lshl_add_u64 v[4:5], v[4:5], 0, v[32:33]
	v_lshlrev_b32_e32 v11, 16, v8
	v_and_b32_e32 v13, 0xffff0000, v8
	v_lshlrev_b32_e32 v15, 16, v9
	v_and_b32_e32 v17, 0xffff0000, v9
	v_mul_f32_e32 v2, 0xbfb8aa3b, v11
	v_mul_f32_e32 v8, 0xbfb8aa3b, v13
	v_mul_f32_e32 v9, 0xbfb8aa3b, v15
	v_mul_f32_e32 v23, 0xbfb8aa3b, v17
	v_exp_f32_e32 v2, v2
	v_exp_f32_e32 v8, v8
	v_exp_f32_e32 v9, v9
	v_exp_f32_e32 v23, v23
	v_add_f32_e32 v2, 1.0, v2
	v_add_f32_e32 v8, 1.0, v8
	v_add_f32_e32 v9, 1.0, v9
	v_add_f32_e32 v29, 1.0, v23
	v_rcp_f32_e32 v23, v2
	v_rcp_f32_e32 v25, v8
	v_rcp_f32_e32 v27, v9
	v_rcp_f32_e32 v29, v29
	v_pk_mul_f32 v[8:9], v[22:23], v[10:11]
	v_pk_mul_f32 v[10:11], v[24:25], v[12:13]
	v_pk_mul_f32 v[12:13], v[26:27], v[14:15]
	v_pk_mul_f32 v[14:15], v[28:29], v[16:17]
	v_mul_f32_e32 v2, v8, v9
	v_mul_f32_e32 v8, v10, v11
	v_mul_f32_e32 v9, v12, v13
	v_mul_f32_e32 v10, v14, v15
	v_cvt_pk_bf16_f32 v8, v2, v8
	v_cvt_pk_bf16_f32 v9, v9, v10
	global_store_dwordx2 v[0:1], v[8:9], off offset:1952
	v_mov_b64_e32 v[8:9], v[218:219]
	v_lshlrev_b32_e32 v10, 16, v21
	v_and_b32_e32 v12, 0xffff0000, v21
	v_lshlrev_b32_e32 v14, 16, v20
	v_and_b32_e32 v16, 0xffff0000, v20
	v_mov_b32_e32 v18, v3
	v_mov_b32_e32 v20, v3
	v_lshlrev_b32_e32 v11, 16, v8
	v_and_b32_e32 v13, 0xffff0000, v8
	v_lshlrev_b32_e32 v15, 16, v9
	v_and_b32_e32 v17, 0xffff0000, v9
	v_mul_f32_e32 v2, 0xbfb8aa3b, v11
	v_mul_f32_e32 v8, 0xbfb8aa3b, v13
	v_mul_f32_e32 v9, 0xbfb8aa3b, v15
	v_mul_f32_e32 v19, 0xbfb8aa3b, v17
	v_exp_f32_e32 v2, v2
	v_exp_f32_e32 v8, v8
	v_exp_f32_e32 v9, v9
	v_exp_f32_e32 v19, v19
	v_add_f32_e32 v2, 1.0, v2
	v_add_f32_e32 v8, 1.0, v8
	v_add_f32_e32 v9, 1.0, v9
	v_add_f32_e32 v25, 1.0, v19
	v_rcp_f32_e32 v19, v2
	v_rcp_f32_e32 v21, v8
	v_rcp_f32_e32 v23, v9
	v_rcp_f32_e32 v25, v25
	v_pk_mul_f32 v[8:9], v[18:19], v[10:11]
	v_pk_mul_f32 v[10:11], v[20:21], v[12:13]
	v_pk_mul_f32 v[12:13], v[22:23], v[14:15]
	v_pk_mul_f32 v[14:15], v[24:25], v[16:17]
	v_mul_f32_e32 v2, v8, v9
	v_mul_f32_e32 v8, v10, v11
	v_mul_f32_e32 v9, v12, v13
	v_mul_f32_e32 v10, v14, v15
	v_cvt_pk_bf16_f32 v8, v2, v8
	v_cvt_pk_bf16_f32 v9, v9, v10
	global_store_dwordx2 v[0:1], v[8:9], off offset:1984
	v_mov_b64_e32 v[4:5], v[220:221]
	v_mov_b32_e32 v12, v3
	v_mov_b32_e32 v14, v3
	v_mov_b32_e32 v16, v3
	v_lshlrev_b32_e32 v2, 16, v7
	v_and_b32_e32 v8, 0xffff0000, v7
	v_lshlrev_b32_e32 v10, 16, v6
	v_and_b32_e32 v6, 0xffff0000, v6
	v_lshlrev_b32_e32 v3, 16, v4
	v_and_b32_e32 v9, 0xffff0000, v4
	v_lshlrev_b32_e32 v11, 16, v5
	v_and_b32_e32 v7, 0xffff0000, v5
	v_mul_f32_e32 v4, 0xbfb8aa3b, v3
	v_mul_f32_e32 v5, 0xbfb8aa3b, v9
	v_mul_f32_e32 v13, 0xbfb8aa3b, v11
	v_mul_f32_e32 v15, 0xbfb8aa3b, v7
	v_exp_f32_e32 v4, v4
	v_exp_f32_e32 v5, v5
	v_exp_f32_e32 v13, v13
	v_exp_f32_e32 v15, v15
	v_add_f32_e32 v4, 1.0, v4
	v_add_f32_e32 v5, 1.0, v5
	v_add_f32_e32 v17, 1.0, v13
	v_add_f32_e32 v19, 1.0, v15
	v_rcp_f32_e32 v13, v4
	v_rcp_f32_e32 v15, v5
	v_rcp_f32_e32 v17, v17
	v_rcp_f32_e32 v19, v19
	v_pk_mul_f32 v[2:3], v[12:13], v[2:3]
	v_pk_mul_f32 v[4:5], v[14:15], v[8:9]
	v_pk_mul_f32 v[8:9], v[16:17], v[10:11]
	v_pk_mul_f32 v[6:7], v[18:19], v[6:7]
	v_mul_f32_e32 v2, v2, v3
	v_mul_f32_e32 v3, v4, v5
	v_mul_f32_e32 v4, v8, v9
	v_mul_f32_e32 v5, v6, v7
	v_cvt_pk_bf16_f32 v2, v2, v3
	v_cvt_pk_bf16_f32 v3, v4, v5
	global_store_dwordx2 v[0:1], v[2:3], off offset:2016
	s_cbranch_scc1 .LBB0_900
